# GEMM loops: loop-counter/pointer SALU block moved from behind the last post-MFMA barrier to in front of it (back-edge rotation, 7.11 style), on top of the late stagger barrier
# baseline (speedup 1.0000x reference)
.Llsb_skip_1:
.LBB0_335:
	ds_read_b128 v[128:131], v174
	ds_read_b128 v[132:135], v174 offset:1024
	ds_read_b128 v[158:161], v174 offset:2048
	ds_read_b128 v[178:181], v174 offset:3072
	ds_read_b128 v[182:185], v175
	ds_read_b128 v[186:189], v175 offset:1024
	ds_read_b128 v[190:193], v175 offset:2048
	ds_read_b128 v[194:197], v175 offset:3072
	s_add_u32 s28, s26, 0xfffc0080
	s_addc_u32 s29, s27, -1
	s_cmp_eq_u32 s56, 12
	s_cselect_b32 s31, s5, s29
	s_cselect_b32 s30, s21, s28
	s_cselect_b32 s29, s19, s55
	s_cselect_b32 s28, s53, s54
	v_lshl_add_u64 v[202:203], s[26:27], 0, v[150:151]
	s_add_i32 m0, s7, 0xc000
	ds_read_b128 v[198:201], v176
	ds_read_b128 v[206:209], v176 offset:1024
	ds_read_b128 v[210:213], v176 offset:2048
	ds_read_b128 v[214:217], v176 offset:3072
	ds_read_b128 v[218:221], v176 offset:4096
	ds_read_b128 v[222:225], v176 offset:5120
	ds_read_b128 v[226:229], v176 offset:6144
	ds_read_b128 v[230:233], v176 offset:7168
	global_load_lds_dwordx4 v[202:203], off
	v_lshl_add_u64 v[202:203], s[26:27], 0, v[152:153]
	s_add_i32 m0, s7, 0xe000
	s_nop 0
	global_load_lds_dwordx4 v[202:203], off
	s_waitcnt vmcnt(8)
	s_waitcnt lgkmcnt(0)
	s_barrier
	s_setprio 1
	s_waitcnt lgkmcnt(0)
	v_mfma_f32_16x16x32_bf16 v[124:127], v[128:131], v[198:201], v[124:127]
	v_mfma_f32_16x16x32_bf16 v[120:123], v[158:161], v[198:201], v[120:123]
	v_mfma_f32_16x16x32_bf16 v[108:111], v[128:131], v[210:213], v[108:111]
	v_mfma_f32_16x16x32_bf16 v[104:107], v[158:161], v[210:213], v[104:107]
	v_mfma_f32_16x16x32_bf16 v[92:95], v[128:131], v[218:221], v[92:95]
	v_mfma_f32_16x16x32_bf16 v[88:91], v[158:161], v[218:221], v[88:91]
	v_mfma_f32_16x16x32_bf16 v[76:79], v[128:131], v[226:229], v[76:79]
	v_mfma_f32_16x16x32_bf16 v[72:75], v[158:161], v[226:229], v[72:75]
	v_mfma_f32_16x16x32_bf16 v[124:127], v[132:135], v[206:209], v[124:127]
	v_mfma_f32_16x16x32_bf16 v[120:123], v[178:181], v[206:209], v[120:123]
	v_mfma_f32_16x16x32_bf16 v[108:111], v[132:135], v[214:217], v[108:111]
	v_mfma_f32_16x16x32_bf16 v[104:107], v[178:181], v[214:217], v[104:107]
	v_mfma_f32_16x16x32_bf16 v[92:95], v[132:135], v[222:225], v[92:95]
	v_mfma_f32_16x16x32_bf16 v[88:91], v[178:181], v[222:225], v[88:91]
	v_mfma_f32_16x16x32_bf16 v[76:79], v[132:135], v[230:233], v[76:79]
	v_mfma_f32_16x16x32_bf16 v[72:75], v[178:181], v[230:233], v[72:75]
	s_setprio 0
	s_setprio 1
	v_mfma_f32_16x16x32_bf16 v[116:119], v[182:185], v[198:201], v[116:119]
	v_mfma_f32_16x16x32_bf16 v[112:115], v[190:193], v[198:201], v[112:115]
	v_mfma_f32_16x16x32_bf16 v[100:103], v[182:185], v[210:213], v[100:103]
	v_mfma_f32_16x16x32_bf16 v[96:99], v[190:193], v[210:213], v[96:99]
	v_mfma_f32_16x16x32_bf16 v[84:87], v[182:185], v[218:221], v[84:87]
	v_mfma_f32_16x16x32_bf16 v[80:83], v[190:193], v[218:221], v[80:83]
	v_mfma_f32_16x16x32_bf16 v[68:71], v[182:185], v[226:229], v[68:71]
	v_mfma_f32_16x16x32_bf16 v[64:67], v[190:193], v[226:229], v[64:67]
	v_mfma_f32_16x16x32_bf16 v[116:119], v[186:189], v[206:209], v[116:119]
	v_mfma_f32_16x16x32_bf16 v[112:115], v[194:197], v[206:209], v[112:115]
	v_mfma_f32_16x16x32_bf16 v[100:103], v[186:189], v[214:217], v[100:103]
	v_mfma_f32_16x16x32_bf16 v[96:99], v[194:197], v[214:217], v[96:99]
	v_mfma_f32_16x16x32_bf16 v[84:87], v[186:189], v[222:225], v[84:87]
	v_mfma_f32_16x16x32_bf16 v[80:83], v[194:197], v[222:225], v[80:83]
	v_mfma_f32_16x16x32_bf16 v[68:71], v[186:189], v[230:233], v[68:71]
	v_mfma_f32_16x16x32_bf16 v[64:67], v[194:197], v[230:233], v[64:67]
	s_setprio 0
	s_barrier
	s_add_i32 s57, s47, s38
	v_lshl_add_u64 v[202:203], s[28:29], 0, v[140:141]
	s_mov_b32 m0, s57
	ds_read_b128 v[198:201], v176 offset:16384
	ds_read_b128 v[206:209], v176 offset:17408
	ds_read_b128 v[210:213], v176 offset:18432
	ds_read_b128 v[214:217], v176 offset:19456
	ds_read_b128 v[218:221], v176 offset:20480
	ds_read_b128 v[222:225], v176 offset:21504
	ds_read_b128 v[226:229], v176 offset:22528
	ds_read_b128 v[230:233], v176 offset:23552
	global_load_lds_dwordx4 v[202:203], off
	s_add_i32 m0, s57, 0x2000
	s_add_u32 s58, s28, 0x40000
	v_lshl_add_u64 v[234:235], s[28:29], 0, v[142:143]
	s_addc_u32 s59, s29, 0
	s_add_i32 s57, s48, s38
	global_load_lds_dwordx4 v[234:235], off
	v_lshl_add_u64 v[236:237], s[58:59], 0, v[140:141]
	s_mov_b32 m0, s57
	v_lshl_add_u64 v[238:239], s[30:31], 0, v[138:139]
	global_load_lds_dwordx4 v[236:237], off
	v_lshl_add_u64 v[236:237], s[58:59], 0, v[142:143]
	s_add_i32 m0, s57, 0x2000
	s_nop 0
	global_load_lds_dwordx4 v[236:237], off
	v_lshl_add_u64 v[236:237], s[30:31], 0, v[136:137]
	s_mov_b32 m0, s7
	s_nop 0
	global_load_lds_dwordx4 v[236:237], off
	s_mov_b32 m0, s39
	s_nop 0
	global_load_lds_dwordx4 v[238:239], off
	s_waitcnt vmcnt(8)
	s_waitcnt lgkmcnt(0)
	s_barrier
	s_setprio 1
	s_waitcnt lgkmcnt(0)
	v_mfma_f32_16x16x32_bf16 v[60:63], v[128:131], v[198:201], v[60:63]
	v_mfma_f32_16x16x32_bf16 v[56:59], v[158:161], v[198:201], v[56:59]
	v_mfma_f32_16x16x32_bf16 v[44:47], v[128:131], v[210:213], v[44:47]
	v_mfma_f32_16x16x32_bf16 v[40:43], v[158:161], v[210:213], v[40:43]
	v_mfma_f32_16x16x32_bf16 v[28:31], v[128:131], v[218:221], v[28:31]
	v_mfma_f32_16x16x32_bf16 v[24:27], v[158:161], v[218:221], v[24:27]
	v_mfma_f32_16x16x32_bf16 v[12:15], v[128:131], v[226:229], v[12:15]
	v_mfma_f32_16x16x32_bf16 v[8:11], v[158:161], v[226:229], v[8:11]
	v_mfma_f32_16x16x32_bf16 v[60:63], v[132:135], v[206:209], v[60:63]
	v_mfma_f32_16x16x32_bf16 v[56:59], v[178:181], v[206:209], v[56:59]
	v_mfma_f32_16x16x32_bf16 v[44:47], v[132:135], v[214:217], v[44:47]
	v_mfma_f32_16x16x32_bf16 v[40:43], v[178:181], v[214:217], v[40:43]
	v_mfma_f32_16x16x32_bf16 v[28:31], v[132:135], v[222:225], v[28:31]
	v_mfma_f32_16x16x32_bf16 v[24:27], v[178:181], v[222:225], v[24:27]
	v_mfma_f32_16x16x32_bf16 v[12:15], v[132:135], v[230:233], v[12:15]
	v_mfma_f32_16x16x32_bf16 v[8:11], v[178:181], v[230:233], v[8:11]
	s_setprio 0
	s_setprio 1
	v_mfma_f32_16x16x32_bf16 v[52:55], v[182:185], v[198:201], v[52:55]
	v_mfma_f32_16x16x32_bf16 v[48:51], v[190:193], v[198:201], v[48:51]
	v_mfma_f32_16x16x32_bf16 v[36:39], v[182:185], v[210:213], v[36:39]
	v_mfma_f32_16x16x32_bf16 v[32:35], v[190:193], v[210:213], v[32:35]
	v_mfma_f32_16x16x32_bf16 v[20:23], v[182:185], v[218:221], v[20:23]
	v_mfma_f32_16x16x32_bf16 v[16:19], v[190:193], v[218:221], v[16:19]
	v_mfma_f32_16x16x32_bf16 v[4:7], v[182:185], v[226:229], v[4:7]
	v_mfma_f32_16x16x32_bf16 v[0:3], v[190:193], v[226:229], v[0:3]
	v_mfma_f32_16x16x32_bf16 v[52:55], v[186:189], v[206:209], v[52:55]
	v_mfma_f32_16x16x32_bf16 v[48:51], v[194:197], v[206:209], v[48:51]
	v_mfma_f32_16x16x32_bf16 v[36:39], v[186:189], v[214:217], v[36:39]
	v_mfma_f32_16x16x32_bf16 v[32:35], v[194:197], v[214:217], v[32:35]
	v_mfma_f32_16x16x32_bf16 v[20:23], v[186:189], v[222:225], v[20:23]
	v_mfma_f32_16x16x32_bf16 v[16:19], v[194:197], v[222:225], v[16:19]
	v_mfma_f32_16x16x32_bf16 v[4:7], v[186:189], v[230:233], v[4:7]
	v_mfma_f32_16x16x32_bf16 v[0:3], v[194:197], v[230:233], v[0:3]
	s_setprio 0
	s_barrier
	s_add_i32 s57, 0, 0x18000
	v_add_u32_e32 v144, s57, v170
	s_add_i32 s58, 0, 0x1c000
	ds_read_b128 v[128:131], v144
	ds_read_b128 v[132:135], v144 offset:1024
	ds_read_b128 v[158:161], v144 offset:2048
	ds_read_b128 v[178:181], v144 offset:3072
	v_add_u32_e32 v144, s58, v170
	ds_read_b128 v[182:185], v144
	ds_read_b128 v[186:189], v144 offset:1024
	ds_read_b128 v[190:193], v144 offset:2048
	ds_read_b128 v[194:197], v144 offset:3072
	s_add_u32 s30, s30, 0x40000
	s_addc_u32 s31, s31, 0
	s_mov_b32 m0, s40
	v_lshl_add_u64 v[240:241], s[30:31], 0, v[136:137]
	ds_read_b128 v[198:201], v176 offset:32768
	ds_read_b128 v[206:209], v176 offset:33792
	ds_read_b128 v[210:213], v176 offset:34816
	ds_read_b128 v[214:217], v176 offset:35840
	ds_read_b128 v[218:221], v176 offset:36864
	ds_read_b128 v[222:225], v176 offset:37888
	ds_read_b128 v[226:229], v176 offset:38912
	ds_read_b128 v[230:233], v176 offset:39936
	global_load_lds_dwordx4 v[240:241], off
	v_lshl_add_u64 v[240:241], s[30:31], 0, v[138:139]
	s_mov_b32 m0, s41
	s_nop 0
	global_load_lds_dwordx4 v[240:241], off
	s_waitcnt vmcnt(8)
	s_waitcnt lgkmcnt(0)
	s_barrier
	s_setprio 1
	s_waitcnt lgkmcnt(0)
	v_mfma_f32_16x16x32_bf16 v[124:127], v[128:131], v[198:201], v[124:127]
	v_mfma_f32_16x16x32_bf16 v[120:123], v[158:161], v[198:201], v[120:123]
	v_mfma_f32_16x16x32_bf16 v[108:111], v[128:131], v[210:213], v[108:111]
	v_mfma_f32_16x16x32_bf16 v[104:107], v[158:161], v[210:213], v[104:107]
	v_mfma_f32_16x16x32_bf16 v[92:95], v[128:131], v[218:221], v[92:95]
	v_mfma_f32_16x16x32_bf16 v[88:91], v[158:161], v[218:221], v[88:91]
	v_mfma_f32_16x16x32_bf16 v[76:79], v[128:131], v[226:229], v[76:79]
	v_mfma_f32_16x16x32_bf16 v[72:75], v[158:161], v[226:229], v[72:75]
	v_mfma_f32_16x16x32_bf16 v[124:127], v[132:135], v[206:209], v[124:127]
	v_mfma_f32_16x16x32_bf16 v[120:123], v[178:181], v[206:209], v[120:123]
	v_mfma_f32_16x16x32_bf16 v[108:111], v[132:135], v[214:217], v[108:111]
	v_mfma_f32_16x16x32_bf16 v[104:107], v[178:181], v[214:217], v[104:107]
	v_mfma_f32_16x16x32_bf16 v[92:95], v[132:135], v[222:225], v[92:95]
	v_mfma_f32_16x16x32_bf16 v[88:91], v[178:181], v[222:225], v[88:91]
	v_mfma_f32_16x16x32_bf16 v[76:79], v[132:135], v[230:233], v[76:79]
	v_mfma_f32_16x16x32_bf16 v[72:75], v[178:181], v[230:233], v[72:75]
	s_setprio 0
	s_setprio 1
	v_mfma_f32_16x16x32_bf16 v[116:119], v[182:185], v[198:201], v[116:119]
	v_mfma_f32_16x16x32_bf16 v[112:115], v[190:193], v[198:201], v[112:115]
	v_mfma_f32_16x16x32_bf16 v[100:103], v[182:185], v[210:213], v[100:103]
	v_mfma_f32_16x16x32_bf16 v[96:99], v[190:193], v[210:213], v[96:99]
	v_mfma_f32_16x16x32_bf16 v[84:87], v[182:185], v[218:221], v[84:87]
	v_mfma_f32_16x16x32_bf16 v[80:83], v[190:193], v[218:221], v[80:83]
	v_mfma_f32_16x16x32_bf16 v[68:71], v[182:185], v[226:229], v[68:71]
	v_mfma_f32_16x16x32_bf16 v[64:67], v[190:193], v[226:229], v[64:67]
	v_mfma_f32_16x16x32_bf16 v[116:119], v[186:189], v[206:209], v[116:119]
	v_mfma_f32_16x16x32_bf16 v[112:115], v[194:197], v[206:209], v[112:115]
	v_mfma_f32_16x16x32_bf16 v[100:103], v[186:189], v[214:217], v[100:103]
	v_mfma_f32_16x16x32_bf16 v[96:99], v[194:197], v[214:217], v[96:99]
	v_mfma_f32_16x16x32_bf16 v[84:87], v[186:189], v[222:225], v[84:87]
	v_mfma_f32_16x16x32_bf16 v[80:83], v[194:197], v[222:225], v[80:83]
	v_mfma_f32_16x16x32_bf16 v[68:71], v[186:189], v[230:233], v[68:71]
	v_mfma_f32_16x16x32_bf16 v[64:67], v[194:197], v[230:233], v[64:67]
	s_setprio 0
	s_barrier
	s_add_i32 s30, s57, s38
	v_lshl_add_u64 v[202:203], v[202:203], 0, s[14:15]
	s_mov_b32 m0, s30
	ds_read_b128 v[198:201], v176 offset:49152
	ds_read_b128 v[206:209], v176 offset:50176
	ds_read_b128 v[210:213], v176 offset:51200
	ds_read_b128 v[214:217], v176 offset:52224
	ds_read_b128 v[218:221], v176 offset:53248
	ds_read_b128 v[222:225], v176 offset:54272
	ds_read_b128 v[226:229], v176 offset:55296
	ds_read_b128 v[230:233], v176 offset:56320
	global_load_lds_dwordx4 v[202:203], off
	s_add_i32 m0, s30, 0x2000
	s_add_u32 s28, s28, 0x40080
	v_lshl_add_u64 v[202:203], v[234:235], 0, s[14:15]
	s_addc_u32 s29, s29, 0
	s_add_i32 s30, s58, s38
	global_load_lds_dwordx4 v[202:203], off
	v_lshl_add_u64 v[202:203], s[28:29], 0, v[140:141]
	s_mov_b32 m0, s30
	s_nop 0
	global_load_lds_dwordx4 v[202:203], off
	v_lshl_add_u64 v[202:203], s[28:29], 0, v[142:143]
	s_add_i32 m0, s30, 0x2000
	s_nop 0
	global_load_lds_dwordx4 v[202:203], off
	v_lshl_add_u64 v[202:203], v[236:237], 0, s[14:15]
	s_mov_b32 m0, s43
	s_nop 0
	global_load_lds_dwordx4 v[202:203], off
	v_lshl_add_u64 v[202:203], v[238:239], 0, s[14:15]
	s_mov_b32 m0, s44
	s_nop 0
	global_load_lds_dwordx4 v[202:203], off
	s_waitcnt vmcnt(8)
	s_waitcnt lgkmcnt(0)
	s_barrier
	s_setprio 1
	s_waitcnt lgkmcnt(0)
	v_mfma_f32_16x16x32_bf16 v[60:63], v[128:131], v[198:201], v[60:63]
	v_mfma_f32_16x16x32_bf16 v[56:59], v[158:161], v[198:201], v[56:59]
	v_mfma_f32_16x16x32_bf16 v[44:47], v[128:131], v[210:213], v[44:47]
	v_mfma_f32_16x16x32_bf16 v[40:43], v[158:161], v[210:213], v[40:43]
	v_mfma_f32_16x16x32_bf16 v[28:31], v[128:131], v[218:221], v[28:31]
	v_mfma_f32_16x16x32_bf16 v[24:27], v[158:161], v[218:221], v[24:27]
	v_mfma_f32_16x16x32_bf16 v[12:15], v[128:131], v[226:229], v[12:15]
	v_mfma_f32_16x16x32_bf16 v[8:11], v[158:161], v[226:229], v[8:11]
	v_mfma_f32_16x16x32_bf16 v[60:63], v[132:135], v[206:209], v[60:63]
	v_mfma_f32_16x16x32_bf16 v[56:59], v[178:181], v[206:209], v[56:59]
	v_mfma_f32_16x16x32_bf16 v[44:47], v[132:135], v[214:217], v[44:47]
	v_mfma_f32_16x16x32_bf16 v[40:43], v[178:181], v[214:217], v[40:43]
	v_mfma_f32_16x16x32_bf16 v[28:31], v[132:135], v[222:225], v[28:31]
	v_mfma_f32_16x16x32_bf16 v[24:27], v[178:181], v[222:225], v[24:27]
	v_mfma_f32_16x16x32_bf16 v[12:15], v[132:135], v[230:233], v[12:15]
	v_mfma_f32_16x16x32_bf16 v[8:11], v[178:181], v[230:233], v[8:11]
	s_setprio 0
	s_setprio 1
	v_mfma_f32_16x16x32_bf16 v[52:55], v[182:185], v[198:201], v[52:55]
	v_mfma_f32_16x16x32_bf16 v[48:51], v[190:193], v[198:201], v[48:51]
	v_mfma_f32_16x16x32_bf16 v[36:39], v[182:185], v[210:213], v[36:39]
	v_mfma_f32_16x16x32_bf16 v[32:35], v[190:193], v[210:213], v[32:35]
	v_mfma_f32_16x16x32_bf16 v[20:23], v[182:185], v[218:221], v[20:23]
	v_mfma_f32_16x16x32_bf16 v[16:19], v[190:193], v[218:221], v[16:19]
	v_mfma_f32_16x16x32_bf16 v[4:7], v[182:185], v[226:229], v[4:7]
	v_mfma_f32_16x16x32_bf16 v[0:3], v[190:193], v[226:229], v[0:3]
	v_mfma_f32_16x16x32_bf16 v[52:55], v[186:189], v[206:209], v[52:55]
	v_mfma_f32_16x16x32_bf16 v[48:51], v[194:197], v[206:209], v[48:51]
	v_mfma_f32_16x16x32_bf16 v[36:39], v[186:189], v[214:217], v[36:39]
	v_mfma_f32_16x16x32_bf16 v[32:35], v[194:197], v[214:217], v[32:35]
	v_mfma_f32_16x16x32_bf16 v[20:23], v[186:189], v[222:225], v[20:23]
	v_mfma_f32_16x16x32_bf16 v[16:19], v[194:197], v[222:225], v[16:19]
	v_mfma_f32_16x16x32_bf16 v[4:7], v[186:189], v[230:233], v[4:7]
	v_mfma_f32_16x16x32_bf16 v[0:3], v[194:197], v[230:233], v[0:3]
	s_add_i32 s56, s56, 2
	s_add_u32 s26, s26, 0x100
	s_addc_u32 s27, s27, 0
	s_add_u32 s54, s54, 0x100
	s_addc_u32 s55, s55, 0
	s_cmp_gt_u32 s56, 13
	s_setprio 0
	s_barrier
	s_cbranch_scc0 .LBB0_335
	s_and_b64 vcc, exec, s[16:17]
	s_cbranch_vccz .LBB0_338
	s_barrier

.Llsb_skip_2:
.LBB0_487:
	ds_read_b128 v[142:145], v135
	ds_read_b128 v[146:149], v135 offset:1024
	ds_read_b128 v[150:153], v135 offset:2048
	ds_read_b128 v[154:157], v135 offset:3072
	ds_read_b128 v[158:161], v140
	ds_read_b128 v[162:165], v140 offset:1024
	ds_read_b128 v[166:169], v140 offset:2048
	ds_read_b128 v[170:173], v140 offset:3072
	s_add_u32 s28, s26, 0xfffc0080
	s_addc_u32 s29, s27, -1
	s_cmp_eq_u32 s57, 12
	s_cselect_b32 s31, s21, s29
	s_cselect_b32 s30, s53, s28
	s_cselect_b32 s29, s19, s56
	s_cselect_b32 s28, s54, s55
	v_lshl_add_u64 v[202:203], s[26:27], 0, v[128:129]
	s_add_i32 m0, s41, 0xc000
	ds_read_b128 v[174:177], v141
	ds_read_b128 v[178:181], v141 offset:1024
	ds_read_b128 v[182:185], v141 offset:2048
	ds_read_b128 v[186:189], v141 offset:3072
	ds_read_b128 v[190:193], v141 offset:4096
	ds_read_b128 v[194:197], v141 offset:5120
	ds_read_b128 v[198:201], v141 offset:6144
	ds_read_b128 v[206:209], v141 offset:7168
	global_load_lds_dwordx4 v[202:203], off
	v_lshl_add_u64 v[202:203], s[26:27], 0, v[130:131]
	s_add_i32 m0, s41, 0xe000
	s_nop 0
	global_load_lds_dwordx4 v[202:203], off
	s_waitcnt vmcnt(8)
	s_waitcnt lgkmcnt(0)
	s_barrier
	s_setprio 1
	s_waitcnt lgkmcnt(0)
	v_mfma_f32_16x16x32_bf16 v[124:127], v[142:145], v[174:177], v[124:127]
	v_mfma_f32_16x16x32_bf16 v[120:123], v[150:153], v[174:177], v[120:123]
	v_mfma_f32_16x16x32_bf16 v[116:119], v[142:145], v[182:185], v[116:119]
	v_mfma_f32_16x16x32_bf16 v[112:115], v[150:153], v[182:185], v[112:115]
	v_mfma_f32_16x16x32_bf16 v[104:107], v[142:145], v[190:193], v[104:107]
	v_mfma_f32_16x16x32_bf16 v[96:99], v[150:153], v[190:193], v[96:99]
	v_mfma_f32_16x16x32_bf16 v[88:91], v[142:145], v[198:201], v[88:91]
	v_mfma_f32_16x16x32_bf16 v[80:83], v[150:153], v[198:201], v[80:83]
	v_mfma_f32_16x16x32_bf16 v[124:127], v[146:149], v[178:181], v[124:127]
	v_mfma_f32_16x16x32_bf16 v[120:123], v[154:157], v[178:181], v[120:123]
	v_mfma_f32_16x16x32_bf16 v[116:119], v[146:149], v[186:189], v[116:119]
	v_mfma_f32_16x16x32_bf16 v[112:115], v[154:157], v[186:189], v[112:115]
	v_mfma_f32_16x16x32_bf16 v[104:107], v[146:149], v[194:197], v[104:107]
	v_mfma_f32_16x16x32_bf16 v[96:99], v[154:157], v[194:197], v[96:99]
	v_mfma_f32_16x16x32_bf16 v[88:91], v[146:149], v[206:209], v[88:91]
	v_mfma_f32_16x16x32_bf16 v[80:83], v[154:157], v[206:209], v[80:83]
	s_setprio 0
	s_setprio 1
	v_mfma_f32_16x16x32_bf16 v[108:111], v[158:161], v[174:177], v[108:111]
	v_mfma_f32_16x16x32_bf16 v[100:103], v[166:169], v[174:177], v[100:103]
	v_mfma_f32_16x16x32_bf16 v[92:95], v[158:161], v[182:185], v[92:95]
	v_mfma_f32_16x16x32_bf16 v[84:87], v[166:169], v[182:185], v[84:87]
	v_mfma_f32_16x16x32_bf16 v[76:79], v[158:161], v[190:193], v[76:79]
	v_mfma_f32_16x16x32_bf16 v[72:75], v[166:169], v[190:193], v[72:75]
	v_mfma_f32_16x16x32_bf16 v[68:71], v[158:161], v[198:201], v[68:71]
	v_mfma_f32_16x16x32_bf16 v[64:67], v[166:169], v[198:201], v[64:67]
	v_mfma_f32_16x16x32_bf16 v[108:111], v[162:165], v[178:181], v[108:111]
	v_mfma_f32_16x16x32_bf16 v[100:103], v[170:173], v[178:181], v[100:103]
	v_mfma_f32_16x16x32_bf16 v[92:95], v[162:165], v[186:189], v[92:95]
	v_mfma_f32_16x16x32_bf16 v[84:87], v[170:173], v[186:189], v[84:87]
	v_mfma_f32_16x16x32_bf16 v[76:79], v[162:165], v[194:197], v[76:79]
	v_mfma_f32_16x16x32_bf16 v[72:75], v[170:173], v[194:197], v[72:75]
	v_mfma_f32_16x16x32_bf16 v[68:71], v[162:165], v[206:209], v[68:71]
	v_mfma_f32_16x16x32_bf16 v[64:67], v[170:173], v[206:209], v[64:67]
	s_setprio 0
	s_barrier
	s_add_i32 s58, s49, s38
	v_lshl_add_u64 v[202:203], s[28:29], 0, v[136:137]
	s_mov_b32 m0, s58
	ds_read_b128 v[174:177], v141 offset:16384
	ds_read_b128 v[178:181], v141 offset:17408
	ds_read_b128 v[182:185], v141 offset:18432
	ds_read_b128 v[186:189], v141 offset:19456
	ds_read_b128 v[190:193], v141 offset:20480
	ds_read_b128 v[194:197], v141 offset:21504
	ds_read_b128 v[198:201], v141 offset:22528
	ds_read_b128 v[206:209], v141 offset:23552
	global_load_lds_dwordx4 v[202:203], off
	s_add_i32 m0, s58, 0x2000
	s_add_u32 s58, s28, 0x40000
	v_lshl_add_u64 v[210:211], s[28:29], 0, v[138:139]
	s_addc_u32 s59, s29, 0
	s_add_i32 s60, s50, s38
	global_load_lds_dwordx4 v[210:211], off
	v_lshl_add_u64 v[212:213], s[58:59], 0, v[136:137]
	s_mov_b32 m0, s60
	v_lshl_add_u64 v[214:215], s[30:31], 0, v[138:139]
	global_load_lds_dwordx4 v[212:213], off
	v_lshl_add_u64 v[212:213], s[58:59], 0, v[138:139]
	s_add_i32 m0, s60, 0x2000
	s_nop 0
	global_load_lds_dwordx4 v[212:213], off
	v_lshl_add_u64 v[212:213], s[30:31], 0, v[136:137]
	s_mov_b32 m0, s41
	s_nop 0
	global_load_lds_dwordx4 v[212:213], off
	s_mov_b32 m0, s42
	s_nop 0
	global_load_lds_dwordx4 v[214:215], off
	s_waitcnt vmcnt(8)
	s_waitcnt lgkmcnt(0)
	s_barrier
	s_setprio 1
	s_waitcnt lgkmcnt(0)
	v_mfma_f32_16x16x32_bf16 v[60:63], v[142:145], v[174:177], v[60:63]
	v_mfma_f32_16x16x32_bf16 v[56:59], v[150:153], v[174:177], v[56:59]
	v_mfma_f32_16x16x32_bf16 v[52:55], v[142:145], v[182:185], v[52:55]
	v_mfma_f32_16x16x32_bf16 v[48:51], v[150:153], v[182:185], v[48:51]
	v_mfma_f32_16x16x32_bf16 v[40:43], v[142:145], v[190:193], v[40:43]
	v_mfma_f32_16x16x32_bf16 v[32:35], v[150:153], v[190:193], v[32:35]
	v_mfma_f32_16x16x32_bf16 v[24:27], v[142:145], v[198:201], v[24:27]
	v_mfma_f32_16x16x32_bf16 v[16:19], v[150:153], v[198:201], v[16:19]
	v_mfma_f32_16x16x32_bf16 v[60:63], v[146:149], v[178:181], v[60:63]
	v_mfma_f32_16x16x32_bf16 v[56:59], v[154:157], v[178:181], v[56:59]
	v_mfma_f32_16x16x32_bf16 v[52:55], v[146:149], v[186:189], v[52:55]
	v_mfma_f32_16x16x32_bf16 v[48:51], v[154:157], v[186:189], v[48:51]
	v_mfma_f32_16x16x32_bf16 v[40:43], v[146:149], v[194:197], v[40:43]
	v_mfma_f32_16x16x32_bf16 v[32:35], v[154:157], v[194:197], v[32:35]
	v_mfma_f32_16x16x32_bf16 v[24:27], v[146:149], v[206:209], v[24:27]
	v_mfma_f32_16x16x32_bf16 v[16:19], v[154:157], v[206:209], v[16:19]
	s_setprio 0
	s_setprio 1
	v_mfma_f32_16x16x32_bf16 v[44:47], v[158:161], v[174:177], v[44:47]
	v_mfma_f32_16x16x32_bf16 v[36:39], v[166:169], v[174:177], v[36:39]
	v_mfma_f32_16x16x32_bf16 v[28:31], v[158:161], v[182:185], v[28:31]
	v_mfma_f32_16x16x32_bf16 v[20:23], v[166:169], v[182:185], v[20:23]
	v_mfma_f32_16x16x32_bf16 v[12:15], v[158:161], v[190:193], v[12:15]
	v_mfma_f32_16x16x32_bf16 v[8:11], v[166:169], v[190:193], v[8:11]
	v_mfma_f32_16x16x32_bf16 v[4:7], v[158:161], v[198:201], v[4:7]
	v_mfma_f32_16x16x32_bf16 v[0:3], v[166:169], v[198:201], v[0:3]
	v_mfma_f32_16x16x32_bf16 v[44:47], v[162:165], v[178:181], v[44:47]
	v_mfma_f32_16x16x32_bf16 v[36:39], v[170:173], v[178:181], v[36:39]
	v_mfma_f32_16x16x32_bf16 v[28:31], v[162:165], v[186:189], v[28:31]
	v_mfma_f32_16x16x32_bf16 v[20:23], v[170:173], v[186:189], v[20:23]
	v_mfma_f32_16x16x32_bf16 v[12:15], v[162:165], v[194:197], v[12:15]
	v_mfma_f32_16x16x32_bf16 v[8:11], v[170:173], v[194:197], v[8:11]
	v_mfma_f32_16x16x32_bf16 v[4:7], v[162:165], v[206:209], v[4:7]
	v_mfma_f32_16x16x32_bf16 v[0:3], v[170:173], v[206:209], v[0:3]
	s_setprio 0
	s_barrier
	s_add_i32 s58, 0, 0x18000
	s_add_i32 s59, 0, 0x1c000
	v_add_u32_e32 v154, s58, v133
	v_add_u32_e32 v170, s59, v133
	ds_read_b128 v[142:145], v154
	ds_read_b128 v[146:149], v154 offset:1024
	ds_read_b128 v[150:153], v154 offset:2048
	ds_read_b128 v[154:157], v154 offset:3072
	ds_read_b128 v[158:161], v170
	ds_read_b128 v[162:165], v170 offset:1024
	ds_read_b128 v[166:169], v170 offset:2048
	ds_read_b128 v[170:173], v170 offset:3072
	s_add_u32 s30, s30, 0x40000
	s_addc_u32 s31, s31, 0
	s_mov_b32 m0, s43
	v_lshl_add_u64 v[216:217], s[30:31], 0, v[136:137]
	ds_read_b128 v[174:177], v141 offset:32768
	ds_read_b128 v[178:181], v141 offset:33792
	ds_read_b128 v[182:185], v141 offset:34816
	ds_read_b128 v[186:189], v141 offset:35840
	ds_read_b128 v[190:193], v141 offset:36864
	ds_read_b128 v[194:197], v141 offset:37888
	ds_read_b128 v[198:201], v141 offset:38912
	ds_read_b128 v[206:209], v141 offset:39936
	global_load_lds_dwordx4 v[216:217], off
	v_lshl_add_u64 v[216:217], s[30:31], 0, v[138:139]
	s_mov_b32 m0, s44
	s_nop 0
	global_load_lds_dwordx4 v[216:217], off
	s_waitcnt vmcnt(8)
	s_waitcnt lgkmcnt(0)
	s_barrier
	s_setprio 1
	s_waitcnt lgkmcnt(0)
	v_mfma_f32_16x16x32_bf16 v[124:127], v[142:145], v[174:177], v[124:127]
	v_mfma_f32_16x16x32_bf16 v[120:123], v[150:153], v[174:177], v[120:123]
	v_mfma_f32_16x16x32_bf16 v[116:119], v[142:145], v[182:185], v[116:119]
	v_mfma_f32_16x16x32_bf16 v[112:115], v[150:153], v[182:185], v[112:115]
	v_mfma_f32_16x16x32_bf16 v[104:107], v[142:145], v[190:193], v[104:107]
	v_mfma_f32_16x16x32_bf16 v[96:99], v[150:153], v[190:193], v[96:99]
	v_mfma_f32_16x16x32_bf16 v[88:91], v[142:145], v[198:201], v[88:91]
	v_mfma_f32_16x16x32_bf16 v[80:83], v[150:153], v[198:201], v[80:83]
	v_mfma_f32_16x16x32_bf16 v[124:127], v[146:149], v[178:181], v[124:127]
	v_mfma_f32_16x16x32_bf16 v[120:123], v[154:157], v[178:181], v[120:123]
	v_mfma_f32_16x16x32_bf16 v[116:119], v[146:149], v[186:189], v[116:119]
	v_mfma_f32_16x16x32_bf16 v[112:115], v[154:157], v[186:189], v[112:115]
	v_mfma_f32_16x16x32_bf16 v[104:107], v[146:149], v[194:197], v[104:107]
	v_mfma_f32_16x16x32_bf16 v[96:99], v[154:157], v[194:197], v[96:99]
	v_mfma_f32_16x16x32_bf16 v[88:91], v[146:149], v[206:209], v[88:91]
	v_mfma_f32_16x16x32_bf16 v[80:83], v[154:157], v[206:209], v[80:83]
	s_setprio 0
	s_setprio 1
	v_mfma_f32_16x16x32_bf16 v[108:111], v[158:161], v[174:177], v[108:111]
	v_mfma_f32_16x16x32_bf16 v[100:103], v[166:169], v[174:177], v[100:103]
	v_mfma_f32_16x16x32_bf16 v[92:95], v[158:161], v[182:185], v[92:95]
	v_mfma_f32_16x16x32_bf16 v[84:87], v[166:169], v[182:185], v[84:87]
	v_mfma_f32_16x16x32_bf16 v[76:79], v[158:161], v[190:193], v[76:79]
	v_mfma_f32_16x16x32_bf16 v[72:75], v[166:169], v[190:193], v[72:75]
	v_mfma_f32_16x16x32_bf16 v[68:71], v[158:161], v[198:201], v[68:71]
	v_mfma_f32_16x16x32_bf16 v[64:67], v[166:169], v[198:201], v[64:67]
	v_mfma_f32_16x16x32_bf16 v[108:111], v[162:165], v[178:181], v[108:111]
	v_mfma_f32_16x16x32_bf16 v[100:103], v[170:173], v[178:181], v[100:103]
	v_mfma_f32_16x16x32_bf16 v[92:95], v[162:165], v[186:189], v[92:95]
	v_mfma_f32_16x16x32_bf16 v[84:87], v[170:173], v[186:189], v[84:87]
	v_mfma_f32_16x16x32_bf16 v[76:79], v[162:165], v[194:197], v[76:79]
	v_mfma_f32_16x16x32_bf16 v[72:75], v[170:173], v[194:197], v[72:75]
	v_mfma_f32_16x16x32_bf16 v[68:71], v[162:165], v[206:209], v[68:71]
	v_mfma_f32_16x16x32_bf16 v[64:67], v[170:173], v[206:209], v[64:67]
	s_setprio 0
	s_barrier
	s_add_i32 s30, s58, s38
	v_lshl_add_u64 v[202:203], v[202:203], 0, s[6:7]
	s_mov_b32 m0, s30
	ds_read_b128 v[174:177], v141 offset:49152
	ds_read_b128 v[178:181], v141 offset:50176
	ds_read_b128 v[182:185], v141 offset:51200
	ds_read_b128 v[186:189], v141 offset:52224
	ds_read_b128 v[190:193], v141 offset:53248
	ds_read_b128 v[194:197], v141 offset:54272
	ds_read_b128 v[198:201], v141 offset:55296
	ds_read_b128 v[206:209], v141 offset:56320
	global_load_lds_dwordx4 v[202:203], off
	s_add_i32 m0, s30, 0x2000
	s_add_u32 s28, s28, 0x40080
	v_lshl_add_u64 v[202:203], v[210:211], 0, s[6:7]
	s_addc_u32 s29, s29, 0
	s_add_i32 s30, s59, s38
	global_load_lds_dwordx4 v[202:203], off
	v_lshl_add_u64 v[202:203], s[28:29], 0, v[136:137]
	s_mov_b32 m0, s30
	s_nop 0
	global_load_lds_dwordx4 v[202:203], off
	v_lshl_add_u64 v[202:203], s[28:29], 0, v[138:139]
	s_add_i32 m0, s30, 0x2000
	s_nop 0
	global_load_lds_dwordx4 v[202:203], off
	v_lshl_add_u64 v[202:203], v[212:213], 0, s[6:7]
	s_mov_b32 m0, s46
	s_nop 0
	global_load_lds_dwordx4 v[202:203], off
	v_lshl_add_u64 v[202:203], v[214:215], 0, s[6:7]
	s_mov_b32 m0, s47
	s_nop 0
	global_load_lds_dwordx4 v[202:203], off
	s_waitcnt vmcnt(8)
	s_waitcnt lgkmcnt(0)
	s_barrier
	s_setprio 1
	s_waitcnt lgkmcnt(0)
	v_mfma_f32_16x16x32_bf16 v[60:63], v[142:145], v[174:177], v[60:63]
	v_mfma_f32_16x16x32_bf16 v[56:59], v[150:153], v[174:177], v[56:59]
	v_mfma_f32_16x16x32_bf16 v[52:55], v[142:145], v[182:185], v[52:55]
	v_mfma_f32_16x16x32_bf16 v[48:51], v[150:153], v[182:185], v[48:51]
	v_mfma_f32_16x16x32_bf16 v[40:43], v[142:145], v[190:193], v[40:43]
	v_mfma_f32_16x16x32_bf16 v[32:35], v[150:153], v[190:193], v[32:35]
	v_mfma_f32_16x16x32_bf16 v[24:27], v[142:145], v[198:201], v[24:27]
	v_mfma_f32_16x16x32_bf16 v[16:19], v[150:153], v[198:201], v[16:19]
	v_mfma_f32_16x16x32_bf16 v[60:63], v[146:149], v[178:181], v[60:63]
	v_mfma_f32_16x16x32_bf16 v[56:59], v[154:157], v[178:181], v[56:59]
	v_mfma_f32_16x16x32_bf16 v[52:55], v[146:149], v[186:189], v[52:55]
	v_mfma_f32_16x16x32_bf16 v[48:51], v[154:157], v[186:189], v[48:51]
	v_mfma_f32_16x16x32_bf16 v[40:43], v[146:149], v[194:197], v[40:43]
	v_mfma_f32_16x16x32_bf16 v[32:35], v[154:157], v[194:197], v[32:35]
	v_mfma_f32_16x16x32_bf16 v[24:27], v[146:149], v[206:209], v[24:27]
	v_mfma_f32_16x16x32_bf16 v[16:19], v[154:157], v[206:209], v[16:19]
	s_setprio 0
	s_setprio 1
	v_mfma_f32_16x16x32_bf16 v[44:47], v[158:161], v[174:177], v[44:47]
	v_mfma_f32_16x16x32_bf16 v[36:39], v[166:169], v[174:177], v[36:39]
	v_mfma_f32_16x16x32_bf16 v[28:31], v[158:161], v[182:185], v[28:31]
	v_mfma_f32_16x16x32_bf16 v[20:23], v[166:169], v[182:185], v[20:23]
	v_mfma_f32_16x16x32_bf16 v[12:15], v[158:161], v[190:193], v[12:15]
	v_mfma_f32_16x16x32_bf16 v[8:11], v[166:169], v[190:193], v[8:11]
	v_mfma_f32_16x16x32_bf16 v[4:7], v[158:161], v[198:201], v[4:7]
	v_mfma_f32_16x16x32_bf16 v[0:3], v[166:169], v[198:201], v[0:3]
	v_mfma_f32_16x16x32_bf16 v[44:47], v[162:165], v[178:181], v[44:47]
	v_mfma_f32_16x16x32_bf16 v[36:39], v[170:173], v[178:181], v[36:39]
	v_mfma_f32_16x16x32_bf16 v[28:31], v[162:165], v[186:189], v[28:31]
	v_mfma_f32_16x16x32_bf16 v[20:23], v[170:173], v[186:189], v[20:23]
	v_mfma_f32_16x16x32_bf16 v[12:15], v[162:165], v[194:197], v[12:15]
	v_mfma_f32_16x16x32_bf16 v[8:11], v[170:173], v[194:197], v[8:11]
	v_mfma_f32_16x16x32_bf16 v[4:7], v[162:165], v[206:209], v[4:7]
	v_mfma_f32_16x16x32_bf16 v[0:3], v[170:173], v[206:209], v[0:3]
	s_add_i32 s57, s57, 2
	s_add_u32 s26, s26, 0x100
	s_addc_u32 s27, s27, 0
	s_add_u32 s55, s55, 0x100
	s_addc_u32 s56, s56, 0
	s_cmp_gt_u32 s57, 13
	s_setprio 0
	s_barrier
	s_cbranch_scc0 .LBB0_487
	s_and_b64 vcc, exec, s[10:11]
	s_cbranch_vccz .LBB0_490
	s_barrier

.Llsb_skip_3:
.LBB0_791:
	ds_read_b128 v[44:47], v200
	ds_read_b128 v[52:55], v200 offset:1024
	ds_read_b128 v[112:115], v200 offset:2048
	ds_read_b128 v[124:127], v200 offset:3072
	ds_read_b128 v[136:139], v201
	ds_read_b128 v[148:151], v201 offset:1024
	ds_read_b128 v[152:155], v201 offset:2048
	ds_read_b128 v[156:159], v201 offset:3072
	s_add_u32 s24, s22, 0xfffd8080
	s_addc_u32 s25, s23, -1
	s_cmp_eq_u32 s56, 6
	s_cselect_b32 s27, s19, s25
	s_cselect_b32 s26, s18, s24
	s_cselect_b32 s25, s21, s55
	s_cselect_b32 s24, s20, s54
	s_mov_b32 m0, s39
	v_lshl_add_u64 v[236:237], s[22:23], 0, v[178:179]
	ds_read_b128 v[160:163], v202
	ds_read_b128 v[208:211], v202 offset:1024
	ds_read_b128 v[212:215], v202 offset:2048
	ds_read_b128 v[216:219], v202 offset:3072
	ds_read_b128 v[220:223], v202 offset:4096
	ds_read_b128 v[224:227], v202 offset:5120
	ds_read_b128 v[228:231], v202 offset:6144
	ds_read_b128 v[232:235], v202 offset:7168
	global_load_lds_dwordx4 v[236:237], off
	v_lshl_add_u64 v[236:237], s[22:23], 0, v[180:181]
	s_mov_b32 m0, s40
	s_nop 0
	global_load_lds_dwordx4 v[236:237], off
	s_waitcnt vmcnt(8)
	s_waitcnt lgkmcnt(0)
	s_barrier
	s_setprio 1
	s_waitcnt lgkmcnt(0)
	v_mfma_f32_16x16x32_bf16 v[144:147], v[44:47], v[160:163], v[144:147]
	v_mfma_f32_16x16x32_bf16 v[140:143], v[112:115], v[160:163], v[140:143]
	v_mfma_f32_16x16x32_bf16 v[120:123], v[44:47], v[212:215], v[120:123]
	v_mfma_f32_16x16x32_bf16 v[116:119], v[112:115], v[212:215], v[116:119]
	v_mfma_f32_16x16x32_bf16 v[100:103], v[44:47], v[220:223], v[100:103]
	v_mfma_f32_16x16x32_bf16 v[96:99], v[112:115], v[220:223], v[96:99]
	v_mfma_f32_16x16x32_bf16 v[84:87], v[44:47], v[228:231], v[84:87]
	v_mfma_f32_16x16x32_bf16 v[80:83], v[112:115], v[228:231], v[80:83]
	v_mfma_f32_16x16x32_bf16 v[144:147], v[52:55], v[208:211], v[144:147]
	v_mfma_f32_16x16x32_bf16 v[140:143], v[124:127], v[208:211], v[140:143]
	v_mfma_f32_16x16x32_bf16 v[120:123], v[52:55], v[216:219], v[120:123]
	v_mfma_f32_16x16x32_bf16 v[116:119], v[124:127], v[216:219], v[116:119]
	v_mfma_f32_16x16x32_bf16 v[100:103], v[52:55], v[224:227], v[100:103]
	v_mfma_f32_16x16x32_bf16 v[96:99], v[124:127], v[224:227], v[96:99]
	v_mfma_f32_16x16x32_bf16 v[84:87], v[52:55], v[232:235], v[84:87]
	v_mfma_f32_16x16x32_bf16 v[80:83], v[124:127], v[232:235], v[80:83]
	s_setprio 0
	s_setprio 1
	v_mfma_f32_16x16x32_bf16 v[132:135], v[136:139], v[160:163], v[132:135]
	v_mfma_f32_16x16x32_bf16 v[128:131], v[152:155], v[160:163], v[128:131]
	v_mfma_f32_16x16x32_bf16 v[108:111], v[136:139], v[212:215], v[108:111]
	v_mfma_f32_16x16x32_bf16 v[104:107], v[152:155], v[212:215], v[104:107]
	v_mfma_f32_16x16x32_bf16 v[92:95], v[136:139], v[220:223], v[92:95]
	v_mfma_f32_16x16x32_bf16 v[88:91], v[152:155], v[220:223], v[88:91]
	v_mfma_f32_16x16x32_bf16 v[76:79], v[136:139], v[228:231], v[76:79]
	v_mfma_f32_16x16x32_bf16 v[72:75], v[152:155], v[228:231], v[72:75]
	v_mfma_f32_16x16x32_bf16 v[132:135], v[148:151], v[208:211], v[132:135]
	v_mfma_f32_16x16x32_bf16 v[128:131], v[156:159], v[208:211], v[128:131]
	v_mfma_f32_16x16x32_bf16 v[108:111], v[148:151], v[216:219], v[108:111]
	v_mfma_f32_16x16x32_bf16 v[104:107], v[156:159], v[216:219], v[104:107]
	v_mfma_f32_16x16x32_bf16 v[92:95], v[148:151], v[224:227], v[92:95]
	v_mfma_f32_16x16x32_bf16 v[88:91], v[156:159], v[224:227], v[88:91]
	v_mfma_f32_16x16x32_bf16 v[76:79], v[148:151], v[232:235], v[76:79]
	v_mfma_f32_16x16x32_bf16 v[72:75], v[156:159], v[232:235], v[72:75]
	s_setprio 0
	s_barrier
	s_mov_b32 m0, s41
	v_lshl_add_u64 v[236:237], s[24:25], 0, v[168:169]
	s_add_u32 s58, s24, 0x28000
	ds_read_b128 v[160:163], v202 offset:16384
	ds_read_b128 v[208:211], v202 offset:17408
	ds_read_b128 v[212:215], v202 offset:18432
	ds_read_b128 v[216:219], v202 offset:19456
	ds_read_b128 v[220:223], v202 offset:20480
	ds_read_b128 v[224:227], v202 offset:21504
	ds_read_b128 v[228:231], v202 offset:22528
	ds_read_b128 v[232:235], v202 offset:23552
	global_load_lds_dwordx4 v[236:237], off
	v_lshl_add_u64 v[238:239], s[24:25], 0, v[164:165]
	s_mov_b32 m0, s43
	s_addc_u32 s59, s25, 0
	global_load_lds_dwordx4 v[238:239], off
	v_lshl_add_u64 v[240:241], s[58:59], 0, v[168:169]
	s_mov_b32 m0, s44
	v_lshl_add_u64 v[242:243], s[26:27], 0, v[166:167]
	global_load_lds_dwordx4 v[240:241], off
	v_lshl_add_u64 v[240:241], s[58:59], 0, v[164:165]
	s_mov_b32 m0, s45
	s_nop 0
	global_load_lds_dwordx4 v[240:241], off
	v_lshl_add_u64 v[240:241], s[26:27], 0, v[170:171]
	s_mov_b32 m0, s30
	s_nop 0
	global_load_lds_dwordx4 v[240:241], off
	s_mov_b32 m0, s31
	s_nop 0
	global_load_lds_dwordx4 v[242:243], off
	s_waitcnt vmcnt(8)
	s_waitcnt lgkmcnt(0)
	s_barrier
	s_setprio 1
	s_waitcnt lgkmcnt(0)
	v_mfma_f32_16x16x32_bf16 v[68:71], v[44:47], v[160:163], v[68:71]
	v_mfma_f32_16x16x32_bf16 v[64:67], v[112:115], v[160:163], v[64:67]
	v_mfma_f32_16x16x32_bf16 v[48:51], v[44:47], v[212:215], v[48:51]
	v_mfma_f32_16x16x32_bf16 v[40:43], v[112:115], v[212:215], v[40:43]
	v_mfma_f32_16x16x32_bf16 v[28:31], v[44:47], v[220:223], v[28:31]
	v_mfma_f32_16x16x32_bf16 v[24:27], v[112:115], v[220:223], v[24:27]
	v_mfma_f32_16x16x32_bf16 v[12:15], v[44:47], v[228:231], v[12:15]
	v_mfma_f32_16x16x32_bf16 v[8:11], v[112:115], v[228:231], v[8:11]
	v_mfma_f32_16x16x32_bf16 v[68:71], v[52:55], v[208:211], v[68:71]
	v_mfma_f32_16x16x32_bf16 v[64:67], v[124:127], v[208:211], v[64:67]
	v_mfma_f32_16x16x32_bf16 v[48:51], v[52:55], v[216:219], v[48:51]
	v_mfma_f32_16x16x32_bf16 v[40:43], v[124:127], v[216:219], v[40:43]
	v_mfma_f32_16x16x32_bf16 v[28:31], v[52:55], v[224:227], v[28:31]
	v_mfma_f32_16x16x32_bf16 v[24:27], v[124:127], v[224:227], v[24:27]
	v_mfma_f32_16x16x32_bf16 v[12:15], v[52:55], v[232:235], v[12:15]
	v_mfma_f32_16x16x32_bf16 v[8:11], v[124:127], v[232:235], v[8:11]
	s_setprio 0
	s_setprio 1
	v_mfma_f32_16x16x32_bf16 v[36:39], v[136:139], v[212:215], v[36:39]
	v_mfma_f32_16x16x32_bf16 v[32:35], v[152:155], v[212:215], v[32:35]
	v_mfma_f32_16x16x32_bf16 v[20:23], v[136:139], v[220:223], v[20:23]
	v_mfma_f32_16x16x32_bf16 v[16:19], v[152:155], v[220:223], v[16:19]
	v_mfma_f32_16x16x32_bf16 v[4:7], v[136:139], v[228:231], v[4:7]
	v_mfma_f32_16x16x32_bf16 v[0:3], v[152:155], v[228:231], v[0:3]
	v_mfma_f32_16x16x32_bf16 v[44:47], v[136:139], v[160:163], v[60:63]
	v_mfma_f32_16x16x32_bf16 v[52:55], v[152:155], v[160:163], v[56:59]
	v_mfma_f32_16x16x32_bf16 v[36:39], v[148:151], v[216:219], v[36:39]
	v_mfma_f32_16x16x32_bf16 v[32:35], v[156:159], v[216:219], v[32:35]
	v_mfma_f32_16x16x32_bf16 v[20:23], v[148:151], v[224:227], v[20:23]
	v_mfma_f32_16x16x32_bf16 v[16:19], v[156:159], v[224:227], v[16:19]
	v_mfma_f32_16x16x32_bf16 v[4:7], v[148:151], v[232:235], v[4:7]
	v_mfma_f32_16x16x32_bf16 v[0:3], v[156:159], v[232:235], v[0:3]
	v_mfma_f32_16x16x32_bf16 v[44:47], v[148:151], v[208:211], v[44:47]
	v_mfma_f32_16x16x32_bf16 v[52:55], v[156:159], v[208:211], v[52:55]
	s_setprio 0
	s_barrier
	ds_read_b128 v[56:59], v203
	ds_read_b128 v[60:63], v203 offset:1024
	ds_read_b128 v[112:115], v203 offset:2048
	ds_read_b128 v[124:127], v203 offset:3072
	ds_read_b128 v[136:139], v205
	ds_read_b128 v[148:151], v205 offset:1024
	ds_read_b128 v[152:155], v205 offset:2048
	ds_read_b128 v[156:159], v205 offset:3072
	s_add_u32 s26, s26, 0x28000
	s_addc_u32 s27, s27, 0
	s_mov_b32 m0, s33
	v_lshl_add_u64 v[244:245], s[26:27], 0, v[170:171]
	ds_read_b128 v[160:163], v202 offset:32768
	ds_read_b128 v[208:211], v202 offset:33792
	ds_read_b128 v[212:215], v202 offset:34816
	ds_read_b128 v[216:219], v202 offset:35840
	ds_read_b128 v[220:223], v202 offset:36864
	ds_read_b128 v[224:227], v202 offset:37888
	ds_read_b128 v[228:231], v202 offset:38912
	ds_read_b128 v[232:235], v202 offset:39936
	global_load_lds_dwordx4 v[244:245], off
	v_lshl_add_u64 v[244:245], s[26:27], 0, v[166:167]
	s_mov_b32 m0, s34
	s_nop 0
	global_load_lds_dwordx4 v[244:245], off
	s_waitcnt vmcnt(8)
	s_waitcnt lgkmcnt(0)
	s_barrier
	s_setprio 1
	s_waitcnt lgkmcnt(0)
	v_mfma_f32_16x16x32_bf16 v[144:147], v[56:59], v[160:163], v[144:147]
	v_mfma_f32_16x16x32_bf16 v[140:143], v[112:115], v[160:163], v[140:143]
	v_mfma_f32_16x16x32_bf16 v[120:123], v[56:59], v[212:215], v[120:123]
	v_mfma_f32_16x16x32_bf16 v[116:119], v[112:115], v[212:215], v[116:119]
	v_mfma_f32_16x16x32_bf16 v[100:103], v[56:59], v[220:223], v[100:103]
	v_mfma_f32_16x16x32_bf16 v[96:99], v[112:115], v[220:223], v[96:99]
	v_mfma_f32_16x16x32_bf16 v[84:87], v[56:59], v[228:231], v[84:87]
	v_mfma_f32_16x16x32_bf16 v[80:83], v[112:115], v[228:231], v[80:83]
	v_mfma_f32_16x16x32_bf16 v[144:147], v[60:63], v[208:211], v[144:147]
	v_mfma_f32_16x16x32_bf16 v[140:143], v[124:127], v[208:211], v[140:143]
	v_mfma_f32_16x16x32_bf16 v[120:123], v[60:63], v[216:219], v[120:123]
	v_mfma_f32_16x16x32_bf16 v[116:119], v[124:127], v[216:219], v[116:119]
	v_mfma_f32_16x16x32_bf16 v[100:103], v[60:63], v[224:227], v[100:103]
	v_mfma_f32_16x16x32_bf16 v[96:99], v[124:127], v[224:227], v[96:99]
	v_mfma_f32_16x16x32_bf16 v[84:87], v[60:63], v[232:235], v[84:87]
	v_mfma_f32_16x16x32_bf16 v[80:83], v[124:127], v[232:235], v[80:83]
	s_setprio 0
	s_setprio 1
	v_mfma_f32_16x16x32_bf16 v[132:135], v[136:139], v[160:163], v[132:135]
	v_mfma_f32_16x16x32_bf16 v[128:131], v[152:155], v[160:163], v[128:131]
	v_mfma_f32_16x16x32_bf16 v[108:111], v[136:139], v[212:215], v[108:111]
	v_mfma_f32_16x16x32_bf16 v[104:107], v[152:155], v[212:215], v[104:107]
	v_mfma_f32_16x16x32_bf16 v[92:95], v[136:139], v[220:223], v[92:95]
	v_mfma_f32_16x16x32_bf16 v[88:91], v[152:155], v[220:223], v[88:91]
	v_mfma_f32_16x16x32_bf16 v[76:79], v[136:139], v[228:231], v[76:79]
	v_mfma_f32_16x16x32_bf16 v[72:75], v[152:155], v[228:231], v[72:75]
	v_mfma_f32_16x16x32_bf16 v[132:135], v[148:151], v[208:211], v[132:135]
	v_mfma_f32_16x16x32_bf16 v[128:131], v[156:159], v[208:211], v[128:131]
	v_mfma_f32_16x16x32_bf16 v[108:111], v[148:151], v[216:219], v[108:111]
	v_mfma_f32_16x16x32_bf16 v[104:107], v[156:159], v[216:219], v[104:107]
	v_mfma_f32_16x16x32_bf16 v[92:95], v[148:151], v[224:227], v[92:95]
	v_mfma_f32_16x16x32_bf16 v[88:91], v[156:159], v[224:227], v[88:91]
	v_mfma_f32_16x16x32_bf16 v[76:79], v[148:151], v[232:235], v[76:79]
	v_mfma_f32_16x16x32_bf16 v[72:75], v[156:159], v[232:235], v[72:75]
	s_setprio 0
	s_barrier
	s_mov_b32 m0, s46
	v_lshl_add_u64 v[236:237], v[236:237], 0, s[14:15]
	s_add_u32 s24, s24, 0x28080
	ds_read_b128 v[160:163], v202 offset:49152
	ds_read_b128 v[208:211], v202 offset:50176
	ds_read_b128 v[212:215], v202 offset:51200
	ds_read_b128 v[216:219], v202 offset:52224
	ds_read_b128 v[220:223], v202 offset:53248
	ds_read_b128 v[224:227], v202 offset:54272
	ds_read_b128 v[228:231], v202 offset:55296
	ds_read_b128 v[232:235], v202 offset:56320
	global_load_lds_dwordx4 v[236:237], off
	v_lshl_add_u64 v[236:237], v[238:239], 0, s[14:15]
	s_mov_b32 m0, s47
	s_addc_u32 s25, s25, 0
	global_load_lds_dwordx4 v[236:237], off
	v_lshl_add_u64 v[236:237], s[24:25], 0, v[168:169]
	s_mov_b32 m0, s48
	s_nop 0
	global_load_lds_dwordx4 v[236:237], off
	v_lshl_add_u64 v[236:237], s[24:25], 0, v[164:165]
	s_mov_b32 m0, s49
	s_nop 0
	global_load_lds_dwordx4 v[236:237], off
	v_lshl_add_u64 v[236:237], v[240:241], 0, s[14:15]
	s_mov_b32 m0, s37
	s_nop 0
	global_load_lds_dwordx4 v[236:237], off
	v_lshl_add_u64 v[236:237], v[242:243], 0, s[14:15]
	s_mov_b32 m0, s38
	s_nop 0
	global_load_lds_dwordx4 v[236:237], off
	s_waitcnt vmcnt(8)
	s_waitcnt lgkmcnt(0)
	s_barrier
	s_setprio 1
	s_waitcnt lgkmcnt(0)
	v_mfma_f32_16x16x32_bf16 v[68:71], v[56:59], v[160:163], v[68:71]
	v_mfma_f32_16x16x32_bf16 v[64:67], v[112:115], v[160:163], v[64:67]
	v_mfma_f32_16x16x32_bf16 v[48:51], v[56:59], v[212:215], v[48:51]
	v_mfma_f32_16x16x32_bf16 v[40:43], v[112:115], v[212:215], v[40:43]
	v_mfma_f32_16x16x32_bf16 v[28:31], v[56:59], v[220:223], v[28:31]
	v_mfma_f32_16x16x32_bf16 v[24:27], v[112:115], v[220:223], v[24:27]
	v_mfma_f32_16x16x32_bf16 v[12:15], v[56:59], v[228:231], v[12:15]
	v_mfma_f32_16x16x32_bf16 v[8:11], v[112:115], v[228:231], v[8:11]
	v_mfma_f32_16x16x32_bf16 v[68:71], v[60:63], v[208:211], v[68:71]
	v_mfma_f32_16x16x32_bf16 v[64:67], v[124:127], v[208:211], v[64:67]
	v_mfma_f32_16x16x32_bf16 v[48:51], v[60:63], v[216:219], v[48:51]
	v_mfma_f32_16x16x32_bf16 v[40:43], v[124:127], v[216:219], v[40:43]
	v_mfma_f32_16x16x32_bf16 v[28:31], v[60:63], v[224:227], v[28:31]
	v_mfma_f32_16x16x32_bf16 v[24:27], v[124:127], v[224:227], v[24:27]
	v_mfma_f32_16x16x32_bf16 v[12:15], v[60:63], v[232:235], v[12:15]
	v_mfma_f32_16x16x32_bf16 v[8:11], v[124:127], v[232:235], v[8:11]
	s_setprio 0
	s_setprio 1
	v_mfma_f32_16x16x32_bf16 v[44:47], v[136:139], v[160:163], v[44:47]
	v_mfma_f32_16x16x32_bf16 v[60:63], v[148:151], v[208:211], v[44:47]
	v_mfma_f32_16x16x32_bf16 v[44:47], v[152:155], v[160:163], v[52:55]
	v_mfma_f32_16x16x32_bf16 v[36:39], v[136:139], v[212:215], v[36:39]
	v_mfma_f32_16x16x32_bf16 v[32:35], v[152:155], v[212:215], v[32:35]
	v_mfma_f32_16x16x32_bf16 v[20:23], v[136:139], v[220:223], v[20:23]
	v_mfma_f32_16x16x32_bf16 v[16:19], v[152:155], v[220:223], v[16:19]
	v_mfma_f32_16x16x32_bf16 v[4:7], v[136:139], v[228:231], v[4:7]
	v_mfma_f32_16x16x32_bf16 v[0:3], v[152:155], v[228:231], v[0:3]
	v_mfma_f32_16x16x32_bf16 v[56:59], v[156:159], v[208:211], v[44:47]
	v_mfma_f32_16x16x32_bf16 v[36:39], v[148:151], v[216:219], v[36:39]
	v_mfma_f32_16x16x32_bf16 v[32:35], v[156:159], v[216:219], v[32:35]
	v_mfma_f32_16x16x32_bf16 v[20:23], v[148:151], v[224:227], v[20:23]
	v_mfma_f32_16x16x32_bf16 v[16:19], v[156:159], v[224:227], v[16:19]
	v_mfma_f32_16x16x32_bf16 v[4:7], v[148:151], v[232:235], v[4:7]
	v_mfma_f32_16x16x32_bf16 v[0:3], v[156:159], v[232:235], v[0:3]
	s_add_i32 s56, s56, 2
	s_add_u32 s22, s22, 0x100
	s_addc_u32 s23, s23, 0
	s_add_u32 s54, s54, 0x100
	s_addc_u32 s55, s55, 0
	s_cmp_gt_u32 s56, 7
	s_setprio 0
	s_barrier
	s_cbranch_scc0 .LBB0_791
	s_and_b64 vcc, exec, s[16:17]
	s_cbranch_vccz .LBB0_794
	s_barrier

.Llsb_skip_4:
.LBB0_807:
	ds_read_b128 v[128:131], v175
	ds_read_b128 v[132:135], v175 offset:1024
	ds_read_b128 v[136:139], v175 offset:2048
	ds_read_b128 v[140:143], v175 offset:3072
	ds_read_b128 v[144:147], v176
	ds_read_b128 v[160:163], v176 offset:1024
	ds_read_b128 v[164:167], v176 offset:2048
	ds_read_b128 v[168:171], v176 offset:3072
	s_add_u32 s30, s28, 0xfffe0080
	s_addc_u32 s31, s29, -1
	s_cmp_eq_u32 s56, 4
	s_cselect_b32 s35, s17, s31
	s_cselect_b32 s34, s52, s30
	s_cselect_b32 s31, s19, s55
	s_cselect_b32 s30, s53, s54
	s_mov_b32 m0, s46
	v_lshl_add_u64 v[182:183], s[28:29], 0, v[156:157]
	ds_read_b128 v[178:181], v177
	ds_read_b128 v[188:191], v177 offset:1024
	ds_read_b128 v[192:195], v177 offset:2048
	ds_read_b128 v[196:199], v177 offset:3072
	ds_read_b128 v[200:203], v177 offset:4096
	ds_read_b128 v[206:209], v177 offset:5120
	ds_read_b128 v[210:213], v177 offset:6144
	ds_read_b128 v[214:217], v177 offset:7168
	global_load_lds_dwordx4 v[182:183], off
	v_lshl_add_u64 v[182:183], s[28:29], 0, v[158:159]
	s_mov_b32 m0, s47
	s_nop 0
	global_load_lds_dwordx4 v[182:183], off
	s_waitcnt vmcnt(8)
	s_waitcnt lgkmcnt(0)
	s_barrier
	s_setprio 1
	s_waitcnt lgkmcnt(0)
	v_mfma_f32_16x16x32_bf16 v[124:127], v[128:131], v[178:181], v[124:127]
	v_mfma_f32_16x16x32_bf16 v[120:123], v[136:139], v[178:181], v[120:123]
	v_mfma_f32_16x16x32_bf16 v[108:111], v[128:131], v[192:195], v[108:111]
	v_mfma_f32_16x16x32_bf16 v[104:107], v[136:139], v[192:195], v[104:107]
	v_mfma_f32_16x16x32_bf16 v[92:95], v[128:131], v[200:203], v[92:95]
	v_mfma_f32_16x16x32_bf16 v[88:91], v[136:139], v[200:203], v[88:91]
	v_mfma_f32_16x16x32_bf16 v[76:79], v[128:131], v[210:213], v[76:79]
	v_mfma_f32_16x16x32_bf16 v[72:75], v[136:139], v[210:213], v[72:75]
	v_mfma_f32_16x16x32_bf16 v[124:127], v[132:135], v[188:191], v[124:127]
	v_mfma_f32_16x16x32_bf16 v[120:123], v[140:143], v[188:191], v[120:123]
	v_mfma_f32_16x16x32_bf16 v[108:111], v[132:135], v[196:199], v[108:111]
	v_mfma_f32_16x16x32_bf16 v[104:107], v[140:143], v[196:199], v[104:107]
	v_mfma_f32_16x16x32_bf16 v[92:95], v[132:135], v[206:209], v[92:95]
	v_mfma_f32_16x16x32_bf16 v[88:91], v[140:143], v[206:209], v[88:91]
	v_mfma_f32_16x16x32_bf16 v[76:79], v[132:135], v[214:217], v[76:79]
	v_mfma_f32_16x16x32_bf16 v[72:75], v[140:143], v[214:217], v[72:75]
	s_setprio 0
	s_setprio 1
	v_mfma_f32_16x16x32_bf16 v[116:119], v[144:147], v[178:181], v[116:119]
	v_mfma_f32_16x16x32_bf16 v[112:115], v[164:167], v[178:181], v[112:115]
	v_mfma_f32_16x16x32_bf16 v[100:103], v[144:147], v[192:195], v[100:103]
	v_mfma_f32_16x16x32_bf16 v[96:99], v[164:167], v[192:195], v[96:99]
	v_mfma_f32_16x16x32_bf16 v[84:87], v[144:147], v[200:203], v[84:87]
	v_mfma_f32_16x16x32_bf16 v[80:83], v[164:167], v[200:203], v[80:83]
	v_mfma_f32_16x16x32_bf16 v[68:71], v[144:147], v[210:213], v[68:71]
	v_mfma_f32_16x16x32_bf16 v[64:67], v[164:167], v[210:213], v[64:67]
	v_mfma_f32_16x16x32_bf16 v[116:119], v[160:163], v[188:191], v[116:119]
	v_mfma_f32_16x16x32_bf16 v[112:115], v[168:171], v[188:191], v[112:115]
	v_mfma_f32_16x16x32_bf16 v[100:103], v[160:163], v[196:199], v[100:103]
	v_mfma_f32_16x16x32_bf16 v[96:99], v[168:171], v[196:199], v[96:99]
	v_mfma_f32_16x16x32_bf16 v[84:87], v[160:163], v[206:209], v[84:87]
	v_mfma_f32_16x16x32_bf16 v[80:83], v[168:171], v[206:209], v[80:83]
	v_mfma_f32_16x16x32_bf16 v[68:71], v[160:163], v[214:217], v[68:71]
	v_mfma_f32_16x16x32_bf16 v[64:67], v[168:171], v[214:217], v[64:67]
	s_setprio 0
	s_barrier
	s_mov_b32 m0, s48
	v_lshl_add_u64 v[182:183], s[30:31], 0, v[152:153]
	s_add_u32 s58, s30, 0x20000
	ds_read_b128 v[178:181], v177 offset:16384
	ds_read_b128 v[188:191], v177 offset:17408
	ds_read_b128 v[192:195], v177 offset:18432
	ds_read_b128 v[196:199], v177 offset:19456
	ds_read_b128 v[200:203], v177 offset:20480
	ds_read_b128 v[206:209], v177 offset:21504
	ds_read_b128 v[210:213], v177 offset:22528
	ds_read_b128 v[214:217], v177 offset:23552
	global_load_lds_dwordx4 v[182:183], off
	v_lshl_add_u64 v[218:219], s[30:31], 0, v[148:149]
	s_mov_b32 m0, s49
	s_addc_u32 s59, s31, 0
	global_load_lds_dwordx4 v[218:219], off
	v_lshl_add_u64 v[220:221], s[58:59], 0, v[152:153]
	s_mov_b32 m0, s50
	v_lshl_add_u64 v[222:223], s[34:35], 0, v[150:151]
	global_load_lds_dwordx4 v[220:221], off
	v_lshl_add_u64 v[220:221], s[58:59], 0, v[148:149]
	s_add_i32 m0, s50, 0x2000
	s_nop 0
	global_load_lds_dwordx4 v[220:221], off
	v_lshl_add_u64 v[220:221], s[34:35], 0, v[154:155]
	s_mov_b32 m0, s27
	s_nop 0
	global_load_lds_dwordx4 v[220:221], off
	s_mov_b32 m0, s39
	s_nop 0
	global_load_lds_dwordx4 v[222:223], off
	s_waitcnt vmcnt(8)
	s_waitcnt lgkmcnt(0)
	s_barrier
	s_setprio 1
	s_waitcnt lgkmcnt(0)
	v_mfma_f32_16x16x32_bf16 v[60:63], v[128:131], v[178:181], v[60:63]
	v_mfma_f32_16x16x32_bf16 v[56:59], v[136:139], v[178:181], v[56:59]
	v_mfma_f32_16x16x32_bf16 v[44:47], v[128:131], v[192:195], v[44:47]
	v_mfma_f32_16x16x32_bf16 v[40:43], v[136:139], v[192:195], v[40:43]
	v_mfma_f32_16x16x32_bf16 v[28:31], v[128:131], v[200:203], v[28:31]
	v_mfma_f32_16x16x32_bf16 v[24:27], v[136:139], v[200:203], v[24:27]
	v_mfma_f32_16x16x32_bf16 v[12:15], v[128:131], v[210:213], v[12:15]
	v_mfma_f32_16x16x32_bf16 v[8:11], v[136:139], v[210:213], v[8:11]
	v_mfma_f32_16x16x32_bf16 v[60:63], v[132:135], v[188:191], v[60:63]
	v_mfma_f32_16x16x32_bf16 v[56:59], v[140:143], v[188:191], v[56:59]
	v_mfma_f32_16x16x32_bf16 v[44:47], v[132:135], v[196:199], v[44:47]
	v_mfma_f32_16x16x32_bf16 v[40:43], v[140:143], v[196:199], v[40:43]
	v_mfma_f32_16x16x32_bf16 v[28:31], v[132:135], v[206:209], v[28:31]
	v_mfma_f32_16x16x32_bf16 v[24:27], v[140:143], v[206:209], v[24:27]
	v_mfma_f32_16x16x32_bf16 v[12:15], v[132:135], v[214:217], v[12:15]
	v_mfma_f32_16x16x32_bf16 v[8:11], v[140:143], v[214:217], v[8:11]
	s_setprio 0
	s_setprio 1
	v_mfma_f32_16x16x32_bf16 v[52:55], v[144:147], v[178:181], v[52:55]
	v_mfma_f32_16x16x32_bf16 v[48:51], v[164:167], v[178:181], v[48:51]
	v_mfma_f32_16x16x32_bf16 v[36:39], v[144:147], v[192:195], v[36:39]
	v_mfma_f32_16x16x32_bf16 v[32:35], v[164:167], v[192:195], v[32:35]
	v_mfma_f32_16x16x32_bf16 v[20:23], v[144:147], v[200:203], v[20:23]
	v_mfma_f32_16x16x32_bf16 v[16:19], v[164:167], v[200:203], v[16:19]
	v_mfma_f32_16x16x32_bf16 v[4:7], v[144:147], v[210:213], v[4:7]
	v_mfma_f32_16x16x32_bf16 v[0:3], v[164:167], v[210:213], v[0:3]
	v_mfma_f32_16x16x32_bf16 v[52:55], v[160:163], v[188:191], v[52:55]
	v_mfma_f32_16x16x32_bf16 v[48:51], v[168:171], v[188:191], v[48:51]
	v_mfma_f32_16x16x32_bf16 v[36:39], v[160:163], v[196:199], v[36:39]
	v_mfma_f32_16x16x32_bf16 v[32:35], v[168:171], v[196:199], v[32:35]
	v_mfma_f32_16x16x32_bf16 v[20:23], v[160:163], v[206:209], v[20:23]
	v_mfma_f32_16x16x32_bf16 v[16:19], v[168:171], v[206:209], v[16:19]
	v_mfma_f32_16x16x32_bf16 v[4:7], v[160:163], v[214:217], v[4:7]
	v_mfma_f32_16x16x32_bf16 v[0:3], v[168:171], v[214:217], v[0:3]
	s_setprio 0
	s_barrier
	s_add_i32 s57, 0, 0x18000
	s_add_i32 s58, 0, 0x1c000
	v_add_u32_e32 v140, s57, v173
	v_add_u32_e32 v168, s58, v173
	ds_read_b128 v[128:131], v140
	ds_read_b128 v[132:135], v140 offset:1024
	ds_read_b128 v[136:139], v140 offset:2048
	ds_read_b128 v[140:143], v140 offset:3072
	ds_read_b128 v[144:147], v168
	ds_read_b128 v[160:163], v168 offset:1024
	ds_read_b128 v[164:167], v168 offset:2048
	ds_read_b128 v[168:171], v168 offset:3072
	s_add_u32 s34, s34, 0x20000
	s_addc_u32 s35, s35, 0
	s_mov_b32 m0, s40
	v_lshl_add_u64 v[224:225], s[34:35], 0, v[154:155]
	ds_read_b128 v[178:181], v177 offset:32768
	ds_read_b128 v[188:191], v177 offset:33792
	ds_read_b128 v[192:195], v177 offset:34816
	ds_read_b128 v[196:199], v177 offset:35840
	ds_read_b128 v[200:203], v177 offset:36864
	ds_read_b128 v[206:209], v177 offset:37888
	ds_read_b128 v[210:213], v177 offset:38912
	ds_read_b128 v[214:217], v177 offset:39936
	global_load_lds_dwordx4 v[224:225], off
	v_lshl_add_u64 v[224:225], s[34:35], 0, v[150:151]
	s_mov_b32 m0, s41
	s_nop 0
	global_load_lds_dwordx4 v[224:225], off
	s_waitcnt vmcnt(8)
	s_waitcnt lgkmcnt(0)
	s_barrier
	s_setprio 1
	s_waitcnt lgkmcnt(0)
	v_mfma_f32_16x16x32_bf16 v[124:127], v[128:131], v[178:181], v[124:127]
	v_mfma_f32_16x16x32_bf16 v[120:123], v[136:139], v[178:181], v[120:123]
	v_mfma_f32_16x16x32_bf16 v[108:111], v[128:131], v[192:195], v[108:111]
	v_mfma_f32_16x16x32_bf16 v[104:107], v[136:139], v[192:195], v[104:107]
	v_mfma_f32_16x16x32_bf16 v[92:95], v[128:131], v[200:203], v[92:95]
	v_mfma_f32_16x16x32_bf16 v[88:91], v[136:139], v[200:203], v[88:91]
	v_mfma_f32_16x16x32_bf16 v[76:79], v[128:131], v[210:213], v[76:79]
	v_mfma_f32_16x16x32_bf16 v[72:75], v[136:139], v[210:213], v[72:75]
	v_mfma_f32_16x16x32_bf16 v[124:127], v[132:135], v[188:191], v[124:127]
	v_mfma_f32_16x16x32_bf16 v[120:123], v[140:143], v[188:191], v[120:123]
	v_mfma_f32_16x16x32_bf16 v[108:111], v[132:135], v[196:199], v[108:111]
	v_mfma_f32_16x16x32_bf16 v[104:107], v[140:143], v[196:199], v[104:107]
	v_mfma_f32_16x16x32_bf16 v[92:95], v[132:135], v[206:209], v[92:95]
	v_mfma_f32_16x16x32_bf16 v[88:91], v[140:143], v[206:209], v[88:91]
	v_mfma_f32_16x16x32_bf16 v[76:79], v[132:135], v[214:217], v[76:79]
	v_mfma_f32_16x16x32_bf16 v[72:75], v[140:143], v[214:217], v[72:75]
	s_setprio 0
	s_setprio 1
	v_mfma_f32_16x16x32_bf16 v[116:119], v[144:147], v[178:181], v[116:119]
	v_mfma_f32_16x16x32_bf16 v[112:115], v[164:167], v[178:181], v[112:115]
	v_mfma_f32_16x16x32_bf16 v[100:103], v[144:147], v[192:195], v[100:103]
	v_mfma_f32_16x16x32_bf16 v[96:99], v[164:167], v[192:195], v[96:99]
	v_mfma_f32_16x16x32_bf16 v[84:87], v[144:147], v[200:203], v[84:87]
	v_mfma_f32_16x16x32_bf16 v[80:83], v[164:167], v[200:203], v[80:83]
	v_mfma_f32_16x16x32_bf16 v[68:71], v[144:147], v[210:213], v[68:71]
	v_mfma_f32_16x16x32_bf16 v[64:67], v[164:167], v[210:213], v[64:67]
	v_mfma_f32_16x16x32_bf16 v[116:119], v[160:163], v[188:191], v[116:119]
	v_mfma_f32_16x16x32_bf16 v[112:115], v[168:171], v[188:191], v[112:115]
	v_mfma_f32_16x16x32_bf16 v[100:103], v[160:163], v[196:199], v[100:103]
	v_mfma_f32_16x16x32_bf16 v[96:99], v[168:171], v[196:199], v[96:99]
	v_mfma_f32_16x16x32_bf16 v[84:87], v[160:163], v[206:209], v[84:87]
	v_mfma_f32_16x16x32_bf16 v[80:83], v[168:171], v[206:209], v[80:83]
	v_mfma_f32_16x16x32_bf16 v[68:71], v[160:163], v[214:217], v[68:71]
	v_mfma_f32_16x16x32_bf16 v[64:67], v[168:171], v[214:217], v[64:67]
	s_setprio 0
	s_barrier
	s_add_i32 s34, s57, s38
	v_lshl_add_u64 v[182:183], v[182:183], 0, s[10:11]
	s_mov_b32 m0, s34
	ds_read_b128 v[178:181], v177 offset:49152
	ds_read_b128 v[188:191], v177 offset:50176
	ds_read_b128 v[192:195], v177 offset:51200
	ds_read_b128 v[196:199], v177 offset:52224
	ds_read_b128 v[200:203], v177 offset:53248
	ds_read_b128 v[206:209], v177 offset:54272
	ds_read_b128 v[210:213], v177 offset:55296
	ds_read_b128 v[214:217], v177 offset:56320
	global_load_lds_dwordx4 v[182:183], off
	s_add_i32 m0, s34, 0x2000
	s_add_u32 s30, s30, 0x20080
	v_lshl_add_u64 v[182:183], v[218:219], 0, s[10:11]
	s_addc_u32 s31, s31, 0
	s_add_i32 s34, s58, s38
	global_load_lds_dwordx4 v[182:183], off
	v_lshl_add_u64 v[182:183], s[30:31], 0, v[152:153]
	s_mov_b32 m0, s34
	s_nop 0
	global_load_lds_dwordx4 v[182:183], off
	v_lshl_add_u64 v[182:183], s[30:31], 0, v[148:149]
	s_add_i32 m0, s34, 0x2000
	s_nop 0
	global_load_lds_dwordx4 v[182:183], off
	v_lshl_add_u64 v[182:183], v[220:221], 0, s[10:11]
	s_mov_b32 m0, s42
	s_nop 0
	global_load_lds_dwordx4 v[182:183], off
	v_lshl_add_u64 v[182:183], v[222:223], 0, s[10:11]
	s_mov_b32 m0, s43
	s_nop 0
	global_load_lds_dwordx4 v[182:183], off
	s_waitcnt vmcnt(8)
	s_waitcnt lgkmcnt(0)
	s_barrier
	s_setprio 1
	s_waitcnt lgkmcnt(0)
	v_mfma_f32_16x16x32_bf16 v[60:63], v[128:131], v[178:181], v[60:63]
	v_mfma_f32_16x16x32_bf16 v[56:59], v[136:139], v[178:181], v[56:59]
	v_mfma_f32_16x16x32_bf16 v[44:47], v[128:131], v[192:195], v[44:47]
	v_mfma_f32_16x16x32_bf16 v[40:43], v[136:139], v[192:195], v[40:43]
	v_mfma_f32_16x16x32_bf16 v[28:31], v[128:131], v[200:203], v[28:31]
	v_mfma_f32_16x16x32_bf16 v[24:27], v[136:139], v[200:203], v[24:27]
	v_mfma_f32_16x16x32_bf16 v[12:15], v[128:131], v[210:213], v[12:15]
	v_mfma_f32_16x16x32_bf16 v[8:11], v[136:139], v[210:213], v[8:11]
	v_mfma_f32_16x16x32_bf16 v[60:63], v[132:135], v[188:191], v[60:63]
	v_mfma_f32_16x16x32_bf16 v[56:59], v[140:143], v[188:191], v[56:59]
	v_mfma_f32_16x16x32_bf16 v[44:47], v[132:135], v[196:199], v[44:47]
	v_mfma_f32_16x16x32_bf16 v[40:43], v[140:143], v[196:199], v[40:43]
	v_mfma_f32_16x16x32_bf16 v[28:31], v[132:135], v[206:209], v[28:31]
	v_mfma_f32_16x16x32_bf16 v[24:27], v[140:143], v[206:209], v[24:27]
	v_mfma_f32_16x16x32_bf16 v[12:15], v[132:135], v[214:217], v[12:15]
	v_mfma_f32_16x16x32_bf16 v[8:11], v[140:143], v[214:217], v[8:11]
	s_setprio 0
	s_setprio 1
	v_mfma_f32_16x16x32_bf16 v[52:55], v[144:147], v[178:181], v[52:55]
	v_mfma_f32_16x16x32_bf16 v[48:51], v[164:167], v[178:181], v[48:51]
	v_mfma_f32_16x16x32_bf16 v[36:39], v[144:147], v[192:195], v[36:39]
	v_mfma_f32_16x16x32_bf16 v[32:35], v[164:167], v[192:195], v[32:35]
	v_mfma_f32_16x16x32_bf16 v[20:23], v[144:147], v[200:203], v[20:23]
	v_mfma_f32_16x16x32_bf16 v[16:19], v[164:167], v[200:203], v[16:19]
	v_mfma_f32_16x16x32_bf16 v[4:7], v[144:147], v[210:213], v[4:7]
	v_mfma_f32_16x16x32_bf16 v[0:3], v[164:167], v[210:213], v[0:3]
	v_mfma_f32_16x16x32_bf16 v[52:55], v[160:163], v[188:191], v[52:55]
	v_mfma_f32_16x16x32_bf16 v[48:51], v[168:171], v[188:191], v[48:51]
	v_mfma_f32_16x16x32_bf16 v[36:39], v[160:163], v[196:199], v[36:39]
	v_mfma_f32_16x16x32_bf16 v[32:35], v[168:171], v[196:199], v[32:35]
	v_mfma_f32_16x16x32_bf16 v[20:23], v[160:163], v[206:209], v[20:23]
	v_mfma_f32_16x16x32_bf16 v[16:19], v[168:171], v[206:209], v[16:19]
	v_mfma_f32_16x16x32_bf16 v[4:7], v[160:163], v[214:217], v[4:7]
	v_mfma_f32_16x16x32_bf16 v[0:3], v[168:171], v[214:217], v[0:3]
	s_add_i32 s56, s56, 2
	s_add_u32 s28, s28, 0x100
	s_addc_u32 s29, s29, 0
	s_add_u32 s54, s54, 0x100
	s_addc_u32 s55, s55, 0
	s_cmp_gt_u32 s56, 5
	s_setprio 0
	s_barrier
	s_cbranch_scc0 .LBB0_807
	s_and_b64 vcc, exec, s[14:15]
	s_cbranch_vccz .LBB0_810
	s_barrier

.Llsb_skip_5:
.LBB0_893:
	ds_read_b128 v[128:131], v189
	ds_read_b128 v[132:135], v189 offset:1024
	ds_read_b128 v[136:139], v189 offset:2048
	ds_read_b128 v[140:143], v189 offset:3072
	ds_read_b128 v[144:147], v190
	ds_read_b128 v[164:167], v190 offset:1024
	ds_read_b128 v[168:171], v190 offset:2048
	ds_read_b128 v[172:175], v190 offset:3072
	s_add_u32 s28, s26, 0xfffe0080
	s_addc_u32 s29, s27, -1
	s_cmp_eq_u32 s52, 4
	s_cselect_b32 s31, s19, s29
	s_cselect_b32 s30, s48, s28
	s_cselect_b32 s29, s17, s51
	s_cselect_b32 s28, s49, s50
	v_lshl_add_u64 v[226:227], s[26:27], 0, v[156:157]
	s_add_i32 m0, s25, 0xc000
	ds_read_b128 v[192:195], v191
	ds_read_b128 v[196:199], v191 offset:1024
	ds_read_b128 v[200:203], v191 offset:2048
	ds_read_b128 v[206:209], v191 offset:3072
	ds_read_b128 v[210:213], v191 offset:4096
	ds_read_b128 v[214:217], v191 offset:5120
	ds_read_b128 v[218:221], v191 offset:6144
	ds_read_b128 v[222:225], v191 offset:7168
	global_load_lds_dwordx4 v[226:227], off
	v_lshl_add_u64 v[226:227], s[26:27], 0, v[158:159]
	s_add_i32 m0, s25, 0xe000
	s_nop 0
	global_load_lds_dwordx4 v[226:227], off
	s_waitcnt vmcnt(8)
	s_waitcnt lgkmcnt(0)
	s_barrier
	s_setprio 1
	s_waitcnt lgkmcnt(0)
	v_mfma_f32_16x16x32_bf16 v[124:127], v[128:131], v[192:195], v[124:127]
	v_mfma_f32_16x16x32_bf16 v[120:123], v[136:139], v[192:195], v[120:123]
	v_mfma_f32_16x16x32_bf16 v[108:111], v[128:131], v[200:203], v[108:111]
	v_mfma_f32_16x16x32_bf16 v[104:107], v[136:139], v[200:203], v[104:107]
	v_mfma_f32_16x16x32_bf16 v[92:95], v[128:131], v[210:213], v[92:95]
	v_mfma_f32_16x16x32_bf16 v[88:91], v[136:139], v[210:213], v[88:91]
	v_mfma_f32_16x16x32_bf16 v[76:79], v[128:131], v[218:221], v[76:79]
	v_mfma_f32_16x16x32_bf16 v[72:75], v[136:139], v[218:221], v[72:75]
	v_mfma_f32_16x16x32_bf16 v[124:127], v[132:135], v[196:199], v[124:127]
	v_mfma_f32_16x16x32_bf16 v[120:123], v[140:143], v[196:199], v[120:123]
	v_mfma_f32_16x16x32_bf16 v[108:111], v[132:135], v[206:209], v[108:111]
	v_mfma_f32_16x16x32_bf16 v[104:107], v[140:143], v[206:209], v[104:107]
	v_mfma_f32_16x16x32_bf16 v[92:95], v[132:135], v[214:217], v[92:95]
	v_mfma_f32_16x16x32_bf16 v[88:91], v[140:143], v[214:217], v[88:91]
	v_mfma_f32_16x16x32_bf16 v[76:79], v[132:135], v[222:225], v[76:79]
	v_mfma_f32_16x16x32_bf16 v[72:75], v[140:143], v[222:225], v[72:75]
	s_setprio 0
	s_setprio 1
	v_mfma_f32_16x16x32_bf16 v[116:119], v[144:147], v[192:195], v[116:119]
	v_mfma_f32_16x16x32_bf16 v[112:115], v[168:171], v[192:195], v[112:115]
	v_mfma_f32_16x16x32_bf16 v[100:103], v[144:147], v[200:203], v[100:103]
	v_mfma_f32_16x16x32_bf16 v[96:99], v[168:171], v[200:203], v[96:99]
	v_mfma_f32_16x16x32_bf16 v[84:87], v[144:147], v[210:213], v[84:87]
	v_mfma_f32_16x16x32_bf16 v[80:83], v[168:171], v[210:213], v[80:83]
	v_mfma_f32_16x16x32_bf16 v[68:71], v[144:147], v[218:221], v[68:71]
	v_mfma_f32_16x16x32_bf16 v[64:67], v[168:171], v[218:221], v[64:67]
	v_mfma_f32_16x16x32_bf16 v[116:119], v[164:167], v[196:199], v[116:119]
	v_mfma_f32_16x16x32_bf16 v[112:115], v[172:175], v[196:199], v[112:115]
	v_mfma_f32_16x16x32_bf16 v[100:103], v[164:167], v[206:209], v[100:103]
	v_mfma_f32_16x16x32_bf16 v[96:99], v[172:175], v[206:209], v[96:99]
	v_mfma_f32_16x16x32_bf16 v[84:87], v[164:167], v[214:217], v[84:87]
	v_mfma_f32_16x16x32_bf16 v[80:83], v[172:175], v[214:217], v[80:83]
	v_mfma_f32_16x16x32_bf16 v[68:71], v[164:167], v[222:225], v[68:71]
	v_mfma_f32_16x16x32_bf16 v[64:67], v[172:175], v[222:225], v[64:67]
	s_setprio 0
	s_barrier
	s_add_i32 s53, s44, s36
	v_lshl_add_u64 v[226:227], s[28:29], 0, v[150:151]
	s_mov_b32 m0, s53
	ds_read_b128 v[192:195], v191 offset:16384
	ds_read_b128 v[196:199], v191 offset:17408
	ds_read_b128 v[200:203], v191 offset:18432
	ds_read_b128 v[206:209], v191 offset:19456
	ds_read_b128 v[210:213], v191 offset:20480
	ds_read_b128 v[214:217], v191 offset:21504
	ds_read_b128 v[218:221], v191 offset:22528
	ds_read_b128 v[222:225], v191 offset:23552
	global_load_lds_dwordx4 v[226:227], off
	s_add_i32 m0, s53, 0x2000
	s_add_u32 s54, s28, 0x20000
	v_lshl_add_u64 v[228:229], s[28:29], 0, v[154:155]
	s_addc_u32 s55, s29, 0
	s_add_i32 s53, s45, s36
	global_load_lds_dwordx4 v[228:229], off
	v_lshl_add_u64 v[230:231], s[54:55], 0, v[150:151]
	s_mov_b32 m0, s53
	v_lshl_add_u64 v[232:233], s[30:31], 0, v[152:153]
	global_load_lds_dwordx4 v[230:231], off
	v_lshl_add_u64 v[230:231], s[54:55], 0, v[154:155]
	s_add_i32 m0, s53, 0x2000
	s_nop 0
	global_load_lds_dwordx4 v[230:231], off
	v_lshl_add_u64 v[230:231], s[30:31], 0, v[148:149]
	s_mov_b32 m0, s25
	s_nop 0
	global_load_lds_dwordx4 v[230:231], off
	s_mov_b32 m0, s37
	s_nop 0
	global_load_lds_dwordx4 v[232:233], off
	s_waitcnt vmcnt(8)
	s_waitcnt lgkmcnt(0)
	s_barrier
	s_setprio 1
	s_waitcnt lgkmcnt(0)
	v_mfma_f32_16x16x32_bf16 v[60:63], v[128:131], v[192:195], v[60:63]
	v_mfma_f32_16x16x32_bf16 v[56:59], v[136:139], v[192:195], v[56:59]
	v_mfma_f32_16x16x32_bf16 v[44:47], v[128:131], v[200:203], v[44:47]
	v_mfma_f32_16x16x32_bf16 v[40:43], v[136:139], v[200:203], v[40:43]
	v_mfma_f32_16x16x32_bf16 v[28:31], v[128:131], v[210:213], v[28:31]
	v_mfma_f32_16x16x32_bf16 v[24:27], v[136:139], v[210:213], v[24:27]
	v_mfma_f32_16x16x32_bf16 v[12:15], v[128:131], v[218:221], v[12:15]
	v_mfma_f32_16x16x32_bf16 v[8:11], v[136:139], v[218:221], v[8:11]
	v_mfma_f32_16x16x32_bf16 v[60:63], v[132:135], v[196:199], v[60:63]
	v_mfma_f32_16x16x32_bf16 v[56:59], v[140:143], v[196:199], v[56:59]
	v_mfma_f32_16x16x32_bf16 v[44:47], v[132:135], v[206:209], v[44:47]
	v_mfma_f32_16x16x32_bf16 v[40:43], v[140:143], v[206:209], v[40:43]
	v_mfma_f32_16x16x32_bf16 v[28:31], v[132:135], v[214:217], v[28:31]
	v_mfma_f32_16x16x32_bf16 v[24:27], v[140:143], v[214:217], v[24:27]
	v_mfma_f32_16x16x32_bf16 v[12:15], v[132:135], v[222:225], v[12:15]
	v_mfma_f32_16x16x32_bf16 v[8:11], v[140:143], v[222:225], v[8:11]
	s_setprio 0
	s_setprio 1
	v_mfma_f32_16x16x32_bf16 v[52:55], v[144:147], v[192:195], v[52:55]
	v_mfma_f32_16x16x32_bf16 v[48:51], v[168:171], v[192:195], v[48:51]
	v_mfma_f32_16x16x32_bf16 v[36:39], v[144:147], v[200:203], v[36:39]
	v_mfma_f32_16x16x32_bf16 v[32:35], v[168:171], v[200:203], v[32:35]
	v_mfma_f32_16x16x32_bf16 v[20:23], v[144:147], v[210:213], v[20:23]
	v_mfma_f32_16x16x32_bf16 v[16:19], v[168:171], v[210:213], v[16:19]
	v_mfma_f32_16x16x32_bf16 v[4:7], v[144:147], v[218:221], v[4:7]
	v_mfma_f32_16x16x32_bf16 v[0:3], v[168:171], v[218:221], v[0:3]
	v_mfma_f32_16x16x32_bf16 v[52:55], v[164:167], v[196:199], v[52:55]
	v_mfma_f32_16x16x32_bf16 v[48:51], v[172:175], v[196:199], v[48:51]
	v_mfma_f32_16x16x32_bf16 v[36:39], v[164:167], v[206:209], v[36:39]
	v_mfma_f32_16x16x32_bf16 v[32:35], v[172:175], v[206:209], v[32:35]
	v_mfma_f32_16x16x32_bf16 v[20:23], v[164:167], v[214:217], v[20:23]
	v_mfma_f32_16x16x32_bf16 v[16:19], v[172:175], v[214:217], v[16:19]
	v_mfma_f32_16x16x32_bf16 v[4:7], v[164:167], v[222:225], v[4:7]
	v_mfma_f32_16x16x32_bf16 v[0:3], v[172:175], v[222:225], v[0:3]
	s_setprio 0
	s_barrier
	s_add_i32 s53, 0, 0x18000
	s_add_i32 s54, 0, 0x1c000
	v_add_u32_e32 v140, s53, v187
	v_add_u32_e32 v172, s54, v187
	ds_read_b128 v[128:131], v140
	ds_read_b128 v[132:135], v140 offset:1024
	ds_read_b128 v[136:139], v140 offset:2048
	ds_read_b128 v[140:143], v140 offset:3072
	ds_read_b128 v[144:147], v172
	ds_read_b128 v[164:167], v172 offset:1024
	ds_read_b128 v[168:171], v172 offset:2048
	ds_read_b128 v[172:175], v172 offset:3072
	s_add_u32 s30, s30, 0x20000
	s_addc_u32 s31, s31, 0
	s_mov_b32 m0, s38
	v_lshl_add_u64 v[234:235], s[30:31], 0, v[148:149]
	ds_read_b128 v[192:195], v191 offset:32768
	ds_read_b128 v[196:199], v191 offset:33792
	ds_read_b128 v[200:203], v191 offset:34816
	ds_read_b128 v[206:209], v191 offset:35840
	ds_read_b128 v[210:213], v191 offset:36864
	ds_read_b128 v[214:217], v191 offset:37888
	ds_read_b128 v[218:221], v191 offset:38912
	ds_read_b128 v[222:225], v191 offset:39936
	global_load_lds_dwordx4 v[234:235], off
	v_lshl_add_u64 v[234:235], s[30:31], 0, v[152:153]
	s_mov_b32 m0, s39
	s_nop 0
	global_load_lds_dwordx4 v[234:235], off
	s_waitcnt vmcnt(8)
	s_waitcnt lgkmcnt(0)
	s_barrier
	s_setprio 1
	s_waitcnt lgkmcnt(0)
	v_mfma_f32_16x16x32_bf16 v[124:127], v[128:131], v[192:195], v[124:127]
	v_mfma_f32_16x16x32_bf16 v[120:123], v[136:139], v[192:195], v[120:123]
	v_mfma_f32_16x16x32_bf16 v[108:111], v[128:131], v[200:203], v[108:111]
	v_mfma_f32_16x16x32_bf16 v[104:107], v[136:139], v[200:203], v[104:107]
	v_mfma_f32_16x16x32_bf16 v[92:95], v[128:131], v[210:213], v[92:95]
	v_mfma_f32_16x16x32_bf16 v[88:91], v[136:139], v[210:213], v[88:91]
	v_mfma_f32_16x16x32_bf16 v[76:79], v[128:131], v[218:221], v[76:79]
	v_mfma_f32_16x16x32_bf16 v[72:75], v[136:139], v[218:221], v[72:75]
	v_mfma_f32_16x16x32_bf16 v[124:127], v[132:135], v[196:199], v[124:127]
	v_mfma_f32_16x16x32_bf16 v[120:123], v[140:143], v[196:199], v[120:123]
	v_mfma_f32_16x16x32_bf16 v[108:111], v[132:135], v[206:209], v[108:111]
	v_mfma_f32_16x16x32_bf16 v[104:107], v[140:143], v[206:209], v[104:107]
	v_mfma_f32_16x16x32_bf16 v[92:95], v[132:135], v[214:217], v[92:95]
	v_mfma_f32_16x16x32_bf16 v[88:91], v[140:143], v[214:217], v[88:91]
	v_mfma_f32_16x16x32_bf16 v[76:79], v[132:135], v[222:225], v[76:79]
	v_mfma_f32_16x16x32_bf16 v[72:75], v[140:143], v[222:225], v[72:75]
	s_setprio 0
	s_setprio 1
	v_mfma_f32_16x16x32_bf16 v[116:119], v[144:147], v[192:195], v[116:119]
	v_mfma_f32_16x16x32_bf16 v[112:115], v[168:171], v[192:195], v[112:115]
	v_mfma_f32_16x16x32_bf16 v[100:103], v[144:147], v[200:203], v[100:103]
	v_mfma_f32_16x16x32_bf16 v[96:99], v[168:171], v[200:203], v[96:99]
	v_mfma_f32_16x16x32_bf16 v[84:87], v[144:147], v[210:213], v[84:87]
	v_mfma_f32_16x16x32_bf16 v[80:83], v[168:171], v[210:213], v[80:83]
	v_mfma_f32_16x16x32_bf16 v[68:71], v[144:147], v[218:221], v[68:71]
	v_mfma_f32_16x16x32_bf16 v[64:67], v[168:171], v[218:221], v[64:67]
	v_mfma_f32_16x16x32_bf16 v[116:119], v[164:167], v[196:199], v[116:119]
	v_mfma_f32_16x16x32_bf16 v[112:115], v[172:175], v[196:199], v[112:115]
	v_mfma_f32_16x16x32_bf16 v[100:103], v[164:167], v[206:209], v[100:103]
	v_mfma_f32_16x16x32_bf16 v[96:99], v[172:175], v[206:209], v[96:99]
	v_mfma_f32_16x16x32_bf16 v[84:87], v[164:167], v[214:217], v[84:87]
	v_mfma_f32_16x16x32_bf16 v[80:83], v[172:175], v[214:217], v[80:83]
	v_mfma_f32_16x16x32_bf16 v[68:71], v[164:167], v[222:225], v[68:71]
	v_mfma_f32_16x16x32_bf16 v[64:67], v[172:175], v[222:225], v[64:67]
	s_setprio 0
	s_barrier
	s_add_i32 s30, s53, s36
	v_lshl_add_u64 v[226:227], v[226:227], 0, s[12:13]
	s_mov_b32 m0, s30
	ds_read_b128 v[192:195], v191 offset:49152
	ds_read_b128 v[196:199], v191 offset:50176
	ds_read_b128 v[200:203], v191 offset:51200
	ds_read_b128 v[206:209], v191 offset:52224
	ds_read_b128 v[210:213], v191 offset:53248
	ds_read_b128 v[214:217], v191 offset:54272
	ds_read_b128 v[218:221], v191 offset:55296
	ds_read_b128 v[222:225], v191 offset:56320
	global_load_lds_dwordx4 v[226:227], off
	s_add_i32 m0, s30, 0x2000
	s_add_u32 s28, s28, 0x20080
	v_lshl_add_u64 v[226:227], v[228:229], 0, s[12:13]
	s_addc_u32 s29, s29, 0
	s_add_i32 s30, s54, s36
	global_load_lds_dwordx4 v[226:227], off
	v_lshl_add_u64 v[226:227], s[28:29], 0, v[150:151]
	s_mov_b32 m0, s30
	s_nop 0
	global_load_lds_dwordx4 v[226:227], off
	v_lshl_add_u64 v[226:227], s[28:29], 0, v[154:155]
	s_add_i32 m0, s30, 0x2000
	s_nop 0
	global_load_lds_dwordx4 v[226:227], off
	v_lshl_add_u64 v[226:227], v[230:231], 0, s[12:13]
	s_mov_b32 m0, s41
	s_nop 0
	global_load_lds_dwordx4 v[226:227], off
	v_lshl_add_u64 v[226:227], v[232:233], 0, s[12:13]
	s_mov_b32 m0, s42
	s_nop 0
	global_load_lds_dwordx4 v[226:227], off
	s_waitcnt vmcnt(8)
	s_waitcnt lgkmcnt(0)
	s_barrier
	s_setprio 1
	s_waitcnt lgkmcnt(0)
	v_mfma_f32_16x16x32_bf16 v[60:63], v[128:131], v[192:195], v[60:63]
	v_mfma_f32_16x16x32_bf16 v[56:59], v[136:139], v[192:195], v[56:59]
	v_mfma_f32_16x16x32_bf16 v[44:47], v[128:131], v[200:203], v[44:47]
	v_mfma_f32_16x16x32_bf16 v[40:43], v[136:139], v[200:203], v[40:43]
	v_mfma_f32_16x16x32_bf16 v[28:31], v[128:131], v[210:213], v[28:31]
	v_mfma_f32_16x16x32_bf16 v[24:27], v[136:139], v[210:213], v[24:27]
	v_mfma_f32_16x16x32_bf16 v[12:15], v[128:131], v[218:221], v[12:15]
	v_mfma_f32_16x16x32_bf16 v[8:11], v[136:139], v[218:221], v[8:11]
	v_mfma_f32_16x16x32_bf16 v[60:63], v[132:135], v[196:199], v[60:63]
	v_mfma_f32_16x16x32_bf16 v[56:59], v[140:143], v[196:199], v[56:59]
	v_mfma_f32_16x16x32_bf16 v[44:47], v[132:135], v[206:209], v[44:47]
	v_mfma_f32_16x16x32_bf16 v[40:43], v[140:143], v[206:209], v[40:43]
	v_mfma_f32_16x16x32_bf16 v[28:31], v[132:135], v[214:217], v[28:31]
	v_mfma_f32_16x16x32_bf16 v[24:27], v[140:143], v[214:217], v[24:27]
	v_mfma_f32_16x16x32_bf16 v[12:15], v[132:135], v[222:225], v[12:15]
	v_mfma_f32_16x16x32_bf16 v[8:11], v[140:143], v[222:225], v[8:11]
	s_setprio 0
	s_setprio 1
	v_mfma_f32_16x16x32_bf16 v[52:55], v[144:147], v[192:195], v[52:55]
	v_mfma_f32_16x16x32_bf16 v[48:51], v[168:171], v[192:195], v[48:51]
	v_mfma_f32_16x16x32_bf16 v[36:39], v[144:147], v[200:203], v[36:39]
	v_mfma_f32_16x16x32_bf16 v[32:35], v[168:171], v[200:203], v[32:35]
	v_mfma_f32_16x16x32_bf16 v[20:23], v[144:147], v[210:213], v[20:23]
	v_mfma_f32_16x16x32_bf16 v[16:19], v[168:171], v[210:213], v[16:19]
	v_mfma_f32_16x16x32_bf16 v[4:7], v[144:147], v[218:221], v[4:7]
	v_mfma_f32_16x16x32_bf16 v[0:3], v[168:171], v[218:221], v[0:3]
	v_mfma_f32_16x16x32_bf16 v[52:55], v[164:167], v[196:199], v[52:55]
	v_mfma_f32_16x16x32_bf16 v[48:51], v[172:175], v[196:199], v[48:51]
	v_mfma_f32_16x16x32_bf16 v[36:39], v[164:167], v[206:209], v[36:39]
	v_mfma_f32_16x16x32_bf16 v[32:35], v[172:175], v[206:209], v[32:35]
	v_mfma_f32_16x16x32_bf16 v[20:23], v[164:167], v[214:217], v[20:23]
	v_mfma_f32_16x16x32_bf16 v[16:19], v[172:175], v[214:217], v[16:19]
	v_mfma_f32_16x16x32_bf16 v[4:7], v[164:167], v[222:225], v[4:7]
	v_mfma_f32_16x16x32_bf16 v[0:3], v[172:175], v[222:225], v[0:3]
	s_add_i32 s52, s52, 2
	s_add_u32 s26, s26, 0x100
	s_addc_u32 s27, s27, 0
	s_add_u32 s50, s50, 0x100
	s_addc_u32 s51, s51, 0
	s_cmp_gt_u32 s52, 5
	s_setprio 0
	s_barrier
	s_cbranch_scc0 .LBB0_893
	s_and_b64 vcc, exec, s[14:15]
	s_cbranch_vccz .LBB0_896
	s_barrier

.Llsb_skip_6:
.LBB0_913:
	ds_read_b128 v[136:139], v154
	ds_read_b128 v[140:143], v154 offset:1024
	ds_read_b128 v[144:147], v154 offset:2048
	ds_read_b128 v[158:161], v154 offset:3072
	ds_read_b128 v[162:165], v155
	ds_read_b128 v[166:169], v155 offset:1024
	ds_read_b128 v[170:173], v155 offset:2048
	ds_read_b128 v[180:183], v155 offset:3072
	s_add_u32 s28, s26, 0xfffa0080
	s_addc_u32 s29, s27, -1
	s_cmp_eq_u32 s57, 4
	s_cselect_b32 s31, s23, s29
	s_cselect_b32 s30, s22, s28
	s_cselect_b32 s29, s25, s56
	s_cselect_b32 s28, s24, s55
	v_lshl_add_u64 v[148:149], s[26:27], 0, v[132:133]
	s_add_i32 m0, s37, 0xc000
	ds_read_b128 v[184:187], v156
	ds_read_b128 v[188:191], v156 offset:1024
	ds_read_b128 v[192:195], v156 offset:2048
	ds_read_b128 v[196:199], v156 offset:3072
	ds_read_b128 v[200:203], v156 offset:4096
	ds_read_b128 v[206:209], v156 offset:5120
	ds_read_b128 v[210:213], v156 offset:6144
	ds_read_b128 v[214:217], v156 offset:7168
	global_load_lds_dwordx4 v[148:149], off
	v_lshl_add_u64 v[148:149], s[26:27], 0, v[134:135]
	s_add_i32 m0, s37, 0xe000
	s_nop 0
	global_load_lds_dwordx4 v[148:149], off
	s_waitcnt vmcnt(8)
	s_waitcnt lgkmcnt(0)
	s_barrier
	s_setprio 1
	s_waitcnt lgkmcnt(0)
	v_mfma_f32_16x16x32_bf16 v[124:127], v[136:139], v[184:187], v[124:127]
	v_mfma_f32_16x16x32_bf16 v[120:123], v[144:147], v[184:187], v[120:123]
	v_mfma_f32_16x16x32_bf16 v[112:115], v[136:139], v[192:195], v[112:115]
	v_mfma_f32_16x16x32_bf16 v[104:107], v[144:147], v[192:195], v[104:107]
	v_mfma_f32_16x16x32_bf16 v[96:99], v[136:139], v[200:203], v[96:99]
	v_mfma_f32_16x16x32_bf16 v[88:91], v[144:147], v[200:203], v[88:91]
	v_mfma_f32_16x16x32_bf16 v[80:83], v[136:139], v[210:213], v[80:83]
	v_mfma_f32_16x16x32_bf16 v[72:75], v[144:147], v[210:213], v[72:75]
	v_mfma_f32_16x16x32_bf16 v[124:127], v[140:143], v[188:191], v[124:127]
	v_mfma_f32_16x16x32_bf16 v[120:123], v[158:161], v[188:191], v[120:123]
	v_mfma_f32_16x16x32_bf16 v[112:115], v[140:143], v[196:199], v[112:115]
	v_mfma_f32_16x16x32_bf16 v[104:107], v[158:161], v[196:199], v[104:107]
	v_mfma_f32_16x16x32_bf16 v[96:99], v[140:143], v[206:209], v[96:99]
	v_mfma_f32_16x16x32_bf16 v[88:91], v[158:161], v[206:209], v[88:91]
	v_mfma_f32_16x16x32_bf16 v[80:83], v[140:143], v[214:217], v[80:83]
	v_mfma_f32_16x16x32_bf16 v[72:75], v[158:161], v[214:217], v[72:75]
	s_setprio 0
	s_setprio 1
	v_mfma_f32_16x16x32_bf16 v[116:119], v[162:165], v[184:187], v[116:119]
	v_mfma_f32_16x16x32_bf16 v[108:111], v[170:173], v[184:187], v[108:111]
	v_mfma_f32_16x16x32_bf16 v[100:103], v[162:165], v[192:195], v[100:103]
	v_mfma_f32_16x16x32_bf16 v[92:95], v[170:173], v[192:195], v[92:95]
	v_mfma_f32_16x16x32_bf16 v[84:87], v[162:165], v[200:203], v[84:87]
	v_mfma_f32_16x16x32_bf16 v[76:79], v[170:173], v[200:203], v[76:79]
	v_mfma_f32_16x16x32_bf16 v[68:71], v[162:165], v[210:213], v[68:71]
	v_mfma_f32_16x16x32_bf16 v[64:67], v[170:173], v[210:213], v[64:67]
	v_mfma_f32_16x16x32_bf16 v[116:119], v[166:169], v[188:191], v[116:119]
	v_mfma_f32_16x16x32_bf16 v[108:111], v[180:183], v[188:191], v[108:111]
	v_mfma_f32_16x16x32_bf16 v[100:103], v[166:169], v[196:199], v[100:103]
	v_mfma_f32_16x16x32_bf16 v[92:95], v[180:183], v[196:199], v[92:95]
	v_mfma_f32_16x16x32_bf16 v[84:87], v[166:169], v[206:209], v[84:87]
	v_mfma_f32_16x16x32_bf16 v[76:79], v[180:183], v[206:209], v[76:79]
	v_mfma_f32_16x16x32_bf16 v[68:71], v[166:169], v[214:217], v[68:71]
	v_mfma_f32_16x16x32_bf16 v[64:67], v[180:183], v[214:217], v[64:67]
	s_setprio 0
	s_barrier
	s_add_i32 s58, s44, s36
	v_lshl_add_u64 v[148:149], s[28:29], 0, v[130:131]
	s_mov_b32 m0, s58
	ds_read_b128 v[184:187], v156 offset:16384
	ds_read_b128 v[188:191], v156 offset:17408
	ds_read_b128 v[192:195], v156 offset:18432
	ds_read_b128 v[196:199], v156 offset:19456
	ds_read_b128 v[200:203], v156 offset:20480
	ds_read_b128 v[206:209], v156 offset:21504
	ds_read_b128 v[210:213], v156 offset:22528
	ds_read_b128 v[214:217], v156 offset:23552
	global_load_lds_dwordx4 v[148:149], off
	s_add_i32 m0, s58, 0x2000
	s_add_u32 s58, s28, 0x60000
	v_lshl_add_u64 v[174:175], s[28:29], 0, v[128:129]
	s_addc_u32 s59, s29, 0
	s_add_i32 s60, s45, s36
	global_load_lds_dwordx4 v[174:175], off
	v_lshl_add_u64 v[218:219], s[58:59], 0, v[130:131]
	s_mov_b32 m0, s60
	v_lshl_add_u64 v[220:221], s[30:31], 0, v[128:129]
	global_load_lds_dwordx4 v[218:219], off
	v_lshl_add_u64 v[218:219], s[58:59], 0, v[128:129]
	s_add_i32 m0, s60, 0x2000
	s_nop 0
	global_load_lds_dwordx4 v[218:219], off
	v_lshl_add_u64 v[218:219], s[30:31], 0, v[130:131]
	s_mov_b32 m0, s37
	s_nop 0
	global_load_lds_dwordx4 v[218:219], off
	s_mov_b32 m0, s38
	s_nop 0
	global_load_lds_dwordx4 v[220:221], off
	s_waitcnt vmcnt(8)
	s_waitcnt lgkmcnt(0)
	s_barrier
	s_setprio 1
	s_waitcnt lgkmcnt(0)
	v_mfma_f32_16x16x32_bf16 v[60:63], v[136:139], v[184:187], v[60:63]
	v_mfma_f32_16x16x32_bf16 v[56:59], v[144:147], v[184:187], v[56:59]
	v_mfma_f32_16x16x32_bf16 v[48:51], v[136:139], v[192:195], v[48:51]
	v_mfma_f32_16x16x32_bf16 v[40:43], v[144:147], v[192:195], v[40:43]
	v_mfma_f32_16x16x32_bf16 v[32:35], v[136:139], v[200:203], v[32:35]
	v_mfma_f32_16x16x32_bf16 v[24:27], v[144:147], v[200:203], v[24:27]
	v_mfma_f32_16x16x32_bf16 v[16:19], v[136:139], v[210:213], v[16:19]
	v_mfma_f32_16x16x32_bf16 v[8:11], v[144:147], v[210:213], v[8:11]
	v_mfma_f32_16x16x32_bf16 v[60:63], v[140:143], v[188:191], v[60:63]
	v_mfma_f32_16x16x32_bf16 v[56:59], v[158:161], v[188:191], v[56:59]
	v_mfma_f32_16x16x32_bf16 v[48:51], v[140:143], v[196:199], v[48:51]
	v_mfma_f32_16x16x32_bf16 v[40:43], v[158:161], v[196:199], v[40:43]
	v_mfma_f32_16x16x32_bf16 v[32:35], v[140:143], v[206:209], v[32:35]
	v_mfma_f32_16x16x32_bf16 v[24:27], v[158:161], v[206:209], v[24:27]
	v_mfma_f32_16x16x32_bf16 v[16:19], v[140:143], v[214:217], v[16:19]
	v_mfma_f32_16x16x32_bf16 v[8:11], v[158:161], v[214:217], v[8:11]
	s_setprio 0
	s_setprio 1
	v_mfma_f32_16x16x32_bf16 v[52:55], v[162:165], v[184:187], v[52:55]
	v_mfma_f32_16x16x32_bf16 v[44:47], v[170:173], v[184:187], v[44:47]
	v_mfma_f32_16x16x32_bf16 v[36:39], v[162:165], v[192:195], v[36:39]
	v_mfma_f32_16x16x32_bf16 v[28:31], v[170:173], v[192:195], v[28:31]
	v_mfma_f32_16x16x32_bf16 v[20:23], v[162:165], v[200:203], v[20:23]
	v_mfma_f32_16x16x32_bf16 v[12:15], v[170:173], v[200:203], v[12:15]
	v_mfma_f32_16x16x32_bf16 v[4:7], v[162:165], v[210:213], v[4:7]
	v_mfma_f32_16x16x32_bf16 v[0:3], v[170:173], v[210:213], v[0:3]
	v_mfma_f32_16x16x32_bf16 v[52:55], v[166:169], v[188:191], v[52:55]
	v_mfma_f32_16x16x32_bf16 v[44:47], v[180:183], v[188:191], v[44:47]
	v_mfma_f32_16x16x32_bf16 v[36:39], v[166:169], v[196:199], v[36:39]
	v_mfma_f32_16x16x32_bf16 v[28:31], v[180:183], v[196:199], v[28:31]
	v_mfma_f32_16x16x32_bf16 v[20:23], v[166:169], v[206:209], v[20:23]
	v_mfma_f32_16x16x32_bf16 v[12:15], v[180:183], v[206:209], v[12:15]
	v_mfma_f32_16x16x32_bf16 v[4:7], v[166:169], v[214:217], v[4:7]
	v_mfma_f32_16x16x32_bf16 v[0:3], v[180:183], v[214:217], v[0:3]
	s_setprio 0
	s_barrier
	s_add_i32 s58, 0, 0x18000
	v_add_u32_e32 v157, s58, v152
	s_add_i32 s59, 0, 0x1c000
	ds_read_b128 v[136:139], v157
	ds_read_b128 v[140:143], v157 offset:1024
	ds_read_b128 v[144:147], v157 offset:2048
	ds_read_b128 v[158:161], v157 offset:3072
	v_add_u32_e32 v157, s59, v152
	ds_read_b128 v[162:165], v157
	ds_read_b128 v[166:169], v157 offset:1024
	ds_read_b128 v[170:173], v157 offset:2048
	ds_read_b128 v[180:183], v157 offset:3072
	s_add_u32 s30, s30, 0x60000
	s_addc_u32 s31, s31, 0
	s_mov_b32 m0, s39
	v_lshl_add_u64 v[222:223], s[30:31], 0, v[130:131]
	ds_read_b128 v[184:187], v156 offset:32768
	ds_read_b128 v[188:191], v156 offset:33792
	ds_read_b128 v[192:195], v156 offset:34816
	ds_read_b128 v[196:199], v156 offset:35840
	ds_read_b128 v[200:203], v156 offset:36864
	ds_read_b128 v[206:209], v156 offset:37888
	ds_read_b128 v[210:213], v156 offset:38912
	ds_read_b128 v[214:217], v156 offset:39936
	global_load_lds_dwordx4 v[222:223], off
	v_lshl_add_u64 v[222:223], s[30:31], 0, v[128:129]
	s_mov_b32 m0, s40
	s_nop 0
	global_load_lds_dwordx4 v[222:223], off
	s_waitcnt vmcnt(8)
	s_waitcnt lgkmcnt(0)
	s_barrier
	s_setprio 1
	s_waitcnt lgkmcnt(0)
	v_mfma_f32_16x16x32_bf16 v[124:127], v[136:139], v[184:187], v[124:127]
	v_mfma_f32_16x16x32_bf16 v[120:123], v[144:147], v[184:187], v[120:123]
	v_mfma_f32_16x16x32_bf16 v[112:115], v[136:139], v[192:195], v[112:115]
	v_mfma_f32_16x16x32_bf16 v[104:107], v[144:147], v[192:195], v[104:107]
	v_mfma_f32_16x16x32_bf16 v[96:99], v[136:139], v[200:203], v[96:99]
	v_mfma_f32_16x16x32_bf16 v[88:91], v[144:147], v[200:203], v[88:91]
	v_mfma_f32_16x16x32_bf16 v[80:83], v[136:139], v[210:213], v[80:83]
	v_mfma_f32_16x16x32_bf16 v[72:75], v[144:147], v[210:213], v[72:75]
	v_mfma_f32_16x16x32_bf16 v[124:127], v[140:143], v[188:191], v[124:127]
	v_mfma_f32_16x16x32_bf16 v[120:123], v[158:161], v[188:191], v[120:123]
	v_mfma_f32_16x16x32_bf16 v[112:115], v[140:143], v[196:199], v[112:115]
	v_mfma_f32_16x16x32_bf16 v[104:107], v[158:161], v[196:199], v[104:107]
	v_mfma_f32_16x16x32_bf16 v[96:99], v[140:143], v[206:209], v[96:99]
	v_mfma_f32_16x16x32_bf16 v[88:91], v[158:161], v[206:209], v[88:91]
	v_mfma_f32_16x16x32_bf16 v[80:83], v[140:143], v[214:217], v[80:83]
	v_mfma_f32_16x16x32_bf16 v[72:75], v[158:161], v[214:217], v[72:75]
	s_setprio 0
	s_setprio 1
	v_mfma_f32_16x16x32_bf16 v[116:119], v[162:165], v[184:187], v[116:119]
	v_mfma_f32_16x16x32_bf16 v[108:111], v[170:173], v[184:187], v[108:111]
	v_mfma_f32_16x16x32_bf16 v[100:103], v[162:165], v[192:195], v[100:103]
	v_mfma_f32_16x16x32_bf16 v[92:95], v[170:173], v[192:195], v[92:95]
	v_mfma_f32_16x16x32_bf16 v[84:87], v[162:165], v[200:203], v[84:87]
	v_mfma_f32_16x16x32_bf16 v[76:79], v[170:173], v[200:203], v[76:79]
	v_mfma_f32_16x16x32_bf16 v[68:71], v[162:165], v[210:213], v[68:71]
	v_mfma_f32_16x16x32_bf16 v[64:67], v[170:173], v[210:213], v[64:67]
	v_mfma_f32_16x16x32_bf16 v[116:119], v[166:169], v[188:191], v[116:119]
	v_mfma_f32_16x16x32_bf16 v[108:111], v[180:183], v[188:191], v[108:111]
	v_mfma_f32_16x16x32_bf16 v[100:103], v[166:169], v[196:199], v[100:103]
	v_mfma_f32_16x16x32_bf16 v[92:95], v[180:183], v[196:199], v[92:95]
	v_mfma_f32_16x16x32_bf16 v[84:87], v[166:169], v[206:209], v[84:87]
	v_mfma_f32_16x16x32_bf16 v[76:79], v[180:183], v[206:209], v[76:79]
	v_mfma_f32_16x16x32_bf16 v[68:71], v[166:169], v[214:217], v[68:71]
	v_mfma_f32_16x16x32_bf16 v[64:67], v[180:183], v[214:217], v[64:67]
	s_setprio 0
	s_barrier
	s_add_i32 s30, s58, s36
	v_lshl_add_u64 v[148:149], v[148:149], 0, s[16:17]
	s_mov_b32 m0, s30
	ds_read_b128 v[184:187], v156 offset:49152
	ds_read_b128 v[188:191], v156 offset:50176
	ds_read_b128 v[192:195], v156 offset:51200
	ds_read_b128 v[196:199], v156 offset:52224
	ds_read_b128 v[200:203], v156 offset:53248
	ds_read_b128 v[206:209], v156 offset:54272
	ds_read_b128 v[210:213], v156 offset:55296
	ds_read_b128 v[214:217], v156 offset:56320
	global_load_lds_dwordx4 v[148:149], off
	s_add_i32 m0, s30, 0x2000
	s_add_u32 s28, s28, 0x60080
	v_lshl_add_u64 v[148:149], v[174:175], 0, s[16:17]
	s_addc_u32 s29, s29, 0
	s_add_i32 s30, s59, s36
	global_load_lds_dwordx4 v[148:149], off
	v_lshl_add_u64 v[148:149], s[28:29], 0, v[130:131]
	s_mov_b32 m0, s30
	s_nop 0
	global_load_lds_dwordx4 v[148:149], off
	v_lshl_add_u64 v[148:149], s[28:29], 0, v[128:129]
	s_add_i32 m0, s30, 0x2000
	s_nop 0
	global_load_lds_dwordx4 v[148:149], off
	v_lshl_add_u64 v[148:149], v[218:219], 0, s[16:17]
	s_mov_b32 m0, s41
	s_nop 0
	global_load_lds_dwordx4 v[148:149], off
	v_lshl_add_u64 v[148:149], v[220:221], 0, s[16:17]
	s_mov_b32 m0, s42
	s_nop 0
	global_load_lds_dwordx4 v[148:149], off
	s_waitcnt vmcnt(8)
	s_waitcnt lgkmcnt(0)
	s_barrier
	s_setprio 1
	s_waitcnt lgkmcnt(0)
	v_mfma_f32_16x16x32_bf16 v[60:63], v[136:139], v[184:187], v[60:63]
	v_mfma_f32_16x16x32_bf16 v[56:59], v[144:147], v[184:187], v[56:59]
	v_mfma_f32_16x16x32_bf16 v[48:51], v[136:139], v[192:195], v[48:51]
	v_mfma_f32_16x16x32_bf16 v[40:43], v[144:147], v[192:195], v[40:43]
	v_mfma_f32_16x16x32_bf16 v[32:35], v[136:139], v[200:203], v[32:35]
	v_mfma_f32_16x16x32_bf16 v[24:27], v[144:147], v[200:203], v[24:27]
	v_mfma_f32_16x16x32_bf16 v[16:19], v[136:139], v[210:213], v[16:19]
	v_mfma_f32_16x16x32_bf16 v[8:11], v[144:147], v[210:213], v[8:11]
	v_mfma_f32_16x16x32_bf16 v[60:63], v[140:143], v[188:191], v[60:63]
	v_mfma_f32_16x16x32_bf16 v[56:59], v[158:161], v[188:191], v[56:59]
	v_mfma_f32_16x16x32_bf16 v[48:51], v[140:143], v[196:199], v[48:51]
	v_mfma_f32_16x16x32_bf16 v[40:43], v[158:161], v[196:199], v[40:43]
	v_mfma_f32_16x16x32_bf16 v[32:35], v[140:143], v[206:209], v[32:35]
	v_mfma_f32_16x16x32_bf16 v[24:27], v[158:161], v[206:209], v[24:27]
	v_mfma_f32_16x16x32_bf16 v[16:19], v[140:143], v[214:217], v[16:19]
	v_mfma_f32_16x16x32_bf16 v[8:11], v[158:161], v[214:217], v[8:11]
	s_setprio 0
	s_setprio 1
	v_mfma_f32_16x16x32_bf16 v[52:55], v[162:165], v[184:187], v[52:55]
	v_mfma_f32_16x16x32_bf16 v[44:47], v[170:173], v[184:187], v[44:47]
	v_mfma_f32_16x16x32_bf16 v[36:39], v[162:165], v[192:195], v[36:39]
	v_mfma_f32_16x16x32_bf16 v[28:31], v[170:173], v[192:195], v[28:31]
	v_mfma_f32_16x16x32_bf16 v[20:23], v[162:165], v[200:203], v[20:23]
	v_mfma_f32_16x16x32_bf16 v[12:15], v[170:173], v[200:203], v[12:15]
	v_mfma_f32_16x16x32_bf16 v[4:7], v[162:165], v[210:213], v[4:7]
	v_mfma_f32_16x16x32_bf16 v[0:3], v[170:173], v[210:213], v[0:3]
	v_mfma_f32_16x16x32_bf16 v[52:55], v[166:169], v[188:191], v[52:55]
	v_mfma_f32_16x16x32_bf16 v[44:47], v[180:183], v[188:191], v[44:47]
	v_mfma_f32_16x16x32_bf16 v[36:39], v[166:169], v[196:199], v[36:39]
	v_mfma_f32_16x16x32_bf16 v[28:31], v[180:183], v[196:199], v[28:31]
	v_mfma_f32_16x16x32_bf16 v[20:23], v[166:169], v[206:209], v[20:23]
	v_mfma_f32_16x16x32_bf16 v[12:15], v[180:183], v[206:209], v[12:15]
	v_mfma_f32_16x16x32_bf16 v[4:7], v[166:169], v[214:217], v[4:7]
	v_mfma_f32_16x16x32_bf16 v[0:3], v[180:183], v[214:217], v[0:3]
	s_add_i32 s57, s57, 2
	s_add_u32 s26, s26, 0x100
	s_addc_u32 s27, s27, 0
	s_add_u32 s55, s55, 0x100
	s_addc_u32 s56, s56, 0
	s_cmp_gt_u32 s57, 5
	s_setprio 0
	s_barrier
	s_cbranch_scc0 .LBB0_913
	s_and_b64 vcc, exec, s[18:19]
	s_cbranch_vccz .LBB0_916
	s_barrier

.Llsb_skip_8:
.LBB0_1088:
	ds_read_b128 v[128:131], v212
	ds_read_b128 v[132:135], v212 offset:1024
	ds_read_b128 v[136:139], v212 offset:2048
	ds_read_b128 v[140:143], v212 offset:3072
	ds_read_b128 v[144:147], v213
	ds_read_b128 v[148:151], v213 offset:1024
	ds_read_b128 v[152:155], v213 offset:2048
	ds_read_b128 v[156:159], v213 offset:3072
	s_add_u32 s22, s20, 0xfffc0080
	s_addc_u32 s23, s21, -1
	s_cmp_eq_u32 s54, 12
	s_cselect_b32 s25, s13, s23
	s_cselect_b32 s24, s50, s22
	s_cselect_b32 s23, s11, s53
	s_cselect_b32 s22, s51, s52
	v_lshl_add_u64 v[202:203], s[20:21], 0, v[182:183]
	s_add_i32 m0, s28, 0xc000
	ds_read_b128 v[160:163], v214
	ds_read_b128 v[164:167], v214 offset:1024
	ds_read_b128 v[168:171], v214 offset:2048
	ds_read_b128 v[172:175], v214 offset:3072
	ds_read_b128 v[190:193], v214 offset:4096
	ds_read_b128 v[194:197], v214 offset:5120
	ds_read_b128 v[198:201], v214 offset:6144
	ds_read_b128 v[216:219], v214 offset:7168
	global_load_lds_dwordx4 v[202:203], off
	v_lshl_add_u64 v[202:203], s[20:21], 0, v[184:185]
	s_add_i32 m0, s28, 0xe000
	s_nop 0
	global_load_lds_dwordx4 v[202:203], off
	s_waitcnt vmcnt(8)
	s_waitcnt lgkmcnt(0)
	s_barrier
	s_setprio 1
	s_waitcnt lgkmcnt(0)
	v_mfma_f32_16x16x32_bf16 v[124:127], v[128:131], v[160:163], v[124:127]
	v_mfma_f32_16x16x32_bf16 v[120:123], v[136:139], v[160:163], v[120:123]
	v_mfma_f32_16x16x32_bf16 v[112:115], v[128:131], v[168:171], v[112:115]
	v_mfma_f32_16x16x32_bf16 v[104:107], v[136:139], v[168:171], v[104:107]
	v_mfma_f32_16x16x32_bf16 v[96:99], v[128:131], v[190:193], v[96:99]
	v_mfma_f32_16x16x32_bf16 v[88:91], v[136:139], v[190:193], v[88:91]
	v_mfma_f32_16x16x32_bf16 v[84:87], v[128:131], v[198:201], v[84:87]
	v_mfma_f32_16x16x32_bf16 v[76:79], v[136:139], v[198:201], v[76:79]
	v_mfma_f32_16x16x32_bf16 v[124:127], v[132:135], v[164:167], v[124:127]
	v_mfma_f32_16x16x32_bf16 v[120:123], v[140:143], v[164:167], v[120:123]
	v_mfma_f32_16x16x32_bf16 v[112:115], v[132:135], v[172:175], v[112:115]
	v_mfma_f32_16x16x32_bf16 v[104:107], v[140:143], v[172:175], v[104:107]
	v_mfma_f32_16x16x32_bf16 v[96:99], v[132:135], v[194:197], v[96:99]
	v_mfma_f32_16x16x32_bf16 v[88:91], v[140:143], v[194:197], v[88:91]
	v_mfma_f32_16x16x32_bf16 v[84:87], v[132:135], v[216:219], v[84:87]
	v_mfma_f32_16x16x32_bf16 v[76:79], v[140:143], v[216:219], v[76:79]
	s_setprio 0
	s_setprio 1
	v_mfma_f32_16x16x32_bf16 v[116:119], v[144:147], v[160:163], v[116:119]
	v_mfma_f32_16x16x32_bf16 v[108:111], v[152:155], v[160:163], v[108:111]
	v_mfma_f32_16x16x32_bf16 v[100:103], v[144:147], v[168:171], v[100:103]
	v_mfma_f32_16x16x32_bf16 v[92:95], v[152:155], v[168:171], v[92:95]
	v_mfma_f32_16x16x32_bf16 v[80:83], v[144:147], v[190:193], v[80:83]
	v_mfma_f32_16x16x32_bf16 v[72:75], v[152:155], v[190:193], v[72:75]
	v_mfma_f32_16x16x32_bf16 v[68:71], v[144:147], v[198:201], v[68:71]
	v_mfma_f32_16x16x32_bf16 v[64:67], v[152:155], v[198:201], v[64:67]
	v_mfma_f32_16x16x32_bf16 v[116:119], v[148:151], v[164:167], v[116:119]
	v_mfma_f32_16x16x32_bf16 v[108:111], v[156:159], v[164:167], v[108:111]
	v_mfma_f32_16x16x32_bf16 v[100:103], v[148:151], v[172:175], v[100:103]
	v_mfma_f32_16x16x32_bf16 v[92:95], v[156:159], v[172:175], v[92:95]
	v_mfma_f32_16x16x32_bf16 v[80:83], v[148:151], v[194:197], v[80:83]
	v_mfma_f32_16x16x32_bf16 v[72:75], v[156:159], v[194:197], v[72:75]
	v_mfma_f32_16x16x32_bf16 v[68:71], v[148:151], v[216:219], v[68:71]
	v_mfma_f32_16x16x32_bf16 v[64:67], v[156:159], v[216:219], v[64:67]
	s_setprio 0
	s_barrier
	s_add_i32 s55, s43, s27
	v_lshl_add_u64 v[202:203], s[22:23], 0, v[176:177]
	s_mov_b32 m0, s55
	ds_read_b128 v[160:163], v214 offset:16384
	ds_read_b128 v[164:167], v214 offset:17408
	ds_read_b128 v[168:171], v214 offset:18432
	ds_read_b128 v[172:175], v214 offset:19456
	ds_read_b128 v[190:193], v214 offset:20480
	ds_read_b128 v[194:197], v214 offset:21504
	ds_read_b128 v[198:201], v214 offset:22528
	ds_read_b128 v[216:219], v214 offset:23552
	global_load_lds_dwordx4 v[202:203], off
	s_add_i32 m0, s55, 0x2000
	s_add_u32 s56, s22, 0x40000
	v_lshl_add_u64 v[220:221], s[22:23], 0, v[178:179]
	s_addc_u32 s57, s23, 0
	s_add_i32 s55, s44, s27
	global_load_lds_dwordx4 v[220:221], off
	v_lshl_add_u64 v[222:223], s[56:57], 0, v[176:177]
	s_mov_b32 m0, s55
	v_lshl_add_u64 v[224:225], s[24:25], 0, v[178:179]
	global_load_lds_dwordx4 v[222:223], off
	v_lshl_add_u64 v[222:223], s[56:57], 0, v[178:179]
	s_add_i32 m0, s55, 0x2000
	s_nop 0
	global_load_lds_dwordx4 v[222:223], off
	v_lshl_add_u64 v[222:223], s[24:25], 0, v[176:177]
	s_mov_b32 m0, s28
	s_nop 0
	global_load_lds_dwordx4 v[222:223], off
	s_mov_b32 m0, s29
	s_nop 0
	global_load_lds_dwordx4 v[224:225], off
	s_waitcnt vmcnt(8)
	s_waitcnt lgkmcnt(0)
	s_barrier
	s_setprio 1
	s_waitcnt lgkmcnt(0)
	v_mfma_f32_16x16x32_bf16 v[60:63], v[128:131], v[160:163], v[60:63]
	v_mfma_f32_16x16x32_bf16 v[56:59], v[136:139], v[160:163], v[56:59]
	v_mfma_f32_16x16x32_bf16 v[48:51], v[128:131], v[168:171], v[48:51]
	v_mfma_f32_16x16x32_bf16 v[40:43], v[136:139], v[168:171], v[40:43]
	v_mfma_f32_16x16x32_bf16 v[32:35], v[128:131], v[190:193], v[32:35]
	v_mfma_f32_16x16x32_bf16 v[24:27], v[136:139], v[190:193], v[24:27]
	v_mfma_f32_16x16x32_bf16 v[20:23], v[128:131], v[198:201], v[20:23]
	v_mfma_f32_16x16x32_bf16 v[12:15], v[136:139], v[198:201], v[12:15]
	v_mfma_f32_16x16x32_bf16 v[60:63], v[132:135], v[164:167], v[60:63]
	v_mfma_f32_16x16x32_bf16 v[56:59], v[140:143], v[164:167], v[56:59]
	v_mfma_f32_16x16x32_bf16 v[48:51], v[132:135], v[172:175], v[48:51]
	v_mfma_f32_16x16x32_bf16 v[40:43], v[140:143], v[172:175], v[40:43]
	v_mfma_f32_16x16x32_bf16 v[32:35], v[132:135], v[194:197], v[32:35]
	v_mfma_f32_16x16x32_bf16 v[24:27], v[140:143], v[194:197], v[24:27]
	v_mfma_f32_16x16x32_bf16 v[20:23], v[132:135], v[216:219], v[20:23]
	v_mfma_f32_16x16x32_bf16 v[12:15], v[140:143], v[216:219], v[12:15]
	s_setprio 0
	s_setprio 1
	v_mfma_f32_16x16x32_bf16 v[52:55], v[144:147], v[160:163], v[52:55]
	v_mfma_f32_16x16x32_bf16 v[44:47], v[152:155], v[160:163], v[44:47]
	v_mfma_f32_16x16x32_bf16 v[36:39], v[144:147], v[168:171], v[36:39]
	v_mfma_f32_16x16x32_bf16 v[28:31], v[152:155], v[168:171], v[28:31]
	v_mfma_f32_16x16x32_bf16 v[16:19], v[144:147], v[190:193], v[16:19]
	v_mfma_f32_16x16x32_bf16 v[8:11], v[152:155], v[190:193], v[8:11]
	v_mfma_f32_16x16x32_bf16 v[4:7], v[144:147], v[198:201], v[4:7]
	v_mfma_f32_16x16x32_bf16 v[0:3], v[152:155], v[198:201], v[0:3]
	v_mfma_f32_16x16x32_bf16 v[52:55], v[148:151], v[164:167], v[52:55]
	v_mfma_f32_16x16x32_bf16 v[44:47], v[156:159], v[164:167], v[44:47]
	v_mfma_f32_16x16x32_bf16 v[36:39], v[148:151], v[172:175], v[36:39]
	v_mfma_f32_16x16x32_bf16 v[28:31], v[156:159], v[172:175], v[28:31]
	v_mfma_f32_16x16x32_bf16 v[16:19], v[148:151], v[194:197], v[16:19]
	v_mfma_f32_16x16x32_bf16 v[8:11], v[156:159], v[194:197], v[8:11]
	v_mfma_f32_16x16x32_bf16 v[4:7], v[148:151], v[216:219], v[4:7]
	v_mfma_f32_16x16x32_bf16 v[0:3], v[156:159], v[216:219], v[0:3]
	s_setprio 0
	s_barrier
	s_add_i32 s55, 0, 0x18000
	s_add_i32 s56, 0, 0x1c000
	v_add_u32_e32 v140, s55, v210
	v_add_u32_e32 v156, s56, v210
	ds_read_b128 v[128:131], v140
	ds_read_b128 v[132:135], v140 offset:1024
	ds_read_b128 v[136:139], v140 offset:2048
	ds_read_b128 v[140:143], v140 offset:3072
	ds_read_b128 v[144:147], v156
	ds_read_b128 v[148:151], v156 offset:1024
	ds_read_b128 v[152:155], v156 offset:2048
	ds_read_b128 v[156:159], v156 offset:3072
	s_add_u32 s24, s24, 0x40000
	s_addc_u32 s25, s25, 0
	s_mov_b32 m0, s30
	v_lshl_add_u64 v[226:227], s[24:25], 0, v[176:177]
	ds_read_b128 v[160:163], v214 offset:32768
	ds_read_b128 v[164:167], v214 offset:33792
	ds_read_b128 v[168:171], v214 offset:34816
	ds_read_b128 v[172:175], v214 offset:35840
	ds_read_b128 v[190:193], v214 offset:36864
	ds_read_b128 v[194:197], v214 offset:37888
	ds_read_b128 v[198:201], v214 offset:38912
	ds_read_b128 v[216:219], v214 offset:39936
	global_load_lds_dwordx4 v[226:227], off
	v_lshl_add_u64 v[226:227], s[24:25], 0, v[178:179]
	s_mov_b32 m0, s31
	s_nop 0
	global_load_lds_dwordx4 v[226:227], off
	s_waitcnt vmcnt(8)
	s_waitcnt lgkmcnt(0)
	s_barrier
	s_setprio 1
	s_waitcnt lgkmcnt(0)
	v_mfma_f32_16x16x32_bf16 v[124:127], v[128:131], v[160:163], v[124:127]
	v_mfma_f32_16x16x32_bf16 v[120:123], v[136:139], v[160:163], v[120:123]
	v_mfma_f32_16x16x32_bf16 v[112:115], v[128:131], v[168:171], v[112:115]
	v_mfma_f32_16x16x32_bf16 v[104:107], v[136:139], v[168:171], v[104:107]
	v_mfma_f32_16x16x32_bf16 v[96:99], v[128:131], v[190:193], v[96:99]
	v_mfma_f32_16x16x32_bf16 v[88:91], v[136:139], v[190:193], v[88:91]
	v_mfma_f32_16x16x32_bf16 v[84:87], v[128:131], v[198:201], v[84:87]
	v_mfma_f32_16x16x32_bf16 v[76:79], v[136:139], v[198:201], v[76:79]
	v_mfma_f32_16x16x32_bf16 v[124:127], v[132:135], v[164:167], v[124:127]
	v_mfma_f32_16x16x32_bf16 v[120:123], v[140:143], v[164:167], v[120:123]
	v_mfma_f32_16x16x32_bf16 v[112:115], v[132:135], v[172:175], v[112:115]
	v_mfma_f32_16x16x32_bf16 v[104:107], v[140:143], v[172:175], v[104:107]
	v_mfma_f32_16x16x32_bf16 v[96:99], v[132:135], v[194:197], v[96:99]
	v_mfma_f32_16x16x32_bf16 v[88:91], v[140:143], v[194:197], v[88:91]
	v_mfma_f32_16x16x32_bf16 v[84:87], v[132:135], v[216:219], v[84:87]
	v_mfma_f32_16x16x32_bf16 v[76:79], v[140:143], v[216:219], v[76:79]
	s_setprio 0
	s_setprio 1
	v_mfma_f32_16x16x32_bf16 v[116:119], v[144:147], v[160:163], v[116:119]
	v_mfma_f32_16x16x32_bf16 v[108:111], v[152:155], v[160:163], v[108:111]
	v_mfma_f32_16x16x32_bf16 v[100:103], v[144:147], v[168:171], v[100:103]
	v_mfma_f32_16x16x32_bf16 v[92:95], v[152:155], v[168:171], v[92:95]
	v_mfma_f32_16x16x32_bf16 v[80:83], v[144:147], v[190:193], v[80:83]
	v_mfma_f32_16x16x32_bf16 v[72:75], v[152:155], v[190:193], v[72:75]
	v_mfma_f32_16x16x32_bf16 v[68:71], v[144:147], v[198:201], v[68:71]
	v_mfma_f32_16x16x32_bf16 v[64:67], v[152:155], v[198:201], v[64:67]
	v_mfma_f32_16x16x32_bf16 v[116:119], v[148:151], v[164:167], v[116:119]
	v_mfma_f32_16x16x32_bf16 v[108:111], v[156:159], v[164:167], v[108:111]
	v_mfma_f32_16x16x32_bf16 v[100:103], v[148:151], v[172:175], v[100:103]
	v_mfma_f32_16x16x32_bf16 v[92:95], v[156:159], v[172:175], v[92:95]
	v_mfma_f32_16x16x32_bf16 v[80:83], v[148:151], v[194:197], v[80:83]
	v_mfma_f32_16x16x32_bf16 v[72:75], v[156:159], v[194:197], v[72:75]
	v_mfma_f32_16x16x32_bf16 v[68:71], v[148:151], v[216:219], v[68:71]
	v_mfma_f32_16x16x32_bf16 v[64:67], v[156:159], v[216:219], v[64:67]
	s_setprio 0
	s_barrier
	s_add_i32 s24, s55, s27
	v_lshl_add_u64 v[202:203], v[202:203], 0, s[6:7]
	s_mov_b32 m0, s24
	ds_read_b128 v[160:163], v214 offset:49152
	ds_read_b128 v[164:167], v214 offset:50176
	ds_read_b128 v[168:171], v214 offset:51200
	ds_read_b128 v[172:175], v214 offset:52224
	ds_read_b128 v[190:193], v214 offset:53248
	ds_read_b128 v[194:197], v214 offset:54272
	ds_read_b128 v[198:201], v214 offset:55296
	ds_read_b128 v[216:219], v214 offset:56320
	global_load_lds_dwordx4 v[202:203], off
	s_add_i32 m0, s24, 0x2000
	s_add_u32 s22, s22, 0x40080
	v_lshl_add_u64 v[202:203], v[220:221], 0, s[6:7]
	s_addc_u32 s23, s23, 0
	s_add_i32 s24, s56, s27
	global_load_lds_dwordx4 v[202:203], off
	v_lshl_add_u64 v[202:203], s[22:23], 0, v[176:177]
	s_mov_b32 m0, s24
	s_nop 0
	global_load_lds_dwordx4 v[202:203], off
	v_lshl_add_u64 v[202:203], s[22:23], 0, v[178:179]
	s_add_i32 m0, s24, 0x2000
	s_nop 0
	global_load_lds_dwordx4 v[202:203], off
	v_lshl_add_u64 v[202:203], v[222:223], 0, s[6:7]
	s_mov_b32 m0, s40
	s_nop 0
	global_load_lds_dwordx4 v[202:203], off
	v_lshl_add_u64 v[202:203], v[224:225], 0, s[6:7]
	s_mov_b32 m0, s41
	s_nop 0
	global_load_lds_dwordx4 v[202:203], off
	s_waitcnt vmcnt(8)
	s_waitcnt lgkmcnt(0)
	s_barrier
	s_setprio 1
	s_waitcnt lgkmcnt(0)
	v_mfma_f32_16x16x32_bf16 v[60:63], v[128:131], v[160:163], v[60:63]
	v_mfma_f32_16x16x32_bf16 v[56:59], v[136:139], v[160:163], v[56:59]
	v_mfma_f32_16x16x32_bf16 v[48:51], v[128:131], v[168:171], v[48:51]
	v_mfma_f32_16x16x32_bf16 v[40:43], v[136:139], v[168:171], v[40:43]
	v_mfma_f32_16x16x32_bf16 v[32:35], v[128:131], v[190:193], v[32:35]
	v_mfma_f32_16x16x32_bf16 v[24:27], v[136:139], v[190:193], v[24:27]
	v_mfma_f32_16x16x32_bf16 v[20:23], v[128:131], v[198:201], v[20:23]
	v_mfma_f32_16x16x32_bf16 v[12:15], v[136:139], v[198:201], v[12:15]
	v_mfma_f32_16x16x32_bf16 v[60:63], v[132:135], v[164:167], v[60:63]
	v_mfma_f32_16x16x32_bf16 v[56:59], v[140:143], v[164:167], v[56:59]
	v_mfma_f32_16x16x32_bf16 v[48:51], v[132:135], v[172:175], v[48:51]
	v_mfma_f32_16x16x32_bf16 v[40:43], v[140:143], v[172:175], v[40:43]
	v_mfma_f32_16x16x32_bf16 v[32:35], v[132:135], v[194:197], v[32:35]
	v_mfma_f32_16x16x32_bf16 v[24:27], v[140:143], v[194:197], v[24:27]
	v_mfma_f32_16x16x32_bf16 v[20:23], v[132:135], v[216:219], v[20:23]
	v_mfma_f32_16x16x32_bf16 v[12:15], v[140:143], v[216:219], v[12:15]
	s_setprio 0
	s_setprio 1
	v_mfma_f32_16x16x32_bf16 v[52:55], v[144:147], v[160:163], v[52:55]
	v_mfma_f32_16x16x32_bf16 v[44:47], v[152:155], v[160:163], v[44:47]
	v_mfma_f32_16x16x32_bf16 v[36:39], v[144:147], v[168:171], v[36:39]
	v_mfma_f32_16x16x32_bf16 v[28:31], v[152:155], v[168:171], v[28:31]
	v_mfma_f32_16x16x32_bf16 v[16:19], v[144:147], v[190:193], v[16:19]
	v_mfma_f32_16x16x32_bf16 v[8:11], v[152:155], v[190:193], v[8:11]
	v_mfma_f32_16x16x32_bf16 v[4:7], v[144:147], v[198:201], v[4:7]
	v_mfma_f32_16x16x32_bf16 v[0:3], v[152:155], v[198:201], v[0:3]
	v_mfma_f32_16x16x32_bf16 v[52:55], v[148:151], v[164:167], v[52:55]
	v_mfma_f32_16x16x32_bf16 v[44:47], v[156:159], v[164:167], v[44:47]
	v_mfma_f32_16x16x32_bf16 v[36:39], v[148:151], v[172:175], v[36:39]
	v_mfma_f32_16x16x32_bf16 v[28:31], v[156:159], v[172:175], v[28:31]
	v_mfma_f32_16x16x32_bf16 v[16:19], v[148:151], v[194:197], v[16:19]
	v_mfma_f32_16x16x32_bf16 v[8:11], v[156:159], v[194:197], v[8:11]
	v_mfma_f32_16x16x32_bf16 v[4:7], v[148:151], v[216:219], v[4:7]
	v_mfma_f32_16x16x32_bf16 v[0:3], v[156:159], v[216:219], v[0:3]
	s_add_i32 s54, s54, 2
	s_add_u32 s20, s20, 0x100
	s_addc_u32 s21, s21, 0
	s_add_u32 s52, s52, 0x100
	s_addc_u32 s53, s53, 0
	s_cmp_gt_u32 s54, 13
	s_setprio 0
	s_barrier
	s_cbranch_scc0 .LBB0_1088
	s_and_b64 vcc, exec, s[8:9]
	s_cbranch_vccz .LBB0_1091
	s_barrier

.Llsb_skip_9:
.LBB0_1243:
	ds_read_b128 v[150:153], v147
	ds_read_b128 v[154:157], v147 offset:1024
	ds_read_b128 v[158:161], v147 offset:2048
	ds_read_b128 v[162:165], v147 offset:3072
	ds_read_b128 v[166:169], v148
	ds_read_b128 v[170:173], v148 offset:1024
	ds_read_b128 v[174:177], v148 offset:2048
	ds_read_b128 v[178:181], v148 offset:3072
	s_add_u32 s24, s22, 0xfffc0080
	s_addc_u32 s25, s23, -1
	s_cmp_eq_u32 s51, 12
	s_cselect_b32 s27, s15, s25
	s_cselect_b32 s26, s47, s24
	s_cselect_b32 s25, s13, s50
	s_cselect_b32 s24, s48, s49
	v_lshl_add_u64 v[202:203], s[22:23], 0, v[136:137]
	s_add_i32 m0, s21, 0xc000
	ds_read_b128 v[182:185], v149
	ds_read_b128 v[186:189], v149 offset:1024
	ds_read_b128 v[190:193], v149 offset:2048
	ds_read_b128 v[194:197], v149 offset:3072
	ds_read_b128 v[198:201], v149 offset:4096
	ds_read_b128 v[206:209], v149 offset:5120
	ds_read_b128 v[210:213], v149 offset:6144
	ds_read_b128 v[214:217], v149 offset:7168
	global_load_lds_dwordx4 v[202:203], off
	v_lshl_add_u64 v[202:203], s[22:23], 0, v[138:139]
	s_add_i32 m0, s21, 0xe000
	s_nop 0
	global_load_lds_dwordx4 v[202:203], off
	s_waitcnt vmcnt(8)
	s_waitcnt lgkmcnt(0)
	s_barrier
	s_setprio 1
	s_waitcnt lgkmcnt(0)
	v_mfma_f32_16x16x32_bf16 v[124:127], v[150:153], v[182:185], v[124:127]
	v_mfma_f32_16x16x32_bf16 v[120:123], v[158:161], v[182:185], v[120:123]
	v_mfma_f32_16x16x32_bf16 v[108:111], v[150:153], v[190:193], v[108:111]
	v_mfma_f32_16x16x32_bf16 v[104:107], v[158:161], v[190:193], v[104:107]
	v_mfma_f32_16x16x32_bf16 v[92:95], v[150:153], v[198:201], v[92:95]
	v_mfma_f32_16x16x32_bf16 v[88:91], v[158:161], v[198:201], v[88:91]
	v_mfma_f32_16x16x32_bf16 v[76:79], v[150:153], v[210:213], v[76:79]
	v_mfma_f32_16x16x32_bf16 v[72:75], v[158:161], v[210:213], v[72:75]
	v_mfma_f32_16x16x32_bf16 v[124:127], v[154:157], v[186:189], v[124:127]
	v_mfma_f32_16x16x32_bf16 v[120:123], v[162:165], v[186:189], v[120:123]
	v_mfma_f32_16x16x32_bf16 v[108:111], v[154:157], v[194:197], v[108:111]
	v_mfma_f32_16x16x32_bf16 v[104:107], v[162:165], v[194:197], v[104:107]
	v_mfma_f32_16x16x32_bf16 v[92:95], v[154:157], v[206:209], v[92:95]
	v_mfma_f32_16x16x32_bf16 v[88:91], v[162:165], v[206:209], v[88:91]
	v_mfma_f32_16x16x32_bf16 v[76:79], v[154:157], v[214:217], v[76:79]
	v_mfma_f32_16x16x32_bf16 v[72:75], v[162:165], v[214:217], v[72:75]
	s_setprio 0
	s_setprio 1
	v_mfma_f32_16x16x32_bf16 v[116:119], v[166:169], v[182:185], v[116:119]
	v_mfma_f32_16x16x32_bf16 v[112:115], v[174:177], v[182:185], v[112:115]
	v_mfma_f32_16x16x32_bf16 v[100:103], v[166:169], v[190:193], v[100:103]
	v_mfma_f32_16x16x32_bf16 v[96:99], v[174:177], v[190:193], v[96:99]
	v_mfma_f32_16x16x32_bf16 v[84:87], v[166:169], v[198:201], v[84:87]
	v_mfma_f32_16x16x32_bf16 v[80:83], v[174:177], v[198:201], v[80:83]
	v_mfma_f32_16x16x32_bf16 v[68:71], v[166:169], v[210:213], v[68:71]
	v_mfma_f32_16x16x32_bf16 v[64:67], v[174:177], v[210:213], v[64:67]
	v_mfma_f32_16x16x32_bf16 v[116:119], v[170:173], v[186:189], v[116:119]
	v_mfma_f32_16x16x32_bf16 v[112:115], v[178:181], v[186:189], v[112:115]
	v_mfma_f32_16x16x32_bf16 v[100:103], v[170:173], v[194:197], v[100:103]
	v_mfma_f32_16x16x32_bf16 v[96:99], v[178:181], v[194:197], v[96:99]
	v_mfma_f32_16x16x32_bf16 v[84:87], v[170:173], v[206:209], v[84:87]
	v_mfma_f32_16x16x32_bf16 v[80:83], v[178:181], v[206:209], v[80:83]
	v_mfma_f32_16x16x32_bf16 v[68:71], v[170:173], v[214:217], v[68:71]
	v_mfma_f32_16x16x32_bf16 v[64:67], v[178:181], v[214:217], v[64:67]
	s_setprio 0
	s_barrier
	s_add_i32 s52, s43, s34
	v_lshl_add_u64 v[202:203], s[24:25], 0, v[130:131]
	s_mov_b32 m0, s52
	ds_read_b128 v[182:185], v149 offset:16384
	ds_read_b128 v[186:189], v149 offset:17408
	ds_read_b128 v[190:193], v149 offset:18432
	ds_read_b128 v[194:197], v149 offset:19456
	ds_read_b128 v[198:201], v149 offset:20480
	ds_read_b128 v[206:209], v149 offset:21504
	ds_read_b128 v[210:213], v149 offset:22528
	ds_read_b128 v[214:217], v149 offset:23552
	global_load_lds_dwordx4 v[202:203], off
	s_add_i32 m0, s52, 0x2000
	s_add_u32 s52, s24, 0x40000
	v_lshl_add_u64 v[218:219], s[24:25], 0, v[134:135]
	s_addc_u32 s53, s25, 0
	s_add_i32 s54, s44, s34
	global_load_lds_dwordx4 v[218:219], off
	v_lshl_add_u64 v[220:221], s[52:53], 0, v[130:131]
	s_mov_b32 m0, s54
	v_lshl_add_u64 v[222:223], s[26:27], 0, v[132:133]
	global_load_lds_dwordx4 v[220:221], off
	v_lshl_add_u64 v[220:221], s[52:53], 0, v[134:135]
	s_add_i32 m0, s54, 0x2000
	s_nop 0
	global_load_lds_dwordx4 v[220:221], off
	v_lshl_add_u64 v[220:221], s[26:27], 0, v[128:129]
	s_mov_b32 m0, s21
	s_nop 0
	global_load_lds_dwordx4 v[220:221], off
	s_mov_b32 m0, s35
	s_nop 0
	global_load_lds_dwordx4 v[222:223], off
	s_waitcnt vmcnt(8)
	s_waitcnt lgkmcnt(0)
	s_barrier
	s_setprio 1
	s_waitcnt lgkmcnt(0)
	v_mfma_f32_16x16x32_bf16 v[60:63], v[150:153], v[182:185], v[60:63]
	v_mfma_f32_16x16x32_bf16 v[56:59], v[158:161], v[182:185], v[56:59]
	v_mfma_f32_16x16x32_bf16 v[44:47], v[150:153], v[190:193], v[44:47]
	v_mfma_f32_16x16x32_bf16 v[40:43], v[158:161], v[190:193], v[40:43]
	v_mfma_f32_16x16x32_bf16 v[28:31], v[150:153], v[198:201], v[28:31]
	v_mfma_f32_16x16x32_bf16 v[24:27], v[158:161], v[198:201], v[24:27]
	v_mfma_f32_16x16x32_bf16 v[12:15], v[150:153], v[210:213], v[12:15]
	v_mfma_f32_16x16x32_bf16 v[8:11], v[158:161], v[210:213], v[8:11]
	v_mfma_f32_16x16x32_bf16 v[60:63], v[154:157], v[186:189], v[60:63]
	v_mfma_f32_16x16x32_bf16 v[56:59], v[162:165], v[186:189], v[56:59]
	v_mfma_f32_16x16x32_bf16 v[44:47], v[154:157], v[194:197], v[44:47]
	v_mfma_f32_16x16x32_bf16 v[40:43], v[162:165], v[194:197], v[40:43]
	v_mfma_f32_16x16x32_bf16 v[28:31], v[154:157], v[206:209], v[28:31]
	v_mfma_f32_16x16x32_bf16 v[24:27], v[162:165], v[206:209], v[24:27]
	v_mfma_f32_16x16x32_bf16 v[12:15], v[154:157], v[214:217], v[12:15]
	v_mfma_f32_16x16x32_bf16 v[8:11], v[162:165], v[214:217], v[8:11]
	s_setprio 0
	s_setprio 1
	v_mfma_f32_16x16x32_bf16 v[52:55], v[166:169], v[182:185], v[52:55]
	v_mfma_f32_16x16x32_bf16 v[48:51], v[174:177], v[182:185], v[48:51]
	v_mfma_f32_16x16x32_bf16 v[36:39], v[166:169], v[190:193], v[36:39]
	v_mfma_f32_16x16x32_bf16 v[32:35], v[174:177], v[190:193], v[32:35]
	v_mfma_f32_16x16x32_bf16 v[20:23], v[166:169], v[198:201], v[20:23]
	v_mfma_f32_16x16x32_bf16 v[16:19], v[174:177], v[198:201], v[16:19]
	v_mfma_f32_16x16x32_bf16 v[4:7], v[166:169], v[210:213], v[4:7]
	v_mfma_f32_16x16x32_bf16 v[0:3], v[174:177], v[210:213], v[0:3]
	v_mfma_f32_16x16x32_bf16 v[52:55], v[170:173], v[186:189], v[52:55]
	v_mfma_f32_16x16x32_bf16 v[48:51], v[178:181], v[186:189], v[48:51]
	v_mfma_f32_16x16x32_bf16 v[36:39], v[170:173], v[194:197], v[36:39]
	v_mfma_f32_16x16x32_bf16 v[32:35], v[178:181], v[194:197], v[32:35]
	v_mfma_f32_16x16x32_bf16 v[20:23], v[170:173], v[206:209], v[20:23]
	v_mfma_f32_16x16x32_bf16 v[16:19], v[178:181], v[206:209], v[16:19]
	v_mfma_f32_16x16x32_bf16 v[4:7], v[170:173], v[214:217], v[4:7]
	v_mfma_f32_16x16x32_bf16 v[0:3], v[178:181], v[214:217], v[0:3]
	s_setprio 0
	s_barrier
	s_add_i32 s52, 0, 0x18000
	s_add_i32 s53, 0, 0x1c000
	v_add_u32_e32 v162, s52, v145
	v_add_u32_e32 v178, s53, v145
	ds_read_b128 v[150:153], v162
	ds_read_b128 v[154:157], v162 offset:1024
	ds_read_b128 v[158:161], v162 offset:2048
	ds_read_b128 v[162:165], v162 offset:3072
	ds_read_b128 v[166:169], v178
	ds_read_b128 v[170:173], v178 offset:1024
	ds_read_b128 v[174:177], v178 offset:2048
	ds_read_b128 v[178:181], v178 offset:3072
	s_add_u32 s26, s26, 0x40000
	s_addc_u32 s27, s27, 0
	s_mov_b32 m0, s36
	v_lshl_add_u64 v[224:225], s[26:27], 0, v[128:129]
	ds_read_b128 v[182:185], v149 offset:32768
	ds_read_b128 v[186:189], v149 offset:33792
	ds_read_b128 v[190:193], v149 offset:34816
	ds_read_b128 v[194:197], v149 offset:35840
	ds_read_b128 v[198:201], v149 offset:36864
	ds_read_b128 v[206:209], v149 offset:37888
	ds_read_b128 v[210:213], v149 offset:38912
	ds_read_b128 v[214:217], v149 offset:39936
	global_load_lds_dwordx4 v[224:225], off
	v_lshl_add_u64 v[224:225], s[26:27], 0, v[132:133]
	s_mov_b32 m0, s37
	s_nop 0
	global_load_lds_dwordx4 v[224:225], off
	s_waitcnt vmcnt(8)
	s_waitcnt lgkmcnt(0)
	s_barrier
	s_setprio 1
	s_waitcnt lgkmcnt(0)
	v_mfma_f32_16x16x32_bf16 v[124:127], v[150:153], v[182:185], v[124:127]
	v_mfma_f32_16x16x32_bf16 v[120:123], v[158:161], v[182:185], v[120:123]
	v_mfma_f32_16x16x32_bf16 v[108:111], v[150:153], v[190:193], v[108:111]
	v_mfma_f32_16x16x32_bf16 v[104:107], v[158:161], v[190:193], v[104:107]
	v_mfma_f32_16x16x32_bf16 v[92:95], v[150:153], v[198:201], v[92:95]
	v_mfma_f32_16x16x32_bf16 v[88:91], v[158:161], v[198:201], v[88:91]
	v_mfma_f32_16x16x32_bf16 v[76:79], v[150:153], v[210:213], v[76:79]
	v_mfma_f32_16x16x32_bf16 v[72:75], v[158:161], v[210:213], v[72:75]
	v_mfma_f32_16x16x32_bf16 v[124:127], v[154:157], v[186:189], v[124:127]
	v_mfma_f32_16x16x32_bf16 v[120:123], v[162:165], v[186:189], v[120:123]
	v_mfma_f32_16x16x32_bf16 v[108:111], v[154:157], v[194:197], v[108:111]
	v_mfma_f32_16x16x32_bf16 v[104:107], v[162:165], v[194:197], v[104:107]
	v_mfma_f32_16x16x32_bf16 v[92:95], v[154:157], v[206:209], v[92:95]
	v_mfma_f32_16x16x32_bf16 v[88:91], v[162:165], v[206:209], v[88:91]
	v_mfma_f32_16x16x32_bf16 v[76:79], v[154:157], v[214:217], v[76:79]
	v_mfma_f32_16x16x32_bf16 v[72:75], v[162:165], v[214:217], v[72:75]
	s_setprio 0
	s_setprio 1
	v_mfma_f32_16x16x32_bf16 v[116:119], v[166:169], v[182:185], v[116:119]
	v_mfma_f32_16x16x32_bf16 v[112:115], v[174:177], v[182:185], v[112:115]
	v_mfma_f32_16x16x32_bf16 v[100:103], v[166:169], v[190:193], v[100:103]
	v_mfma_f32_16x16x32_bf16 v[96:99], v[174:177], v[190:193], v[96:99]
	v_mfma_f32_16x16x32_bf16 v[84:87], v[166:169], v[198:201], v[84:87]
	v_mfma_f32_16x16x32_bf16 v[80:83], v[174:177], v[198:201], v[80:83]
	v_mfma_f32_16x16x32_bf16 v[68:71], v[166:169], v[210:213], v[68:71]
	v_mfma_f32_16x16x32_bf16 v[64:67], v[174:177], v[210:213], v[64:67]
	v_mfma_f32_16x16x32_bf16 v[116:119], v[170:173], v[186:189], v[116:119]
	v_mfma_f32_16x16x32_bf16 v[112:115], v[178:181], v[186:189], v[112:115]
	v_mfma_f32_16x16x32_bf16 v[100:103], v[170:173], v[194:197], v[100:103]
	v_mfma_f32_16x16x32_bf16 v[96:99], v[178:181], v[194:197], v[96:99]
	v_mfma_f32_16x16x32_bf16 v[84:87], v[170:173], v[206:209], v[84:87]
	v_mfma_f32_16x16x32_bf16 v[80:83], v[178:181], v[206:209], v[80:83]
	v_mfma_f32_16x16x32_bf16 v[68:71], v[170:173], v[214:217], v[68:71]
	v_mfma_f32_16x16x32_bf16 v[64:67], v[178:181], v[214:217], v[64:67]
	s_setprio 0
	s_barrier
	s_add_i32 s26, s52, s34
	v_lshl_add_u64 v[202:203], v[202:203], 0, s[8:9]
	s_mov_b32 m0, s26
	ds_read_b128 v[182:185], v149 offset:49152
	ds_read_b128 v[186:189], v149 offset:50176
	ds_read_b128 v[190:193], v149 offset:51200
	ds_read_b128 v[194:197], v149 offset:52224
	ds_read_b128 v[198:201], v149 offset:53248
	ds_read_b128 v[206:209], v149 offset:54272
	ds_read_b128 v[210:213], v149 offset:55296
	ds_read_b128 v[214:217], v149 offset:56320
	global_load_lds_dwordx4 v[202:203], off
	s_add_i32 m0, s26, 0x2000
	s_add_u32 s24, s24, 0x40080
	v_lshl_add_u64 v[202:203], v[218:219], 0, s[8:9]
	s_addc_u32 s25, s25, 0
	s_add_i32 s26, s53, s34
	global_load_lds_dwordx4 v[202:203], off
	v_lshl_add_u64 v[202:203], s[24:25], 0, v[130:131]
	s_mov_b32 m0, s26
	s_nop 0
	global_load_lds_dwordx4 v[202:203], off
	v_lshl_add_u64 v[202:203], s[24:25], 0, v[134:135]
	s_add_i32 m0, s26, 0x2000
	s_nop 0
	global_load_lds_dwordx4 v[202:203], off
	v_lshl_add_u64 v[202:203], v[220:221], 0, s[8:9]
	s_mov_b32 m0, s40
	s_nop 0
	global_load_lds_dwordx4 v[202:203], off
	v_lshl_add_u64 v[202:203], v[222:223], 0, s[8:9]
	s_mov_b32 m0, s41
	s_nop 0
	global_load_lds_dwordx4 v[202:203], off
	s_waitcnt vmcnt(8)
	s_waitcnt lgkmcnt(0)
	s_barrier
	s_setprio 1
	s_waitcnt lgkmcnt(0)
	v_mfma_f32_16x16x32_bf16 v[60:63], v[150:153], v[182:185], v[60:63]
	v_mfma_f32_16x16x32_bf16 v[56:59], v[158:161], v[182:185], v[56:59]
	v_mfma_f32_16x16x32_bf16 v[44:47], v[150:153], v[190:193], v[44:47]
	v_mfma_f32_16x16x32_bf16 v[40:43], v[158:161], v[190:193], v[40:43]
	v_mfma_f32_16x16x32_bf16 v[28:31], v[150:153], v[198:201], v[28:31]
	v_mfma_f32_16x16x32_bf16 v[24:27], v[158:161], v[198:201], v[24:27]
	v_mfma_f32_16x16x32_bf16 v[12:15], v[150:153], v[210:213], v[12:15]
	v_mfma_f32_16x16x32_bf16 v[8:11], v[158:161], v[210:213], v[8:11]
	v_mfma_f32_16x16x32_bf16 v[60:63], v[154:157], v[186:189], v[60:63]
	v_mfma_f32_16x16x32_bf16 v[56:59], v[162:165], v[186:189], v[56:59]
	v_mfma_f32_16x16x32_bf16 v[44:47], v[154:157], v[194:197], v[44:47]
	v_mfma_f32_16x16x32_bf16 v[40:43], v[162:165], v[194:197], v[40:43]
	v_mfma_f32_16x16x32_bf16 v[28:31], v[154:157], v[206:209], v[28:31]
	v_mfma_f32_16x16x32_bf16 v[24:27], v[162:165], v[206:209], v[24:27]
	v_mfma_f32_16x16x32_bf16 v[12:15], v[154:157], v[214:217], v[12:15]
	v_mfma_f32_16x16x32_bf16 v[8:11], v[162:165], v[214:217], v[8:11]
	s_setprio 0
	s_setprio 1
	v_mfma_f32_16x16x32_bf16 v[52:55], v[166:169], v[182:185], v[52:55]
	v_mfma_f32_16x16x32_bf16 v[48:51], v[174:177], v[182:185], v[48:51]
	v_mfma_f32_16x16x32_bf16 v[36:39], v[166:169], v[190:193], v[36:39]
	v_mfma_f32_16x16x32_bf16 v[32:35], v[174:177], v[190:193], v[32:35]
	v_mfma_f32_16x16x32_bf16 v[20:23], v[166:169], v[198:201], v[20:23]
	v_mfma_f32_16x16x32_bf16 v[16:19], v[174:177], v[198:201], v[16:19]
	v_mfma_f32_16x16x32_bf16 v[4:7], v[166:169], v[210:213], v[4:7]
	v_mfma_f32_16x16x32_bf16 v[0:3], v[174:177], v[210:213], v[0:3]
	v_mfma_f32_16x16x32_bf16 v[52:55], v[170:173], v[186:189], v[52:55]
	v_mfma_f32_16x16x32_bf16 v[48:51], v[178:181], v[186:189], v[48:51]
	v_mfma_f32_16x16x32_bf16 v[36:39], v[170:173], v[194:197], v[36:39]
	v_mfma_f32_16x16x32_bf16 v[32:35], v[178:181], v[194:197], v[32:35]
	v_mfma_f32_16x16x32_bf16 v[20:23], v[170:173], v[206:209], v[20:23]
	v_mfma_f32_16x16x32_bf16 v[16:19], v[178:181], v[206:209], v[16:19]
	v_mfma_f32_16x16x32_bf16 v[4:7], v[170:173], v[214:217], v[4:7]
	v_mfma_f32_16x16x32_bf16 v[0:3], v[178:181], v[214:217], v[0:3]
	s_add_i32 s51, s51, 2
	s_add_u32 s22, s22, 0x100
	s_addc_u32 s23, s23, 0
	s_add_u32 s49, s49, 0x100
	s_addc_u32 s50, s50, 0
	s_cmp_gt_u32 s51, 13
	s_setprio 0
	s_barrier
	s_cbranch_scc0 .LBB0_1243
	s_and_b64 vcc, exec, s[10:11]
	s_cbranch_vccz .LBB0_1246
	s_barrier

.Llsb_skip_10:
.LBB0_1324:
	ds_read_b128 v[128:131], v212
	ds_read_b128 v[132:135], v212 offset:1024
	ds_read_b128 v[136:139], v212 offset:2048
	ds_read_b128 v[140:143], v212 offset:3072
	ds_read_b128 v[144:147], v213
	ds_read_b128 v[148:151], v213 offset:1024
	ds_read_b128 v[152:155], v213 offset:2048
	ds_read_b128 v[156:159], v213 offset:3072
	s_add_u32 s18, s16, 0xfff50080
	s_addc_u32 s19, s17, -1
	s_cmp_eq_u32 s52, 40
	s_cselect_b32 s21, s5, s19
	s_cselect_b32 s20, s4, s18
	s_cselect_b32 s19, s15, s51
	s_cselect_b32 s18, s14, s50
	v_lshl_add_u64 v[202:203], s[16:17], 0, v[182:183]
	s_add_i32 m0, s23, 0xc000
	ds_read_b128 v[160:163], v214
	ds_read_b128 v[164:167], v214 offset:1024
	ds_read_b128 v[168:171], v214 offset:2048
	ds_read_b128 v[172:175], v214 offset:3072
	ds_read_b128 v[190:193], v214 offset:4096
	ds_read_b128 v[194:197], v214 offset:5120
	ds_read_b128 v[198:201], v214 offset:6144
	ds_read_b128 v[216:219], v214 offset:7168
	global_load_lds_dwordx4 v[202:203], off
	v_lshl_add_u64 v[202:203], s[16:17], 0, v[184:185]
	s_add_i32 m0, s23, 0xe000
	s_nop 0
	global_load_lds_dwordx4 v[202:203], off
	s_waitcnt vmcnt(8)
	s_waitcnt lgkmcnt(0)
	s_barrier
	s_setprio 1
	s_waitcnt lgkmcnt(0)
	v_mfma_f32_16x16x32_bf16 v[124:127], v[128:131], v[160:163], v[124:127]
	v_mfma_f32_16x16x32_bf16 v[120:123], v[136:139], v[160:163], v[120:123]
	v_mfma_f32_16x16x32_bf16 v[112:115], v[128:131], v[168:171], v[112:115]
	v_mfma_f32_16x16x32_bf16 v[104:107], v[136:139], v[168:171], v[104:107]
	v_mfma_f32_16x16x32_bf16 v[96:99], v[128:131], v[190:193], v[96:99]
	v_mfma_f32_16x16x32_bf16 v[88:91], v[136:139], v[190:193], v[88:91]
	v_mfma_f32_16x16x32_bf16 v[84:87], v[128:131], v[198:201], v[84:87]
	v_mfma_f32_16x16x32_bf16 v[76:79], v[136:139], v[198:201], v[76:79]
	v_mfma_f32_16x16x32_bf16 v[124:127], v[132:135], v[164:167], v[124:127]
	v_mfma_f32_16x16x32_bf16 v[120:123], v[140:143], v[164:167], v[120:123]
	v_mfma_f32_16x16x32_bf16 v[112:115], v[132:135], v[172:175], v[112:115]
	v_mfma_f32_16x16x32_bf16 v[104:107], v[140:143], v[172:175], v[104:107]
	v_mfma_f32_16x16x32_bf16 v[96:99], v[132:135], v[194:197], v[96:99]
	v_mfma_f32_16x16x32_bf16 v[88:91], v[140:143], v[194:197], v[88:91]
	v_mfma_f32_16x16x32_bf16 v[84:87], v[132:135], v[216:219], v[84:87]
	v_mfma_f32_16x16x32_bf16 v[76:79], v[140:143], v[216:219], v[76:79]
	s_setprio 0
	s_setprio 1
	v_mfma_f32_16x16x32_bf16 v[116:119], v[144:147], v[160:163], v[116:119]
	v_mfma_f32_16x16x32_bf16 v[108:111], v[152:155], v[160:163], v[108:111]
	v_mfma_f32_16x16x32_bf16 v[100:103], v[144:147], v[168:171], v[100:103]
	v_mfma_f32_16x16x32_bf16 v[92:95], v[152:155], v[168:171], v[92:95]
	v_mfma_f32_16x16x32_bf16 v[80:83], v[144:147], v[190:193], v[80:83]
	v_mfma_f32_16x16x32_bf16 v[72:75], v[152:155], v[190:193], v[72:75]
	v_mfma_f32_16x16x32_bf16 v[68:71], v[144:147], v[198:201], v[68:71]
	v_mfma_f32_16x16x32_bf16 v[64:67], v[152:155], v[198:201], v[64:67]
	v_mfma_f32_16x16x32_bf16 v[116:119], v[148:151], v[164:167], v[116:119]
	v_mfma_f32_16x16x32_bf16 v[108:111], v[156:159], v[164:167], v[108:111]
	v_mfma_f32_16x16x32_bf16 v[100:103], v[148:151], v[172:175], v[100:103]
	v_mfma_f32_16x16x32_bf16 v[92:95], v[156:159], v[172:175], v[92:95]
	v_mfma_f32_16x16x32_bf16 v[80:83], v[148:151], v[194:197], v[80:83]
	v_mfma_f32_16x16x32_bf16 v[72:75], v[156:159], v[194:197], v[72:75]
	v_mfma_f32_16x16x32_bf16 v[68:71], v[148:151], v[216:219], v[68:71]
	v_mfma_f32_16x16x32_bf16 v[64:67], v[156:159], v[216:219], v[64:67]
	s_setprio 0
	s_barrier
	s_add_i32 s53, s35, s22
	v_lshl_add_u64 v[202:203], s[18:19], 0, v[176:177]
	s_mov_b32 m0, s53
	ds_read_b128 v[160:163], v214 offset:16384
	ds_read_b128 v[164:167], v214 offset:17408
	ds_read_b128 v[168:171], v214 offset:18432
	ds_read_b128 v[172:175], v214 offset:19456
	ds_read_b128 v[190:193], v214 offset:20480
	ds_read_b128 v[194:197], v214 offset:21504
	ds_read_b128 v[198:201], v214 offset:22528
	ds_read_b128 v[216:219], v214 offset:23552
	global_load_lds_dwordx4 v[202:203], off
	s_add_i32 m0, s53, 0x2000
	s_add_u32 s54, s18, 0xb0000
	v_lshl_add_u64 v[220:221], s[18:19], 0, v[178:179]
	s_addc_u32 s55, s19, 0
	s_add_i32 s53, s40, s22
	global_load_lds_dwordx4 v[220:221], off
	v_lshl_add_u64 v[222:223], s[54:55], 0, v[176:177]
	s_mov_b32 m0, s53
	v_lshl_add_u64 v[224:225], s[20:21], 0, v[178:179]
	global_load_lds_dwordx4 v[222:223], off
	v_lshl_add_u64 v[222:223], s[54:55], 0, v[178:179]
	s_add_i32 m0, s53, 0x2000
	s_nop 0
	global_load_lds_dwordx4 v[222:223], off
	v_lshl_add_u64 v[222:223], s[20:21], 0, v[176:177]
	s_mov_b32 m0, s23
	s_nop 0
	global_load_lds_dwordx4 v[222:223], off
	s_mov_b32 m0, s24
	s_nop 0
	global_load_lds_dwordx4 v[224:225], off
	s_waitcnt vmcnt(8)
	s_waitcnt lgkmcnt(0)
	s_barrier
	s_setprio 1
	s_waitcnt lgkmcnt(0)
	v_mfma_f32_16x16x32_bf16 v[60:63], v[128:131], v[160:163], v[60:63]
	v_mfma_f32_16x16x32_bf16 v[56:59], v[136:139], v[160:163], v[56:59]
	v_mfma_f32_16x16x32_bf16 v[48:51], v[128:131], v[168:171], v[48:51]
	v_mfma_f32_16x16x32_bf16 v[40:43], v[136:139], v[168:171], v[40:43]
	v_mfma_f32_16x16x32_bf16 v[32:35], v[128:131], v[190:193], v[32:35]
	v_mfma_f32_16x16x32_bf16 v[24:27], v[136:139], v[190:193], v[24:27]
	v_mfma_f32_16x16x32_bf16 v[20:23], v[128:131], v[198:201], v[20:23]
	v_mfma_f32_16x16x32_bf16 v[12:15], v[136:139], v[198:201], v[12:15]
	v_mfma_f32_16x16x32_bf16 v[60:63], v[132:135], v[164:167], v[60:63]
	v_mfma_f32_16x16x32_bf16 v[56:59], v[140:143], v[164:167], v[56:59]
	v_mfma_f32_16x16x32_bf16 v[48:51], v[132:135], v[172:175], v[48:51]
	v_mfma_f32_16x16x32_bf16 v[40:43], v[140:143], v[172:175], v[40:43]
	v_mfma_f32_16x16x32_bf16 v[32:35], v[132:135], v[194:197], v[32:35]
	v_mfma_f32_16x16x32_bf16 v[24:27], v[140:143], v[194:197], v[24:27]
	v_mfma_f32_16x16x32_bf16 v[20:23], v[132:135], v[216:219], v[20:23]
	v_mfma_f32_16x16x32_bf16 v[12:15], v[140:143], v[216:219], v[12:15]
	s_setprio 0
	s_setprio 1
	v_mfma_f32_16x16x32_bf16 v[52:55], v[144:147], v[160:163], v[52:55]
	v_mfma_f32_16x16x32_bf16 v[44:47], v[152:155], v[160:163], v[44:47]
	v_mfma_f32_16x16x32_bf16 v[36:39], v[144:147], v[168:171], v[36:39]
	v_mfma_f32_16x16x32_bf16 v[28:31], v[152:155], v[168:171], v[28:31]
	v_mfma_f32_16x16x32_bf16 v[16:19], v[144:147], v[190:193], v[16:19]
	v_mfma_f32_16x16x32_bf16 v[8:11], v[152:155], v[190:193], v[8:11]
	v_mfma_f32_16x16x32_bf16 v[4:7], v[144:147], v[198:201], v[4:7]
	v_mfma_f32_16x16x32_bf16 v[0:3], v[152:155], v[198:201], v[0:3]
	v_mfma_f32_16x16x32_bf16 v[52:55], v[148:151], v[164:167], v[52:55]
	v_mfma_f32_16x16x32_bf16 v[44:47], v[156:159], v[164:167], v[44:47]
	v_mfma_f32_16x16x32_bf16 v[36:39], v[148:151], v[172:175], v[36:39]
	v_mfma_f32_16x16x32_bf16 v[28:31], v[156:159], v[172:175], v[28:31]
	v_mfma_f32_16x16x32_bf16 v[16:19], v[148:151], v[194:197], v[16:19]
	v_mfma_f32_16x16x32_bf16 v[8:11], v[156:159], v[194:197], v[8:11]
	v_mfma_f32_16x16x32_bf16 v[4:7], v[148:151], v[216:219], v[4:7]
	v_mfma_f32_16x16x32_bf16 v[0:3], v[156:159], v[216:219], v[0:3]
	s_setprio 0
	s_barrier
	s_add_i32 s53, 0, 0x18000
	s_add_i32 s54, 0, 0x1c000
	v_add_u32_e32 v140, s53, v210
	v_add_u32_e32 v156, s54, v210
	ds_read_b128 v[128:131], v140
	ds_read_b128 v[132:135], v140 offset:1024
	ds_read_b128 v[136:139], v140 offset:2048
	ds_read_b128 v[140:143], v140 offset:3072
	ds_read_b128 v[144:147], v156
	ds_read_b128 v[148:151], v156 offset:1024
	ds_read_b128 v[152:155], v156 offset:2048
	ds_read_b128 v[156:159], v156 offset:3072
	s_add_u32 s20, s20, 0xb0000
	s_addc_u32 s21, s21, 0
	s_mov_b32 m0, s25
	v_lshl_add_u64 v[226:227], s[20:21], 0, v[176:177]
	ds_read_b128 v[160:163], v214 offset:32768
	ds_read_b128 v[164:167], v214 offset:33792
	ds_read_b128 v[168:171], v214 offset:34816
	ds_read_b128 v[172:175], v214 offset:35840
	ds_read_b128 v[190:193], v214 offset:36864
	ds_read_b128 v[194:197], v214 offset:37888
	ds_read_b128 v[198:201], v214 offset:38912
	ds_read_b128 v[216:219], v214 offset:39936
	global_load_lds_dwordx4 v[226:227], off
	v_lshl_add_u64 v[226:227], s[20:21], 0, v[178:179]
	s_mov_b32 m0, s26
	s_nop 0
	global_load_lds_dwordx4 v[226:227], off
	s_waitcnt vmcnt(8)
	s_waitcnt lgkmcnt(0)
	s_barrier
	s_setprio 1
	s_waitcnt lgkmcnt(0)
	v_mfma_f32_16x16x32_bf16 v[124:127], v[128:131], v[160:163], v[124:127]
	v_mfma_f32_16x16x32_bf16 v[120:123], v[136:139], v[160:163], v[120:123]
	v_mfma_f32_16x16x32_bf16 v[112:115], v[128:131], v[168:171], v[112:115]
	v_mfma_f32_16x16x32_bf16 v[104:107], v[136:139], v[168:171], v[104:107]
	v_mfma_f32_16x16x32_bf16 v[96:99], v[128:131], v[190:193], v[96:99]
	v_mfma_f32_16x16x32_bf16 v[88:91], v[136:139], v[190:193], v[88:91]
	v_mfma_f32_16x16x32_bf16 v[84:87], v[128:131], v[198:201], v[84:87]
	v_mfma_f32_16x16x32_bf16 v[76:79], v[136:139], v[198:201], v[76:79]
	v_mfma_f32_16x16x32_bf16 v[124:127], v[132:135], v[164:167], v[124:127]
	v_mfma_f32_16x16x32_bf16 v[120:123], v[140:143], v[164:167], v[120:123]
	v_mfma_f32_16x16x32_bf16 v[112:115], v[132:135], v[172:175], v[112:115]
	v_mfma_f32_16x16x32_bf16 v[104:107], v[140:143], v[172:175], v[104:107]
	v_mfma_f32_16x16x32_bf16 v[96:99], v[132:135], v[194:197], v[96:99]
	v_mfma_f32_16x16x32_bf16 v[88:91], v[140:143], v[194:197], v[88:91]
	v_mfma_f32_16x16x32_bf16 v[84:87], v[132:135], v[216:219], v[84:87]
	v_mfma_f32_16x16x32_bf16 v[76:79], v[140:143], v[216:219], v[76:79]
	s_setprio 0
	s_setprio 1
	v_mfma_f32_16x16x32_bf16 v[116:119], v[144:147], v[160:163], v[116:119]
	v_mfma_f32_16x16x32_bf16 v[108:111], v[152:155], v[160:163], v[108:111]
	v_mfma_f32_16x16x32_bf16 v[100:103], v[144:147], v[168:171], v[100:103]
	v_mfma_f32_16x16x32_bf16 v[92:95], v[152:155], v[168:171], v[92:95]
	v_mfma_f32_16x16x32_bf16 v[80:83], v[144:147], v[190:193], v[80:83]
	v_mfma_f32_16x16x32_bf16 v[72:75], v[152:155], v[190:193], v[72:75]
	v_mfma_f32_16x16x32_bf16 v[68:71], v[144:147], v[198:201], v[68:71]
	v_mfma_f32_16x16x32_bf16 v[64:67], v[152:155], v[198:201], v[64:67]
	v_mfma_f32_16x16x32_bf16 v[116:119], v[148:151], v[164:167], v[116:119]
	v_mfma_f32_16x16x32_bf16 v[108:111], v[156:159], v[164:167], v[108:111]
	v_mfma_f32_16x16x32_bf16 v[100:103], v[148:151], v[172:175], v[100:103]
	v_mfma_f32_16x16x32_bf16 v[92:95], v[156:159], v[172:175], v[92:95]
	v_mfma_f32_16x16x32_bf16 v[80:83], v[148:151], v[194:197], v[80:83]
	v_mfma_f32_16x16x32_bf16 v[72:75], v[156:159], v[194:197], v[72:75]
	v_mfma_f32_16x16x32_bf16 v[68:71], v[148:151], v[216:219], v[68:71]
	v_mfma_f32_16x16x32_bf16 v[64:67], v[156:159], v[216:219], v[64:67]
	s_setprio 0
	s_barrier
	s_add_i32 s20, s53, s22
	v_lshl_add_u64 v[202:203], v[202:203], 0, s[10:11]
	s_mov_b32 m0, s20
	ds_read_b128 v[160:163], v214 offset:49152
	ds_read_b128 v[164:167], v214 offset:50176
	ds_read_b128 v[168:171], v214 offset:51200
	ds_read_b128 v[172:175], v214 offset:52224
	ds_read_b128 v[190:193], v214 offset:53248
	ds_read_b128 v[194:197], v214 offset:54272
	ds_read_b128 v[198:201], v214 offset:55296
	ds_read_b128 v[216:219], v214 offset:56320
	global_load_lds_dwordx4 v[202:203], off
	s_add_i32 m0, s20, 0x2000
	s_add_u32 s18, s18, 0xb0080
	v_lshl_add_u64 v[202:203], v[220:221], 0, s[10:11]
	s_addc_u32 s19, s19, 0
	s_add_i32 s20, s54, s22
	global_load_lds_dwordx4 v[202:203], off
	v_lshl_add_u64 v[202:203], s[18:19], 0, v[176:177]
	s_mov_b32 m0, s20
	s_nop 0
	global_load_lds_dwordx4 v[202:203], off
	v_lshl_add_u64 v[202:203], s[18:19], 0, v[178:179]
	s_add_i32 m0, s20, 0x2000
	s_nop 0
	global_load_lds_dwordx4 v[202:203], off
	v_lshl_add_u64 v[202:203], v[222:223], 0, s[10:11]
	s_mov_b32 m0, s29
	s_nop 0
	global_load_lds_dwordx4 v[202:203], off
	v_lshl_add_u64 v[202:203], v[224:225], 0, s[10:11]
	s_mov_b32 m0, s30
	s_nop 0
	global_load_lds_dwordx4 v[202:203], off
	s_waitcnt vmcnt(8)
	s_waitcnt lgkmcnt(0)
	s_barrier
	s_setprio 1
	s_waitcnt lgkmcnt(0)
	v_mfma_f32_16x16x32_bf16 v[60:63], v[128:131], v[160:163], v[60:63]
	v_mfma_f32_16x16x32_bf16 v[56:59], v[136:139], v[160:163], v[56:59]
	v_mfma_f32_16x16x32_bf16 v[48:51], v[128:131], v[168:171], v[48:51]
	v_mfma_f32_16x16x32_bf16 v[40:43], v[136:139], v[168:171], v[40:43]
	v_mfma_f32_16x16x32_bf16 v[32:35], v[128:131], v[190:193], v[32:35]
	v_mfma_f32_16x16x32_bf16 v[24:27], v[136:139], v[190:193], v[24:27]
	v_mfma_f32_16x16x32_bf16 v[20:23], v[128:131], v[198:201], v[20:23]
	v_mfma_f32_16x16x32_bf16 v[12:15], v[136:139], v[198:201], v[12:15]
	v_mfma_f32_16x16x32_bf16 v[60:63], v[132:135], v[164:167], v[60:63]
	v_mfma_f32_16x16x32_bf16 v[56:59], v[140:143], v[164:167], v[56:59]
	v_mfma_f32_16x16x32_bf16 v[48:51], v[132:135], v[172:175], v[48:51]
	v_mfma_f32_16x16x32_bf16 v[40:43], v[140:143], v[172:175], v[40:43]
	v_mfma_f32_16x16x32_bf16 v[32:35], v[132:135], v[194:197], v[32:35]
	v_mfma_f32_16x16x32_bf16 v[24:27], v[140:143], v[194:197], v[24:27]
	v_mfma_f32_16x16x32_bf16 v[20:23], v[132:135], v[216:219], v[20:23]
	v_mfma_f32_16x16x32_bf16 v[12:15], v[140:143], v[216:219], v[12:15]
	s_setprio 0
	s_setprio 1
	v_mfma_f32_16x16x32_bf16 v[52:55], v[144:147], v[160:163], v[52:55]
	v_mfma_f32_16x16x32_bf16 v[44:47], v[152:155], v[160:163], v[44:47]
	v_mfma_f32_16x16x32_bf16 v[36:39], v[144:147], v[168:171], v[36:39]
	v_mfma_f32_16x16x32_bf16 v[28:31], v[152:155], v[168:171], v[28:31]
	v_mfma_f32_16x16x32_bf16 v[16:19], v[144:147], v[190:193], v[16:19]
	v_mfma_f32_16x16x32_bf16 v[8:11], v[152:155], v[190:193], v[8:11]
	v_mfma_f32_16x16x32_bf16 v[4:7], v[144:147], v[198:201], v[4:7]
	v_mfma_f32_16x16x32_bf16 v[0:3], v[152:155], v[198:201], v[0:3]
	v_mfma_f32_16x16x32_bf16 v[52:55], v[148:151], v[164:167], v[52:55]
	v_mfma_f32_16x16x32_bf16 v[44:47], v[156:159], v[164:167], v[44:47]
	v_mfma_f32_16x16x32_bf16 v[36:39], v[148:151], v[172:175], v[36:39]
	v_mfma_f32_16x16x32_bf16 v[28:31], v[156:159], v[172:175], v[28:31]
	v_mfma_f32_16x16x32_bf16 v[16:19], v[148:151], v[194:197], v[16:19]
	v_mfma_f32_16x16x32_bf16 v[8:11], v[156:159], v[194:197], v[8:11]
	v_mfma_f32_16x16x32_bf16 v[4:7], v[148:151], v[216:219], v[4:7]
	v_mfma_f32_16x16x32_bf16 v[0:3], v[156:159], v[216:219], v[0:3]
	s_add_i32 s52, s52, 2
	s_add_u32 s16, s16, 0x100
	s_addc_u32 s17, s17, 0
	s_add_u32 s50, s50, 0x100
	s_addc_u32 s51, s51, 0
	s_cmp_gt_u32 s52, 41
	s_setprio 0
	s_barrier
	s_cbranch_scc0 .LBB0_1324
	s_and_b64 vcc, exec, s[12:13]
	s_cbranch_vccz .LBB0_1327
	s_barrier

.Llsb_skip_13:
.LBB0_1639:
	ds_read_b128 v[142:145], v135
	ds_read_b128 v[146:149], v135 offset:1024
	ds_read_b128 v[150:153], v135 offset:2048
	ds_read_b128 v[154:157], v135 offset:3072
	ds_read_b128 v[158:161], v140
	ds_read_b128 v[162:165], v140 offset:1024
	ds_read_b128 v[166:169], v140 offset:2048
	ds_read_b128 v[170:173], v140 offset:3072
	s_add_u32 s30, s28, 0xfffc0080
	s_addc_u32 s31, s29, -1
	s_cmp_eq_u32 s60, 12
	s_cselect_b32 s35, s23, s31
	s_cselect_b32 s34, s56, s30
	s_cselect_b32 s31, s21, s59
	s_cselect_b32 s30, s57, s58
	v_lshl_add_u64 v[202:203], s[28:29], 0, v[128:129]
	s_add_i32 m0, s43, 0xc000
	ds_read_b128 v[174:177], v141
	ds_read_b128 v[178:181], v141 offset:1024
	ds_read_b128 v[182:185], v141 offset:2048
	ds_read_b128 v[186:189], v141 offset:3072
	ds_read_b128 v[190:193], v141 offset:4096
	ds_read_b128 v[194:197], v141 offset:5120
	ds_read_b128 v[198:201], v141 offset:6144
	ds_read_b128 v[206:209], v141 offset:7168
	global_load_lds_dwordx4 v[202:203], off
	v_lshl_add_u64 v[202:203], s[28:29], 0, v[130:131]
	s_add_i32 m0, s43, 0xe000
	s_nop 0
	global_load_lds_dwordx4 v[202:203], off
	s_waitcnt vmcnt(8)
	s_waitcnt lgkmcnt(0)
	s_barrier
	s_setprio 1
	s_waitcnt lgkmcnt(0)
	v_mfma_f32_16x16x32_bf16 v[124:127], v[142:145], v[174:177], v[124:127]
	v_mfma_f32_16x16x32_bf16 v[120:123], v[150:153], v[174:177], v[120:123]
	v_mfma_f32_16x16x32_bf16 v[116:119], v[142:145], v[182:185], v[116:119]
	v_mfma_f32_16x16x32_bf16 v[112:115], v[150:153], v[182:185], v[112:115]
	v_mfma_f32_16x16x32_bf16 v[104:107], v[142:145], v[190:193], v[104:107]
	v_mfma_f32_16x16x32_bf16 v[96:99], v[150:153], v[190:193], v[96:99]
	v_mfma_f32_16x16x32_bf16 v[88:91], v[142:145], v[198:201], v[88:91]
	v_mfma_f32_16x16x32_bf16 v[80:83], v[150:153], v[198:201], v[80:83]
	v_mfma_f32_16x16x32_bf16 v[124:127], v[146:149], v[178:181], v[124:127]
	v_mfma_f32_16x16x32_bf16 v[120:123], v[154:157], v[178:181], v[120:123]
	v_mfma_f32_16x16x32_bf16 v[116:119], v[146:149], v[186:189], v[116:119]
	v_mfma_f32_16x16x32_bf16 v[112:115], v[154:157], v[186:189], v[112:115]
	v_mfma_f32_16x16x32_bf16 v[104:107], v[146:149], v[194:197], v[104:107]
	v_mfma_f32_16x16x32_bf16 v[96:99], v[154:157], v[194:197], v[96:99]
	v_mfma_f32_16x16x32_bf16 v[88:91], v[146:149], v[206:209], v[88:91]
	v_mfma_f32_16x16x32_bf16 v[80:83], v[154:157], v[206:209], v[80:83]
	s_setprio 0
	s_setprio 1
	v_mfma_f32_16x16x32_bf16 v[108:111], v[158:161], v[174:177], v[108:111]
	v_mfma_f32_16x16x32_bf16 v[100:103], v[166:169], v[174:177], v[100:103]
	v_mfma_f32_16x16x32_bf16 v[92:95], v[158:161], v[182:185], v[92:95]
	v_mfma_f32_16x16x32_bf16 v[84:87], v[166:169], v[182:185], v[84:87]
	v_mfma_f32_16x16x32_bf16 v[76:79], v[158:161], v[190:193], v[76:79]
	v_mfma_f32_16x16x32_bf16 v[72:75], v[166:169], v[190:193], v[72:75]
	v_mfma_f32_16x16x32_bf16 v[68:71], v[158:161], v[198:201], v[68:71]
	v_mfma_f32_16x16x32_bf16 v[64:67], v[166:169], v[198:201], v[64:67]
	v_mfma_f32_16x16x32_bf16 v[108:111], v[162:165], v[178:181], v[108:111]
	v_mfma_f32_16x16x32_bf16 v[100:103], v[170:173], v[178:181], v[100:103]
	v_mfma_f32_16x16x32_bf16 v[92:95], v[162:165], v[186:189], v[92:95]
	v_mfma_f32_16x16x32_bf16 v[84:87], v[170:173], v[186:189], v[84:87]
	v_mfma_f32_16x16x32_bf16 v[76:79], v[162:165], v[194:197], v[76:79]
	v_mfma_f32_16x16x32_bf16 v[72:75], v[170:173], v[194:197], v[72:75]
	v_mfma_f32_16x16x32_bf16 v[68:71], v[162:165], v[206:209], v[68:71]
	v_mfma_f32_16x16x32_bf16 v[64:67], v[170:173], v[206:209], v[64:67]
	s_setprio 0
	s_barrier
	s_add_i32 s61, s51, s40
	v_lshl_add_u64 v[202:203], s[30:31], 0, v[136:137]
	s_mov_b32 m0, s61
	ds_read_b128 v[174:177], v141 offset:16384
	ds_read_b128 v[178:181], v141 offset:17408
	ds_read_b128 v[182:185], v141 offset:18432
	ds_read_b128 v[186:189], v141 offset:19456
	ds_read_b128 v[190:193], v141 offset:20480
	ds_read_b128 v[194:197], v141 offset:21504
	ds_read_b128 v[198:201], v141 offset:22528
	ds_read_b128 v[206:209], v141 offset:23552
	global_load_lds_dwordx4 v[202:203], off
	s_add_i32 m0, s61, 0x2000
	s_add_u32 s62, s30, 0x40000
	v_lshl_add_u64 v[210:211], s[30:31], 0, v[138:139]
	s_addc_u32 s63, s31, 0
	s_add_i32 s61, s52, s40
	global_load_lds_dwordx4 v[210:211], off
	v_lshl_add_u64 v[212:213], s[62:63], 0, v[136:137]
	s_mov_b32 m0, s61
	v_lshl_add_u64 v[214:215], s[34:35], 0, v[138:139]
	global_load_lds_dwordx4 v[212:213], off
	v_lshl_add_u64 v[212:213], s[62:63], 0, v[138:139]
	s_add_i32 m0, s61, 0x2000
	s_nop 0
	global_load_lds_dwordx4 v[212:213], off
	v_lshl_add_u64 v[212:213], s[34:35], 0, v[136:137]
	s_mov_b32 m0, s43
	s_nop 0
	global_load_lds_dwordx4 v[212:213], off
	s_mov_b32 m0, s44
	s_nop 0
	global_load_lds_dwordx4 v[214:215], off
	s_waitcnt vmcnt(8)
	s_waitcnt lgkmcnt(0)
	s_barrier
	s_setprio 1
	s_waitcnt lgkmcnt(0)
	v_mfma_f32_16x16x32_bf16 v[60:63], v[142:145], v[174:177], v[60:63]
	v_mfma_f32_16x16x32_bf16 v[56:59], v[150:153], v[174:177], v[56:59]
	v_mfma_f32_16x16x32_bf16 v[52:55], v[142:145], v[182:185], v[52:55]
	v_mfma_f32_16x16x32_bf16 v[48:51], v[150:153], v[182:185], v[48:51]
	v_mfma_f32_16x16x32_bf16 v[40:43], v[142:145], v[190:193], v[40:43]
	v_mfma_f32_16x16x32_bf16 v[32:35], v[150:153], v[190:193], v[32:35]
	v_mfma_f32_16x16x32_bf16 v[24:27], v[142:145], v[198:201], v[24:27]
	v_mfma_f32_16x16x32_bf16 v[16:19], v[150:153], v[198:201], v[16:19]
	v_mfma_f32_16x16x32_bf16 v[60:63], v[146:149], v[178:181], v[60:63]
	v_mfma_f32_16x16x32_bf16 v[56:59], v[154:157], v[178:181], v[56:59]
	v_mfma_f32_16x16x32_bf16 v[52:55], v[146:149], v[186:189], v[52:55]
	v_mfma_f32_16x16x32_bf16 v[48:51], v[154:157], v[186:189], v[48:51]
	v_mfma_f32_16x16x32_bf16 v[40:43], v[146:149], v[194:197], v[40:43]
	v_mfma_f32_16x16x32_bf16 v[32:35], v[154:157], v[194:197], v[32:35]
	v_mfma_f32_16x16x32_bf16 v[24:27], v[146:149], v[206:209], v[24:27]
	v_mfma_f32_16x16x32_bf16 v[16:19], v[154:157], v[206:209], v[16:19]
	s_setprio 0
	s_setprio 1
	v_mfma_f32_16x16x32_bf16 v[44:47], v[158:161], v[174:177], v[44:47]
	v_mfma_f32_16x16x32_bf16 v[36:39], v[166:169], v[174:177], v[36:39]
	v_mfma_f32_16x16x32_bf16 v[28:31], v[158:161], v[182:185], v[28:31]
	v_mfma_f32_16x16x32_bf16 v[20:23], v[166:169], v[182:185], v[20:23]
	v_mfma_f32_16x16x32_bf16 v[12:15], v[158:161], v[190:193], v[12:15]
	v_mfma_f32_16x16x32_bf16 v[8:11], v[166:169], v[190:193], v[8:11]
	v_mfma_f32_16x16x32_bf16 v[4:7], v[158:161], v[198:201], v[4:7]
	v_mfma_f32_16x16x32_bf16 v[0:3], v[166:169], v[198:201], v[0:3]
	v_mfma_f32_16x16x32_bf16 v[44:47], v[162:165], v[178:181], v[44:47]
	v_mfma_f32_16x16x32_bf16 v[36:39], v[170:173], v[178:181], v[36:39]
	v_mfma_f32_16x16x32_bf16 v[28:31], v[162:165], v[186:189], v[28:31]
	v_mfma_f32_16x16x32_bf16 v[20:23], v[170:173], v[186:189], v[20:23]
	v_mfma_f32_16x16x32_bf16 v[12:15], v[162:165], v[194:197], v[12:15]
	v_mfma_f32_16x16x32_bf16 v[8:11], v[170:173], v[194:197], v[8:11]
	v_mfma_f32_16x16x32_bf16 v[4:7], v[162:165], v[206:209], v[4:7]
	v_mfma_f32_16x16x32_bf16 v[0:3], v[170:173], v[206:209], v[0:3]
	s_setprio 0
	s_barrier
	s_add_i32 s61, 0, 0x18000
	s_add_i32 s62, 0, 0x1c000
	v_add_u32_e32 v154, s61, v133
	v_add_u32_e32 v170, s62, v133
	ds_read_b128 v[142:145], v154
	ds_read_b128 v[146:149], v154 offset:1024
	ds_read_b128 v[150:153], v154 offset:2048
	ds_read_b128 v[154:157], v154 offset:3072
	ds_read_b128 v[158:161], v170
	ds_read_b128 v[162:165], v170 offset:1024
	ds_read_b128 v[166:169], v170 offset:2048
	ds_read_b128 v[170:173], v170 offset:3072
	s_add_u32 s34, s34, 0x40000
	s_addc_u32 s35, s35, 0
	s_mov_b32 m0, s45
	v_lshl_add_u64 v[216:217], s[34:35], 0, v[136:137]
	ds_read_b128 v[174:177], v141 offset:32768
	ds_read_b128 v[178:181], v141 offset:33792
	ds_read_b128 v[182:185], v141 offset:34816
	ds_read_b128 v[186:189], v141 offset:35840
	ds_read_b128 v[190:193], v141 offset:36864
	ds_read_b128 v[194:197], v141 offset:37888
	ds_read_b128 v[198:201], v141 offset:38912
	ds_read_b128 v[206:209], v141 offset:39936
	global_load_lds_dwordx4 v[216:217], off
	v_lshl_add_u64 v[216:217], s[34:35], 0, v[138:139]
	s_mov_b32 m0, s46
	s_nop 0
	global_load_lds_dwordx4 v[216:217], off
	s_waitcnt vmcnt(8)
	s_waitcnt lgkmcnt(0)
	s_barrier
	s_setprio 1
	s_waitcnt lgkmcnt(0)
	v_mfma_f32_16x16x32_bf16 v[124:127], v[142:145], v[174:177], v[124:127]
	v_mfma_f32_16x16x32_bf16 v[120:123], v[150:153], v[174:177], v[120:123]
	v_mfma_f32_16x16x32_bf16 v[116:119], v[142:145], v[182:185], v[116:119]
	v_mfma_f32_16x16x32_bf16 v[112:115], v[150:153], v[182:185], v[112:115]
	v_mfma_f32_16x16x32_bf16 v[104:107], v[142:145], v[190:193], v[104:107]
	v_mfma_f32_16x16x32_bf16 v[96:99], v[150:153], v[190:193], v[96:99]
	v_mfma_f32_16x16x32_bf16 v[88:91], v[142:145], v[198:201], v[88:91]
	v_mfma_f32_16x16x32_bf16 v[80:83], v[150:153], v[198:201], v[80:83]
	v_mfma_f32_16x16x32_bf16 v[124:127], v[146:149], v[178:181], v[124:127]
	v_mfma_f32_16x16x32_bf16 v[120:123], v[154:157], v[178:181], v[120:123]
	v_mfma_f32_16x16x32_bf16 v[116:119], v[146:149], v[186:189], v[116:119]
	v_mfma_f32_16x16x32_bf16 v[112:115], v[154:157], v[186:189], v[112:115]
	v_mfma_f32_16x16x32_bf16 v[104:107], v[146:149], v[194:197], v[104:107]
	v_mfma_f32_16x16x32_bf16 v[96:99], v[154:157], v[194:197], v[96:99]
	v_mfma_f32_16x16x32_bf16 v[88:91], v[146:149], v[206:209], v[88:91]
	v_mfma_f32_16x16x32_bf16 v[80:83], v[154:157], v[206:209], v[80:83]
	s_setprio 0
	s_setprio 1
	v_mfma_f32_16x16x32_bf16 v[108:111], v[158:161], v[174:177], v[108:111]
	v_mfma_f32_16x16x32_bf16 v[100:103], v[166:169], v[174:177], v[100:103]
	v_mfma_f32_16x16x32_bf16 v[92:95], v[158:161], v[182:185], v[92:95]
	v_mfma_f32_16x16x32_bf16 v[84:87], v[166:169], v[182:185], v[84:87]
	v_mfma_f32_16x16x32_bf16 v[76:79], v[158:161], v[190:193], v[76:79]
	v_mfma_f32_16x16x32_bf16 v[72:75], v[166:169], v[190:193], v[72:75]
	v_mfma_f32_16x16x32_bf16 v[68:71], v[158:161], v[198:201], v[68:71]
	v_mfma_f32_16x16x32_bf16 v[64:67], v[166:169], v[198:201], v[64:67]
	v_mfma_f32_16x16x32_bf16 v[108:111], v[162:165], v[178:181], v[108:111]
	v_mfma_f32_16x16x32_bf16 v[100:103], v[170:173], v[178:181], v[100:103]
	v_mfma_f32_16x16x32_bf16 v[92:95], v[162:165], v[186:189], v[92:95]
	v_mfma_f32_16x16x32_bf16 v[84:87], v[170:173], v[186:189], v[84:87]
	v_mfma_f32_16x16x32_bf16 v[76:79], v[162:165], v[194:197], v[76:79]
	v_mfma_f32_16x16x32_bf16 v[72:75], v[170:173], v[194:197], v[72:75]
	v_mfma_f32_16x16x32_bf16 v[68:71], v[162:165], v[206:209], v[68:71]
	v_mfma_f32_16x16x32_bf16 v[64:67], v[170:173], v[206:209], v[64:67]
	s_setprio 0
	s_barrier
	s_add_i32 s34, s61, s40
	v_lshl_add_u64 v[202:203], v[202:203], 0, s[6:7]
	s_mov_b32 m0, s34
	ds_read_b128 v[174:177], v141 offset:49152
	ds_read_b128 v[178:181], v141 offset:50176
	ds_read_b128 v[182:185], v141 offset:51200
	ds_read_b128 v[186:189], v141 offset:52224
	ds_read_b128 v[190:193], v141 offset:53248
	ds_read_b128 v[194:197], v141 offset:54272
	ds_read_b128 v[198:201], v141 offset:55296
	ds_read_b128 v[206:209], v141 offset:56320
	global_load_lds_dwordx4 v[202:203], off
	s_add_i32 m0, s34, 0x2000
	s_add_u32 s30, s30, 0x40080
	v_lshl_add_u64 v[202:203], v[210:211], 0, s[6:7]
	s_addc_u32 s31, s31, 0
	s_add_i32 s34, s62, s40
	global_load_lds_dwordx4 v[202:203], off
	v_lshl_add_u64 v[202:203], s[30:31], 0, v[136:137]
	s_mov_b32 m0, s34
	s_nop 0
	global_load_lds_dwordx4 v[202:203], off
	v_lshl_add_u64 v[202:203], s[30:31], 0, v[138:139]
	s_add_i32 m0, s34, 0x2000
	s_nop 0
	global_load_lds_dwordx4 v[202:203], off
	v_lshl_add_u64 v[202:203], v[212:213], 0, s[6:7]
	s_mov_b32 m0, s48
	s_nop 0
	global_load_lds_dwordx4 v[202:203], off
	v_lshl_add_u64 v[202:203], v[214:215], 0, s[6:7]
	s_mov_b32 m0, s49
	s_nop 0
	global_load_lds_dwordx4 v[202:203], off
	s_waitcnt vmcnt(8)
	s_waitcnt lgkmcnt(0)
	s_barrier
	s_setprio 1
	s_waitcnt lgkmcnt(0)
	v_mfma_f32_16x16x32_bf16 v[60:63], v[142:145], v[174:177], v[60:63]
	v_mfma_f32_16x16x32_bf16 v[56:59], v[150:153], v[174:177], v[56:59]
	v_mfma_f32_16x16x32_bf16 v[52:55], v[142:145], v[182:185], v[52:55]
	v_mfma_f32_16x16x32_bf16 v[48:51], v[150:153], v[182:185], v[48:51]
	v_mfma_f32_16x16x32_bf16 v[40:43], v[142:145], v[190:193], v[40:43]
	v_mfma_f32_16x16x32_bf16 v[32:35], v[150:153], v[190:193], v[32:35]
	v_mfma_f32_16x16x32_bf16 v[24:27], v[142:145], v[198:201], v[24:27]
	v_mfma_f32_16x16x32_bf16 v[16:19], v[150:153], v[198:201], v[16:19]
	v_mfma_f32_16x16x32_bf16 v[60:63], v[146:149], v[178:181], v[60:63]
	v_mfma_f32_16x16x32_bf16 v[56:59], v[154:157], v[178:181], v[56:59]
	v_mfma_f32_16x16x32_bf16 v[52:55], v[146:149], v[186:189], v[52:55]
	v_mfma_f32_16x16x32_bf16 v[48:51], v[154:157], v[186:189], v[48:51]
	v_mfma_f32_16x16x32_bf16 v[40:43], v[146:149], v[194:197], v[40:43]
	v_mfma_f32_16x16x32_bf16 v[32:35], v[154:157], v[194:197], v[32:35]
	v_mfma_f32_16x16x32_bf16 v[24:27], v[146:149], v[206:209], v[24:27]
	v_mfma_f32_16x16x32_bf16 v[16:19], v[154:157], v[206:209], v[16:19]
	s_setprio 0
	s_setprio 1
	v_mfma_f32_16x16x32_bf16 v[44:47], v[158:161], v[174:177], v[44:47]
	v_mfma_f32_16x16x32_bf16 v[36:39], v[166:169], v[174:177], v[36:39]
	v_mfma_f32_16x16x32_bf16 v[28:31], v[158:161], v[182:185], v[28:31]
	v_mfma_f32_16x16x32_bf16 v[20:23], v[166:169], v[182:185], v[20:23]
	v_mfma_f32_16x16x32_bf16 v[12:15], v[158:161], v[190:193], v[12:15]
	v_mfma_f32_16x16x32_bf16 v[8:11], v[166:169], v[190:193], v[8:11]
	v_mfma_f32_16x16x32_bf16 v[4:7], v[158:161], v[198:201], v[4:7]
	v_mfma_f32_16x16x32_bf16 v[0:3], v[166:169], v[198:201], v[0:3]
	v_mfma_f32_16x16x32_bf16 v[44:47], v[162:165], v[178:181], v[44:47]
	v_mfma_f32_16x16x32_bf16 v[36:39], v[170:173], v[178:181], v[36:39]
	v_mfma_f32_16x16x32_bf16 v[28:31], v[162:165], v[186:189], v[28:31]
	v_mfma_f32_16x16x32_bf16 v[20:23], v[170:173], v[186:189], v[20:23]
	v_mfma_f32_16x16x32_bf16 v[12:15], v[162:165], v[194:197], v[12:15]
	v_mfma_f32_16x16x32_bf16 v[8:11], v[170:173], v[194:197], v[8:11]
	v_mfma_f32_16x16x32_bf16 v[4:7], v[162:165], v[206:209], v[4:7]
	v_mfma_f32_16x16x32_bf16 v[0:3], v[170:173], v[206:209], v[0:3]
	s_add_i32 s60, s60, 2
	s_add_u32 s28, s28, 0x100
	s_addc_u32 s29, s29, 0
	s_add_u32 s58, s58, 0x100
	s_addc_u32 s59, s59, 0
	s_cmp_gt_u32 s60, 13
	s_setprio 0
	s_barrier
	s_cbranch_scc0 .LBB0_1639
	s_and_b64 vcc, exec, s[10:11]
	s_cbranch_vccz .LBB0_1642
	s_barrier

.Llsb_skip_17:
.LBB0_2065:
	ds_read_b128 v[136:139], v154
	ds_read_b128 v[140:143], v154 offset:1024
	ds_read_b128 v[144:147], v154 offset:2048
	ds_read_b128 v[158:161], v154 offset:3072
	ds_read_b128 v[162:165], v155
	ds_read_b128 v[166:169], v155 offset:1024
	ds_read_b128 v[170:173], v155 offset:2048
	ds_read_b128 v[180:183], v155 offset:3072
	s_add_u32 s38, s36, 0xfffa0080
	s_addc_u32 s39, s37, -1
	s_cmp_eq_u32 s67, 4
	s_cselect_b32 s41, s31, s39
	s_cselect_b32 s40, s30, s38
	s_cselect_b32 s39, s35, s66
	s_cselect_b32 s38, s34, s65
	v_lshl_add_u64 v[148:149], s[36:37], 0, v[132:133]
	s_add_i32 m0, s45, 0xc000
	ds_read_b128 v[184:187], v156
	ds_read_b128 v[188:191], v156 offset:1024
	ds_read_b128 v[192:195], v156 offset:2048
	ds_read_b128 v[196:199], v156 offset:3072
	ds_read_b128 v[200:203], v156 offset:4096
	ds_read_b128 v[206:209], v156 offset:5120
	ds_read_b128 v[210:213], v156 offset:6144
	ds_read_b128 v[214:217], v156 offset:7168
	global_load_lds_dwordx4 v[148:149], off
	v_lshl_add_u64 v[148:149], s[36:37], 0, v[134:135]
	s_add_i32 m0, s45, 0xe000
	s_nop 0
	global_load_lds_dwordx4 v[148:149], off
	s_waitcnt vmcnt(8)
	s_waitcnt lgkmcnt(0)
	s_barrier
	s_setprio 1
	s_waitcnt lgkmcnt(0)
	v_mfma_f32_16x16x32_bf16 v[124:127], v[136:139], v[184:187], v[124:127]
	v_mfma_f32_16x16x32_bf16 v[120:123], v[144:147], v[184:187], v[120:123]
	v_mfma_f32_16x16x32_bf16 v[112:115], v[136:139], v[192:195], v[112:115]
	v_mfma_f32_16x16x32_bf16 v[104:107], v[144:147], v[192:195], v[104:107]
	v_mfma_f32_16x16x32_bf16 v[96:99], v[136:139], v[200:203], v[96:99]
	v_mfma_f32_16x16x32_bf16 v[88:91], v[144:147], v[200:203], v[88:91]
	v_mfma_f32_16x16x32_bf16 v[80:83], v[136:139], v[210:213], v[80:83]
	v_mfma_f32_16x16x32_bf16 v[72:75], v[144:147], v[210:213], v[72:75]
	v_mfma_f32_16x16x32_bf16 v[124:127], v[140:143], v[188:191], v[124:127]
	v_mfma_f32_16x16x32_bf16 v[120:123], v[158:161], v[188:191], v[120:123]
	v_mfma_f32_16x16x32_bf16 v[112:115], v[140:143], v[196:199], v[112:115]
	v_mfma_f32_16x16x32_bf16 v[104:107], v[158:161], v[196:199], v[104:107]
	v_mfma_f32_16x16x32_bf16 v[96:99], v[140:143], v[206:209], v[96:99]
	v_mfma_f32_16x16x32_bf16 v[88:91], v[158:161], v[206:209], v[88:91]
	v_mfma_f32_16x16x32_bf16 v[80:83], v[140:143], v[214:217], v[80:83]
	v_mfma_f32_16x16x32_bf16 v[72:75], v[158:161], v[214:217], v[72:75]
	s_setprio 0
	s_setprio 1
	v_mfma_f32_16x16x32_bf16 v[116:119], v[162:165], v[184:187], v[116:119]
	v_mfma_f32_16x16x32_bf16 v[108:111], v[170:173], v[184:187], v[108:111]
	v_mfma_f32_16x16x32_bf16 v[100:103], v[162:165], v[192:195], v[100:103]
	v_mfma_f32_16x16x32_bf16 v[92:95], v[170:173], v[192:195], v[92:95]
	v_mfma_f32_16x16x32_bf16 v[84:87], v[162:165], v[200:203], v[84:87]
	v_mfma_f32_16x16x32_bf16 v[76:79], v[170:173], v[200:203], v[76:79]
	v_mfma_f32_16x16x32_bf16 v[68:71], v[162:165], v[210:213], v[68:71]
	v_mfma_f32_16x16x32_bf16 v[64:67], v[170:173], v[210:213], v[64:67]
	v_mfma_f32_16x16x32_bf16 v[116:119], v[166:169], v[188:191], v[116:119]
	v_mfma_f32_16x16x32_bf16 v[108:111], v[180:183], v[188:191], v[108:111]
	v_mfma_f32_16x16x32_bf16 v[100:103], v[166:169], v[196:199], v[100:103]
	v_mfma_f32_16x16x32_bf16 v[92:95], v[180:183], v[196:199], v[92:95]
	v_mfma_f32_16x16x32_bf16 v[84:87], v[166:169], v[206:209], v[84:87]
	v_mfma_f32_16x16x32_bf16 v[76:79], v[180:183], v[206:209], v[76:79]
	v_mfma_f32_16x16x32_bf16 v[68:71], v[166:169], v[214:217], v[68:71]
	v_mfma_f32_16x16x32_bf16 v[64:67], v[180:183], v[214:217], v[64:67]
	s_setprio 0
	s_barrier
	s_add_i32 s68, s52, s44
	v_lshl_add_u64 v[148:149], s[38:39], 0, v[130:131]
	s_mov_b32 m0, s68
	ds_read_b128 v[184:187], v156 offset:16384
	ds_read_b128 v[188:191], v156 offset:17408
	ds_read_b128 v[192:195], v156 offset:18432
	ds_read_b128 v[196:199], v156 offset:19456
	ds_read_b128 v[200:203], v156 offset:20480
	ds_read_b128 v[206:209], v156 offset:21504
	ds_read_b128 v[210:213], v156 offset:22528
	ds_read_b128 v[214:217], v156 offset:23552
	global_load_lds_dwordx4 v[148:149], off
	s_add_i32 m0, s68, 0x2000
	s_add_u32 s68, s38, 0x60000
	v_lshl_add_u64 v[174:175], s[38:39], 0, v[128:129]
	s_addc_u32 s69, s39, 0
	s_add_i32 s70, s53, s44
	global_load_lds_dwordx4 v[174:175], off
	v_lshl_add_u64 v[218:219], s[68:69], 0, v[130:131]
	s_mov_b32 m0, s70
	v_lshl_add_u64 v[220:221], s[40:41], 0, v[128:129]
	global_load_lds_dwordx4 v[218:219], off
	v_lshl_add_u64 v[218:219], s[68:69], 0, v[128:129]
	s_add_i32 m0, s70, 0x2000
	s_nop 0
	global_load_lds_dwordx4 v[218:219], off
	v_lshl_add_u64 v[218:219], s[40:41], 0, v[130:131]
	s_mov_b32 m0, s45
	s_nop 0
	global_load_lds_dwordx4 v[218:219], off
	s_mov_b32 m0, s46
	s_nop 0
	global_load_lds_dwordx4 v[220:221], off
	s_waitcnt vmcnt(8)
	s_waitcnt lgkmcnt(0)
	s_barrier
	s_setprio 1
	s_waitcnt lgkmcnt(0)
	v_mfma_f32_16x16x32_bf16 v[60:63], v[136:139], v[184:187], v[60:63]
	v_mfma_f32_16x16x32_bf16 v[56:59], v[144:147], v[184:187], v[56:59]
	v_mfma_f32_16x16x32_bf16 v[48:51], v[136:139], v[192:195], v[48:51]
	v_mfma_f32_16x16x32_bf16 v[40:43], v[144:147], v[192:195], v[40:43]
	v_mfma_f32_16x16x32_bf16 v[32:35], v[136:139], v[200:203], v[32:35]
	v_mfma_f32_16x16x32_bf16 v[24:27], v[144:147], v[200:203], v[24:27]
	v_mfma_f32_16x16x32_bf16 v[16:19], v[136:139], v[210:213], v[16:19]
	v_mfma_f32_16x16x32_bf16 v[8:11], v[144:147], v[210:213], v[8:11]
	v_mfma_f32_16x16x32_bf16 v[60:63], v[140:143], v[188:191], v[60:63]
	v_mfma_f32_16x16x32_bf16 v[56:59], v[158:161], v[188:191], v[56:59]
	v_mfma_f32_16x16x32_bf16 v[48:51], v[140:143], v[196:199], v[48:51]
	v_mfma_f32_16x16x32_bf16 v[40:43], v[158:161], v[196:199], v[40:43]
	v_mfma_f32_16x16x32_bf16 v[32:35], v[140:143], v[206:209], v[32:35]
	v_mfma_f32_16x16x32_bf16 v[24:27], v[158:161], v[206:209], v[24:27]
	v_mfma_f32_16x16x32_bf16 v[16:19], v[140:143], v[214:217], v[16:19]
	v_mfma_f32_16x16x32_bf16 v[8:11], v[158:161], v[214:217], v[8:11]
	s_setprio 0
	s_setprio 1
	v_mfma_f32_16x16x32_bf16 v[52:55], v[162:165], v[184:187], v[52:55]
	v_mfma_f32_16x16x32_bf16 v[44:47], v[170:173], v[184:187], v[44:47]
	v_mfma_f32_16x16x32_bf16 v[36:39], v[162:165], v[192:195], v[36:39]
	v_mfma_f32_16x16x32_bf16 v[28:31], v[170:173], v[192:195], v[28:31]
	v_mfma_f32_16x16x32_bf16 v[20:23], v[162:165], v[200:203], v[20:23]
	v_mfma_f32_16x16x32_bf16 v[12:15], v[170:173], v[200:203], v[12:15]
	v_mfma_f32_16x16x32_bf16 v[4:7], v[162:165], v[210:213], v[4:7]
	v_mfma_f32_16x16x32_bf16 v[0:3], v[170:173], v[210:213], v[0:3]
	v_mfma_f32_16x16x32_bf16 v[52:55], v[166:169], v[188:191], v[52:55]
	v_mfma_f32_16x16x32_bf16 v[44:47], v[180:183], v[188:191], v[44:47]
	v_mfma_f32_16x16x32_bf16 v[36:39], v[166:169], v[196:199], v[36:39]
	v_mfma_f32_16x16x32_bf16 v[28:31], v[180:183], v[196:199], v[28:31]
	v_mfma_f32_16x16x32_bf16 v[20:23], v[166:169], v[206:209], v[20:23]
	v_mfma_f32_16x16x32_bf16 v[12:15], v[180:183], v[206:209], v[12:15]
	v_mfma_f32_16x16x32_bf16 v[4:7], v[166:169], v[214:217], v[4:7]
	v_mfma_f32_16x16x32_bf16 v[0:3], v[180:183], v[214:217], v[0:3]
	s_setprio 0
	s_barrier
	s_add_i32 s68, 0, 0x18000
	v_add_u32_e32 v157, s68, v152
	s_add_i32 s69, 0, 0x1c000
	ds_read_b128 v[136:139], v157
	ds_read_b128 v[140:143], v157 offset:1024
	ds_read_b128 v[144:147], v157 offset:2048
	ds_read_b128 v[158:161], v157 offset:3072
	v_add_u32_e32 v157, s69, v152
	ds_read_b128 v[162:165], v157
	ds_read_b128 v[166:169], v157 offset:1024
	ds_read_b128 v[170:173], v157 offset:2048
	ds_read_b128 v[180:183], v157 offset:3072
	s_add_u32 s40, s40, 0x60000
	s_addc_u32 s41, s41, 0
	s_mov_b32 m0, s47
	v_lshl_add_u64 v[222:223], s[40:41], 0, v[130:131]
	ds_read_b128 v[184:187], v156 offset:32768
	ds_read_b128 v[188:191], v156 offset:33792
	ds_read_b128 v[192:195], v156 offset:34816
	ds_read_b128 v[196:199], v156 offset:35840
	ds_read_b128 v[200:203], v156 offset:36864
	ds_read_b128 v[206:209], v156 offset:37888
	ds_read_b128 v[210:213], v156 offset:38912
	ds_read_b128 v[214:217], v156 offset:39936
	global_load_lds_dwordx4 v[222:223], off
	v_lshl_add_u64 v[222:223], s[40:41], 0, v[128:129]
	s_mov_b32 m0, s48
	s_nop 0
	global_load_lds_dwordx4 v[222:223], off
	s_waitcnt vmcnt(8)
	s_waitcnt lgkmcnt(0)
	s_barrier
	s_setprio 1
	s_waitcnt lgkmcnt(0)
	v_mfma_f32_16x16x32_bf16 v[124:127], v[136:139], v[184:187], v[124:127]
	v_mfma_f32_16x16x32_bf16 v[120:123], v[144:147], v[184:187], v[120:123]
	v_mfma_f32_16x16x32_bf16 v[112:115], v[136:139], v[192:195], v[112:115]
	v_mfma_f32_16x16x32_bf16 v[104:107], v[144:147], v[192:195], v[104:107]
	v_mfma_f32_16x16x32_bf16 v[96:99], v[136:139], v[200:203], v[96:99]
	v_mfma_f32_16x16x32_bf16 v[88:91], v[144:147], v[200:203], v[88:91]
	v_mfma_f32_16x16x32_bf16 v[80:83], v[136:139], v[210:213], v[80:83]
	v_mfma_f32_16x16x32_bf16 v[72:75], v[144:147], v[210:213], v[72:75]
	v_mfma_f32_16x16x32_bf16 v[124:127], v[140:143], v[188:191], v[124:127]
	v_mfma_f32_16x16x32_bf16 v[120:123], v[158:161], v[188:191], v[120:123]
	v_mfma_f32_16x16x32_bf16 v[112:115], v[140:143], v[196:199], v[112:115]
	v_mfma_f32_16x16x32_bf16 v[104:107], v[158:161], v[196:199], v[104:107]
	v_mfma_f32_16x16x32_bf16 v[96:99], v[140:143], v[206:209], v[96:99]
	v_mfma_f32_16x16x32_bf16 v[88:91], v[158:161], v[206:209], v[88:91]
	v_mfma_f32_16x16x32_bf16 v[80:83], v[140:143], v[214:217], v[80:83]
	v_mfma_f32_16x16x32_bf16 v[72:75], v[158:161], v[214:217], v[72:75]
	s_setprio 0
	s_setprio 1
	v_mfma_f32_16x16x32_bf16 v[116:119], v[162:165], v[184:187], v[116:119]
	v_mfma_f32_16x16x32_bf16 v[108:111], v[170:173], v[184:187], v[108:111]
	v_mfma_f32_16x16x32_bf16 v[100:103], v[162:165], v[192:195], v[100:103]
	v_mfma_f32_16x16x32_bf16 v[92:95], v[170:173], v[192:195], v[92:95]
	v_mfma_f32_16x16x32_bf16 v[84:87], v[162:165], v[200:203], v[84:87]
	v_mfma_f32_16x16x32_bf16 v[76:79], v[170:173], v[200:203], v[76:79]
	v_mfma_f32_16x16x32_bf16 v[68:71], v[162:165], v[210:213], v[68:71]
	v_mfma_f32_16x16x32_bf16 v[64:67], v[170:173], v[210:213], v[64:67]
	v_mfma_f32_16x16x32_bf16 v[116:119], v[166:169], v[188:191], v[116:119]
	v_mfma_f32_16x16x32_bf16 v[108:111], v[180:183], v[188:191], v[108:111]
	v_mfma_f32_16x16x32_bf16 v[100:103], v[166:169], v[196:199], v[100:103]
	v_mfma_f32_16x16x32_bf16 v[92:95], v[180:183], v[196:199], v[92:95]
	v_mfma_f32_16x16x32_bf16 v[84:87], v[166:169], v[206:209], v[84:87]
	v_mfma_f32_16x16x32_bf16 v[76:79], v[180:183], v[206:209], v[76:79]
	v_mfma_f32_16x16x32_bf16 v[68:71], v[166:169], v[214:217], v[68:71]
	v_mfma_f32_16x16x32_bf16 v[64:67], v[180:183], v[214:217], v[64:67]
	s_setprio 0
	s_barrier
	s_add_i32 s40, s68, s44
	v_lshl_add_u64 v[148:149], v[148:149], 0, s[16:17]
	s_mov_b32 m0, s40
	ds_read_b128 v[184:187], v156 offset:49152
	ds_read_b128 v[188:191], v156 offset:50176
	ds_read_b128 v[192:195], v156 offset:51200
	ds_read_b128 v[196:199], v156 offset:52224
	ds_read_b128 v[200:203], v156 offset:53248
	ds_read_b128 v[206:209], v156 offset:54272
	ds_read_b128 v[210:213], v156 offset:55296
	ds_read_b128 v[214:217], v156 offset:56320
	global_load_lds_dwordx4 v[148:149], off
	s_add_i32 m0, s40, 0x2000
	s_add_u32 s38, s38, 0x60080
	v_lshl_add_u64 v[148:149], v[174:175], 0, s[16:17]
	s_addc_u32 s39, s39, 0
	s_add_i32 s40, s69, s44
	global_load_lds_dwordx4 v[148:149], off
	v_lshl_add_u64 v[148:149], s[38:39], 0, v[130:131]
	s_mov_b32 m0, s40
	s_nop 0
	global_load_lds_dwordx4 v[148:149], off
	v_lshl_add_u64 v[148:149], s[38:39], 0, v[128:129]
	s_add_i32 m0, s40, 0x2000
	s_nop 0
	global_load_lds_dwordx4 v[148:149], off
	v_lshl_add_u64 v[148:149], v[218:219], 0, s[16:17]
	s_mov_b32 m0, s49
	s_nop 0
	global_load_lds_dwordx4 v[148:149], off
	v_lshl_add_u64 v[148:149], v[220:221], 0, s[16:17]
	s_mov_b32 m0, s50
	s_nop 0
	global_load_lds_dwordx4 v[148:149], off
	s_waitcnt vmcnt(8)
	s_waitcnt lgkmcnt(0)
	s_barrier
	s_setprio 1
	s_waitcnt lgkmcnt(0)
	v_mfma_f32_16x16x32_bf16 v[60:63], v[136:139], v[184:187], v[60:63]
	v_mfma_f32_16x16x32_bf16 v[56:59], v[144:147], v[184:187], v[56:59]
	v_mfma_f32_16x16x32_bf16 v[48:51], v[136:139], v[192:195], v[48:51]
	v_mfma_f32_16x16x32_bf16 v[40:43], v[144:147], v[192:195], v[40:43]
	v_mfma_f32_16x16x32_bf16 v[32:35], v[136:139], v[200:203], v[32:35]
	v_mfma_f32_16x16x32_bf16 v[24:27], v[144:147], v[200:203], v[24:27]
	v_mfma_f32_16x16x32_bf16 v[16:19], v[136:139], v[210:213], v[16:19]
	v_mfma_f32_16x16x32_bf16 v[8:11], v[144:147], v[210:213], v[8:11]
	v_mfma_f32_16x16x32_bf16 v[60:63], v[140:143], v[188:191], v[60:63]
	v_mfma_f32_16x16x32_bf16 v[56:59], v[158:161], v[188:191], v[56:59]
	v_mfma_f32_16x16x32_bf16 v[48:51], v[140:143], v[196:199], v[48:51]
	v_mfma_f32_16x16x32_bf16 v[40:43], v[158:161], v[196:199], v[40:43]
	v_mfma_f32_16x16x32_bf16 v[32:35], v[140:143], v[206:209], v[32:35]
	v_mfma_f32_16x16x32_bf16 v[24:27], v[158:161], v[206:209], v[24:27]
	v_mfma_f32_16x16x32_bf16 v[16:19], v[140:143], v[214:217], v[16:19]
	v_mfma_f32_16x16x32_bf16 v[8:11], v[158:161], v[214:217], v[8:11]
	s_setprio 0
	s_setprio 1
	v_mfma_f32_16x16x32_bf16 v[52:55], v[162:165], v[184:187], v[52:55]
	v_mfma_f32_16x16x32_bf16 v[44:47], v[170:173], v[184:187], v[44:47]
	v_mfma_f32_16x16x32_bf16 v[36:39], v[162:165], v[192:195], v[36:39]
	v_mfma_f32_16x16x32_bf16 v[28:31], v[170:173], v[192:195], v[28:31]
	v_mfma_f32_16x16x32_bf16 v[20:23], v[162:165], v[200:203], v[20:23]
	v_mfma_f32_16x16x32_bf16 v[12:15], v[170:173], v[200:203], v[12:15]
	v_mfma_f32_16x16x32_bf16 v[4:7], v[162:165], v[210:213], v[4:7]
	v_mfma_f32_16x16x32_bf16 v[0:3], v[170:173], v[210:213], v[0:3]
	v_mfma_f32_16x16x32_bf16 v[52:55], v[166:169], v[188:191], v[52:55]
	v_mfma_f32_16x16x32_bf16 v[44:47], v[180:183], v[188:191], v[44:47]
	v_mfma_f32_16x16x32_bf16 v[36:39], v[166:169], v[196:199], v[36:39]
	v_mfma_f32_16x16x32_bf16 v[28:31], v[180:183], v[196:199], v[28:31]
	v_mfma_f32_16x16x32_bf16 v[20:23], v[166:169], v[206:209], v[20:23]
	v_mfma_f32_16x16x32_bf16 v[12:15], v[180:183], v[206:209], v[12:15]
	v_mfma_f32_16x16x32_bf16 v[4:7], v[166:169], v[214:217], v[4:7]
	v_mfma_f32_16x16x32_bf16 v[0:3], v[180:183], v[214:217], v[0:3]
	s_add_i32 s67, s67, 2
	s_add_u32 s36, s36, 0x100
	s_addc_u32 s37, s37, 0
	s_add_u32 s65, s65, 0x100
	s_addc_u32 s66, s66, 0
	s_cmp_gt_u32 s67, 5
	s_setprio 0
	s_barrier
	s_cbranch_scc0 .LBB0_2065
	s_and_b64 vcc, exec, s[18:19]
	s_cbranch_vccz .LBB0_2068
	s_barrier

.Llsb_skip_19:
.LBB0_2240:
	ds_read_b128 v[128:131], v212
	ds_read_b128 v[132:135], v212 offset:1024
	ds_read_b128 v[136:139], v212 offset:2048
	ds_read_b128 v[140:143], v212 offset:3072
	ds_read_b128 v[144:147], v213
	ds_read_b128 v[148:151], v213 offset:1024
	ds_read_b128 v[152:155], v213 offset:2048
	ds_read_b128 v[156:159], v213 offset:3072
	s_add_u32 s24, s22, 0xfffc0080
	s_addc_u32 s25, s23, -1
	s_cmp_eq_u32 s56, 12
	s_cselect_b32 s27, s15, s25
	s_cselect_b32 s26, s52, s24
	s_cselect_b32 s25, s13, s55
	s_cselect_b32 s24, s53, s54
	v_lshl_add_u64 v[202:203], s[22:23], 0, v[182:183]
	s_add_i32 m0, s30, 0xc000
	ds_read_b128 v[160:163], v214
	ds_read_b128 v[164:167], v214 offset:1024
	ds_read_b128 v[168:171], v214 offset:2048
	ds_read_b128 v[172:175], v214 offset:3072
	ds_read_b128 v[190:193], v214 offset:4096
	ds_read_b128 v[194:197], v214 offset:5120
	ds_read_b128 v[198:201], v214 offset:6144
	ds_read_b128 v[216:219], v214 offset:7168
	global_load_lds_dwordx4 v[202:203], off
	v_lshl_add_u64 v[202:203], s[22:23], 0, v[184:185]
	s_add_i32 m0, s30, 0xe000
	s_nop 0
	global_load_lds_dwordx4 v[202:203], off
	s_waitcnt vmcnt(8)
	s_waitcnt lgkmcnt(0)
	s_barrier
	s_setprio 1
	s_waitcnt lgkmcnt(0)
	v_mfma_f32_16x16x32_bf16 v[124:127], v[128:131], v[160:163], v[124:127]
	v_mfma_f32_16x16x32_bf16 v[120:123], v[136:139], v[160:163], v[120:123]
	v_mfma_f32_16x16x32_bf16 v[112:115], v[128:131], v[168:171], v[112:115]
	v_mfma_f32_16x16x32_bf16 v[104:107], v[136:139], v[168:171], v[104:107]
	v_mfma_f32_16x16x32_bf16 v[96:99], v[128:131], v[190:193], v[96:99]
	v_mfma_f32_16x16x32_bf16 v[88:91], v[136:139], v[190:193], v[88:91]
	v_mfma_f32_16x16x32_bf16 v[84:87], v[128:131], v[198:201], v[84:87]
	v_mfma_f32_16x16x32_bf16 v[76:79], v[136:139], v[198:201], v[76:79]
	v_mfma_f32_16x16x32_bf16 v[124:127], v[132:135], v[164:167], v[124:127]
	v_mfma_f32_16x16x32_bf16 v[120:123], v[140:143], v[164:167], v[120:123]
	v_mfma_f32_16x16x32_bf16 v[112:115], v[132:135], v[172:175], v[112:115]
	v_mfma_f32_16x16x32_bf16 v[104:107], v[140:143], v[172:175], v[104:107]
	v_mfma_f32_16x16x32_bf16 v[96:99], v[132:135], v[194:197], v[96:99]
	v_mfma_f32_16x16x32_bf16 v[88:91], v[140:143], v[194:197], v[88:91]
	v_mfma_f32_16x16x32_bf16 v[84:87], v[132:135], v[216:219], v[84:87]
	v_mfma_f32_16x16x32_bf16 v[76:79], v[140:143], v[216:219], v[76:79]
	s_setprio 0
	s_setprio 1
	v_mfma_f32_16x16x32_bf16 v[116:119], v[144:147], v[160:163], v[116:119]
	v_mfma_f32_16x16x32_bf16 v[108:111], v[152:155], v[160:163], v[108:111]
	v_mfma_f32_16x16x32_bf16 v[100:103], v[144:147], v[168:171], v[100:103]
	v_mfma_f32_16x16x32_bf16 v[92:95], v[152:155], v[168:171], v[92:95]
	v_mfma_f32_16x16x32_bf16 v[80:83], v[144:147], v[190:193], v[80:83]
	v_mfma_f32_16x16x32_bf16 v[72:75], v[152:155], v[190:193], v[72:75]
	v_mfma_f32_16x16x32_bf16 v[68:71], v[144:147], v[198:201], v[68:71]
	v_mfma_f32_16x16x32_bf16 v[64:67], v[152:155], v[198:201], v[64:67]
	v_mfma_f32_16x16x32_bf16 v[116:119], v[148:151], v[164:167], v[116:119]
	v_mfma_f32_16x16x32_bf16 v[108:111], v[156:159], v[164:167], v[108:111]
	v_mfma_f32_16x16x32_bf16 v[100:103], v[148:151], v[172:175], v[100:103]
	v_mfma_f32_16x16x32_bf16 v[92:95], v[156:159], v[172:175], v[92:95]
	v_mfma_f32_16x16x32_bf16 v[80:83], v[148:151], v[194:197], v[80:83]
	v_mfma_f32_16x16x32_bf16 v[72:75], v[156:159], v[194:197], v[72:75]
	v_mfma_f32_16x16x32_bf16 v[68:71], v[148:151], v[216:219], v[68:71]
	v_mfma_f32_16x16x32_bf16 v[64:67], v[156:159], v[216:219], v[64:67]
	s_setprio 0
	s_barrier
	s_add_i32 s57, s45, s29
	v_lshl_add_u64 v[202:203], s[24:25], 0, v[176:177]
	s_mov_b32 m0, s57
	ds_read_b128 v[160:163], v214 offset:16384
	ds_read_b128 v[164:167], v214 offset:17408
	ds_read_b128 v[168:171], v214 offset:18432
	ds_read_b128 v[172:175], v214 offset:19456
	ds_read_b128 v[190:193], v214 offset:20480
	ds_read_b128 v[194:197], v214 offset:21504
	ds_read_b128 v[198:201], v214 offset:22528
	ds_read_b128 v[216:219], v214 offset:23552
	global_load_lds_dwordx4 v[202:203], off
	s_add_i32 m0, s57, 0x2000
	s_add_u32 s58, s24, 0x40000
	v_lshl_add_u64 v[220:221], s[24:25], 0, v[178:179]
	s_addc_u32 s59, s25, 0
	s_add_i32 s57, s46, s29
	global_load_lds_dwordx4 v[220:221], off
	v_lshl_add_u64 v[222:223], s[58:59], 0, v[176:177]
	s_mov_b32 m0, s57
	v_lshl_add_u64 v[224:225], s[26:27], 0, v[178:179]
	global_load_lds_dwordx4 v[222:223], off
	v_lshl_add_u64 v[222:223], s[58:59], 0, v[178:179]
	s_add_i32 m0, s57, 0x2000
	s_nop 0
	global_load_lds_dwordx4 v[222:223], off
	v_lshl_add_u64 v[222:223], s[26:27], 0, v[176:177]
	s_mov_b32 m0, s30
	s_nop 0
	global_load_lds_dwordx4 v[222:223], off
	s_mov_b32 m0, s31
	s_nop 0
	global_load_lds_dwordx4 v[224:225], off
	s_waitcnt vmcnt(8)
	s_waitcnt lgkmcnt(0)
	s_barrier
	s_setprio 1
	s_waitcnt lgkmcnt(0)
	v_mfma_f32_16x16x32_bf16 v[60:63], v[128:131], v[160:163], v[60:63]
	v_mfma_f32_16x16x32_bf16 v[56:59], v[136:139], v[160:163], v[56:59]
	v_mfma_f32_16x16x32_bf16 v[48:51], v[128:131], v[168:171], v[48:51]
	v_mfma_f32_16x16x32_bf16 v[40:43], v[136:139], v[168:171], v[40:43]
	v_mfma_f32_16x16x32_bf16 v[32:35], v[128:131], v[190:193], v[32:35]
	v_mfma_f32_16x16x32_bf16 v[24:27], v[136:139], v[190:193], v[24:27]
	v_mfma_f32_16x16x32_bf16 v[20:23], v[128:131], v[198:201], v[20:23]
	v_mfma_f32_16x16x32_bf16 v[12:15], v[136:139], v[198:201], v[12:15]
	v_mfma_f32_16x16x32_bf16 v[60:63], v[132:135], v[164:167], v[60:63]
	v_mfma_f32_16x16x32_bf16 v[56:59], v[140:143], v[164:167], v[56:59]
	v_mfma_f32_16x16x32_bf16 v[48:51], v[132:135], v[172:175], v[48:51]
	v_mfma_f32_16x16x32_bf16 v[40:43], v[140:143], v[172:175], v[40:43]
	v_mfma_f32_16x16x32_bf16 v[32:35], v[132:135], v[194:197], v[32:35]
	v_mfma_f32_16x16x32_bf16 v[24:27], v[140:143], v[194:197], v[24:27]
	v_mfma_f32_16x16x32_bf16 v[20:23], v[132:135], v[216:219], v[20:23]
	v_mfma_f32_16x16x32_bf16 v[12:15], v[140:143], v[216:219], v[12:15]
	s_setprio 0
	s_setprio 1
	v_mfma_f32_16x16x32_bf16 v[52:55], v[144:147], v[160:163], v[52:55]
	v_mfma_f32_16x16x32_bf16 v[44:47], v[152:155], v[160:163], v[44:47]
	v_mfma_f32_16x16x32_bf16 v[36:39], v[144:147], v[168:171], v[36:39]
	v_mfma_f32_16x16x32_bf16 v[28:31], v[152:155], v[168:171], v[28:31]
	v_mfma_f32_16x16x32_bf16 v[16:19], v[144:147], v[190:193], v[16:19]
	v_mfma_f32_16x16x32_bf16 v[8:11], v[152:155], v[190:193], v[8:11]
	v_mfma_f32_16x16x32_bf16 v[4:7], v[144:147], v[198:201], v[4:7]
	v_mfma_f32_16x16x32_bf16 v[0:3], v[152:155], v[198:201], v[0:3]
	v_mfma_f32_16x16x32_bf16 v[52:55], v[148:151], v[164:167], v[52:55]
	v_mfma_f32_16x16x32_bf16 v[44:47], v[156:159], v[164:167], v[44:47]
	v_mfma_f32_16x16x32_bf16 v[36:39], v[148:151], v[172:175], v[36:39]
	v_mfma_f32_16x16x32_bf16 v[28:31], v[156:159], v[172:175], v[28:31]
	v_mfma_f32_16x16x32_bf16 v[16:19], v[148:151], v[194:197], v[16:19]
	v_mfma_f32_16x16x32_bf16 v[8:11], v[156:159], v[194:197], v[8:11]
	v_mfma_f32_16x16x32_bf16 v[4:7], v[148:151], v[216:219], v[4:7]
	v_mfma_f32_16x16x32_bf16 v[0:3], v[156:159], v[216:219], v[0:3]
	s_setprio 0
	s_barrier
	s_add_i32 s57, 0, 0x18000
	s_add_i32 s58, 0, 0x1c000
	v_add_u32_e32 v140, s57, v210
	v_add_u32_e32 v156, s58, v210
	ds_read_b128 v[128:131], v140
	ds_read_b128 v[132:135], v140 offset:1024
	ds_read_b128 v[136:139], v140 offset:2048
	ds_read_b128 v[140:143], v140 offset:3072
	ds_read_b128 v[144:147], v156
	ds_read_b128 v[148:151], v156 offset:1024
	ds_read_b128 v[152:155], v156 offset:2048
	ds_read_b128 v[156:159], v156 offset:3072
	s_add_u32 s26, s26, 0x40000
	s_addc_u32 s27, s27, 0
	s_mov_b32 m0, s34
	v_lshl_add_u64 v[226:227], s[26:27], 0, v[176:177]
	ds_read_b128 v[160:163], v214 offset:32768
	ds_read_b128 v[164:167], v214 offset:33792
	ds_read_b128 v[168:171], v214 offset:34816
	ds_read_b128 v[172:175], v214 offset:35840
	ds_read_b128 v[190:193], v214 offset:36864
	ds_read_b128 v[194:197], v214 offset:37888
	ds_read_b128 v[198:201], v214 offset:38912
	ds_read_b128 v[216:219], v214 offset:39936
	global_load_lds_dwordx4 v[226:227], off
	v_lshl_add_u64 v[226:227], s[26:27], 0, v[178:179]
	s_mov_b32 m0, s35
	s_nop 0
	global_load_lds_dwordx4 v[226:227], off
	s_waitcnt vmcnt(8)
	s_waitcnt lgkmcnt(0)
	s_barrier
	s_setprio 1
	s_waitcnt lgkmcnt(0)
	v_mfma_f32_16x16x32_bf16 v[124:127], v[128:131], v[160:163], v[124:127]
	v_mfma_f32_16x16x32_bf16 v[120:123], v[136:139], v[160:163], v[120:123]
	v_mfma_f32_16x16x32_bf16 v[112:115], v[128:131], v[168:171], v[112:115]
	v_mfma_f32_16x16x32_bf16 v[104:107], v[136:139], v[168:171], v[104:107]
	v_mfma_f32_16x16x32_bf16 v[96:99], v[128:131], v[190:193], v[96:99]
	v_mfma_f32_16x16x32_bf16 v[88:91], v[136:139], v[190:193], v[88:91]
	v_mfma_f32_16x16x32_bf16 v[84:87], v[128:131], v[198:201], v[84:87]
	v_mfma_f32_16x16x32_bf16 v[76:79], v[136:139], v[198:201], v[76:79]
	v_mfma_f32_16x16x32_bf16 v[124:127], v[132:135], v[164:167], v[124:127]
	v_mfma_f32_16x16x32_bf16 v[120:123], v[140:143], v[164:167], v[120:123]
	v_mfma_f32_16x16x32_bf16 v[112:115], v[132:135], v[172:175], v[112:115]
	v_mfma_f32_16x16x32_bf16 v[104:107], v[140:143], v[172:175], v[104:107]
	v_mfma_f32_16x16x32_bf16 v[96:99], v[132:135], v[194:197], v[96:99]
	v_mfma_f32_16x16x32_bf16 v[88:91], v[140:143], v[194:197], v[88:91]
	v_mfma_f32_16x16x32_bf16 v[84:87], v[132:135], v[216:219], v[84:87]
	v_mfma_f32_16x16x32_bf16 v[76:79], v[140:143], v[216:219], v[76:79]
	s_setprio 0
	s_setprio 1
	v_mfma_f32_16x16x32_bf16 v[116:119], v[144:147], v[160:163], v[116:119]
	v_mfma_f32_16x16x32_bf16 v[108:111], v[152:155], v[160:163], v[108:111]
	v_mfma_f32_16x16x32_bf16 v[100:103], v[144:147], v[168:171], v[100:103]
	v_mfma_f32_16x16x32_bf16 v[92:95], v[152:155], v[168:171], v[92:95]
	v_mfma_f32_16x16x32_bf16 v[80:83], v[144:147], v[190:193], v[80:83]
	v_mfma_f32_16x16x32_bf16 v[72:75], v[152:155], v[190:193], v[72:75]
	v_mfma_f32_16x16x32_bf16 v[68:71], v[144:147], v[198:201], v[68:71]
	v_mfma_f32_16x16x32_bf16 v[64:67], v[152:155], v[198:201], v[64:67]
	v_mfma_f32_16x16x32_bf16 v[116:119], v[148:151], v[164:167], v[116:119]
	v_mfma_f32_16x16x32_bf16 v[108:111], v[156:159], v[164:167], v[108:111]
	v_mfma_f32_16x16x32_bf16 v[100:103], v[148:151], v[172:175], v[100:103]
	v_mfma_f32_16x16x32_bf16 v[92:95], v[156:159], v[172:175], v[92:95]
	v_mfma_f32_16x16x32_bf16 v[80:83], v[148:151], v[194:197], v[80:83]
	v_mfma_f32_16x16x32_bf16 v[72:75], v[156:159], v[194:197], v[72:75]
	v_mfma_f32_16x16x32_bf16 v[68:71], v[148:151], v[216:219], v[68:71]
	v_mfma_f32_16x16x32_bf16 v[64:67], v[156:159], v[216:219], v[64:67]
	s_setprio 0
	s_barrier
	s_add_i32 s26, s57, s29
	v_lshl_add_u64 v[202:203], v[202:203], 0, s[8:9]
	s_mov_b32 m0, s26
	ds_read_b128 v[160:163], v214 offset:49152
	ds_read_b128 v[164:167], v214 offset:50176
	ds_read_b128 v[168:171], v214 offset:51200
	ds_read_b128 v[172:175], v214 offset:52224
	ds_read_b128 v[190:193], v214 offset:53248
	ds_read_b128 v[194:197], v214 offset:54272
	ds_read_b128 v[198:201], v214 offset:55296
	ds_read_b128 v[216:219], v214 offset:56320
	global_load_lds_dwordx4 v[202:203], off
	s_add_i32 m0, s26, 0x2000
	s_add_u32 s24, s24, 0x40080
	v_lshl_add_u64 v[202:203], v[220:221], 0, s[8:9]
	s_addc_u32 s25, s25, 0
	s_add_i32 s26, s58, s29
	global_load_lds_dwordx4 v[202:203], off
	v_lshl_add_u64 v[202:203], s[24:25], 0, v[176:177]
	s_mov_b32 m0, s26
	s_nop 0
	global_load_lds_dwordx4 v[202:203], off
	v_lshl_add_u64 v[202:203], s[24:25], 0, v[178:179]
	s_add_i32 m0, s26, 0x2000
	s_nop 0
	global_load_lds_dwordx4 v[202:203], off
	v_lshl_add_u64 v[202:203], v[222:223], 0, s[8:9]
	s_mov_b32 m0, s42
	s_nop 0
	global_load_lds_dwordx4 v[202:203], off
	v_lshl_add_u64 v[202:203], v[224:225], 0, s[8:9]
	s_mov_b32 m0, s43
	s_nop 0
	global_load_lds_dwordx4 v[202:203], off
	s_waitcnt vmcnt(8)
	s_waitcnt lgkmcnt(0)
	s_barrier
	s_setprio 1
	s_waitcnt lgkmcnt(0)
	v_mfma_f32_16x16x32_bf16 v[60:63], v[128:131], v[160:163], v[60:63]
	v_mfma_f32_16x16x32_bf16 v[56:59], v[136:139], v[160:163], v[56:59]
	v_mfma_f32_16x16x32_bf16 v[48:51], v[128:131], v[168:171], v[48:51]
	v_mfma_f32_16x16x32_bf16 v[40:43], v[136:139], v[168:171], v[40:43]
	v_mfma_f32_16x16x32_bf16 v[32:35], v[128:131], v[190:193], v[32:35]
	v_mfma_f32_16x16x32_bf16 v[24:27], v[136:139], v[190:193], v[24:27]
	v_mfma_f32_16x16x32_bf16 v[20:23], v[128:131], v[198:201], v[20:23]
	v_mfma_f32_16x16x32_bf16 v[12:15], v[136:139], v[198:201], v[12:15]
	v_mfma_f32_16x16x32_bf16 v[60:63], v[132:135], v[164:167], v[60:63]
	v_mfma_f32_16x16x32_bf16 v[56:59], v[140:143], v[164:167], v[56:59]
	v_mfma_f32_16x16x32_bf16 v[48:51], v[132:135], v[172:175], v[48:51]
	v_mfma_f32_16x16x32_bf16 v[40:43], v[140:143], v[172:175], v[40:43]
	v_mfma_f32_16x16x32_bf16 v[32:35], v[132:135], v[194:197], v[32:35]
	v_mfma_f32_16x16x32_bf16 v[24:27], v[140:143], v[194:197], v[24:27]
	v_mfma_f32_16x16x32_bf16 v[20:23], v[132:135], v[216:219], v[20:23]
	v_mfma_f32_16x16x32_bf16 v[12:15], v[140:143], v[216:219], v[12:15]
	s_setprio 0
	s_setprio 1
	v_mfma_f32_16x16x32_bf16 v[52:55], v[144:147], v[160:163], v[52:55]
	v_mfma_f32_16x16x32_bf16 v[44:47], v[152:155], v[160:163], v[44:47]
	v_mfma_f32_16x16x32_bf16 v[36:39], v[144:147], v[168:171], v[36:39]
	v_mfma_f32_16x16x32_bf16 v[28:31], v[152:155], v[168:171], v[28:31]
	v_mfma_f32_16x16x32_bf16 v[16:19], v[144:147], v[190:193], v[16:19]
	v_mfma_f32_16x16x32_bf16 v[8:11], v[152:155], v[190:193], v[8:11]
	v_mfma_f32_16x16x32_bf16 v[4:7], v[144:147], v[198:201], v[4:7]
	v_mfma_f32_16x16x32_bf16 v[0:3], v[152:155], v[198:201], v[0:3]
	v_mfma_f32_16x16x32_bf16 v[52:55], v[148:151], v[164:167], v[52:55]
	v_mfma_f32_16x16x32_bf16 v[44:47], v[156:159], v[164:167], v[44:47]
	v_mfma_f32_16x16x32_bf16 v[36:39], v[148:151], v[172:175], v[36:39]
	v_mfma_f32_16x16x32_bf16 v[28:31], v[156:159], v[172:175], v[28:31]
	v_mfma_f32_16x16x32_bf16 v[16:19], v[148:151], v[194:197], v[16:19]
	v_mfma_f32_16x16x32_bf16 v[8:11], v[156:159], v[194:197], v[8:11]
	v_mfma_f32_16x16x32_bf16 v[4:7], v[148:151], v[216:219], v[4:7]
	v_mfma_f32_16x16x32_bf16 v[0:3], v[156:159], v[216:219], v[0:3]
	s_add_i32 s56, s56, 2
	s_add_u32 s22, s22, 0x100
	s_addc_u32 s23, s23, 0
	s_add_u32 s54, s54, 0x100
	s_addc_u32 s55, s55, 0
	s_cmp_gt_u32 s56, 13
	s_setprio 0
	s_barrier
	s_cbranch_scc0 .LBB0_2240
	s_and_b64 vcc, exec, s[10:11]
	s_cbranch_vccz .LBB0_2243
	s_barrier

.Llsb_skip_21:
.LBB0_2476:
	ds_read_b128 v[128:131], v212
	ds_read_b128 v[132:135], v212 offset:1024
	ds_read_b128 v[136:139], v212 offset:2048
	ds_read_b128 v[140:143], v212 offset:3072
	ds_read_b128 v[144:147], v213
	ds_read_b128 v[148:151], v213 offset:1024
	ds_read_b128 v[152:155], v213 offset:2048
	ds_read_b128 v[156:159], v213 offset:3072
	s_add_u32 s18, s16, 0xfff50080
	s_addc_u32 s19, s17, -1
	s_cmp_eq_u32 s52, 40
	s_cselect_b32 s21, s5, s19
	s_cselect_b32 s20, s4, s18
	s_cselect_b32 s19, s15, s51
	s_cselect_b32 s18, s14, s50
	v_lshl_add_u64 v[202:203], s[16:17], 0, v[182:183]
	s_add_i32 m0, s23, 0xc000
	ds_read_b128 v[160:163], v214
	ds_read_b128 v[164:167], v214 offset:1024
	ds_read_b128 v[168:171], v214 offset:2048
	ds_read_b128 v[172:175], v214 offset:3072
	ds_read_b128 v[190:193], v214 offset:4096
	ds_read_b128 v[194:197], v214 offset:5120
	ds_read_b128 v[198:201], v214 offset:6144
	ds_read_b128 v[216:219], v214 offset:7168
	global_load_lds_dwordx4 v[202:203], off
	v_lshl_add_u64 v[202:203], s[16:17], 0, v[184:185]
	s_add_i32 m0, s23, 0xe000
	s_nop 0
	global_load_lds_dwordx4 v[202:203], off
	s_waitcnt vmcnt(8)
	s_waitcnt lgkmcnt(0)
	s_barrier
	s_setprio 1
	s_waitcnt lgkmcnt(0)
	v_mfma_f32_16x16x32_bf16 v[124:127], v[128:131], v[160:163], v[124:127]
	v_mfma_f32_16x16x32_bf16 v[120:123], v[136:139], v[160:163], v[120:123]
	v_mfma_f32_16x16x32_bf16 v[112:115], v[128:131], v[168:171], v[112:115]
	v_mfma_f32_16x16x32_bf16 v[104:107], v[136:139], v[168:171], v[104:107]
	v_mfma_f32_16x16x32_bf16 v[96:99], v[128:131], v[190:193], v[96:99]
	v_mfma_f32_16x16x32_bf16 v[88:91], v[136:139], v[190:193], v[88:91]
	v_mfma_f32_16x16x32_bf16 v[84:87], v[128:131], v[198:201], v[84:87]
	v_mfma_f32_16x16x32_bf16 v[76:79], v[136:139], v[198:201], v[76:79]
	v_mfma_f32_16x16x32_bf16 v[124:127], v[132:135], v[164:167], v[124:127]
	v_mfma_f32_16x16x32_bf16 v[120:123], v[140:143], v[164:167], v[120:123]
	v_mfma_f32_16x16x32_bf16 v[112:115], v[132:135], v[172:175], v[112:115]
	v_mfma_f32_16x16x32_bf16 v[104:107], v[140:143], v[172:175], v[104:107]
	v_mfma_f32_16x16x32_bf16 v[96:99], v[132:135], v[194:197], v[96:99]
	v_mfma_f32_16x16x32_bf16 v[88:91], v[140:143], v[194:197], v[88:91]
	v_mfma_f32_16x16x32_bf16 v[84:87], v[132:135], v[216:219], v[84:87]
	v_mfma_f32_16x16x32_bf16 v[76:79], v[140:143], v[216:219], v[76:79]
	s_setprio 0
	s_setprio 1
	v_mfma_f32_16x16x32_bf16 v[116:119], v[144:147], v[160:163], v[116:119]
	v_mfma_f32_16x16x32_bf16 v[108:111], v[152:155], v[160:163], v[108:111]
	v_mfma_f32_16x16x32_bf16 v[100:103], v[144:147], v[168:171], v[100:103]
	v_mfma_f32_16x16x32_bf16 v[92:95], v[152:155], v[168:171], v[92:95]
	v_mfma_f32_16x16x32_bf16 v[80:83], v[144:147], v[190:193], v[80:83]
	v_mfma_f32_16x16x32_bf16 v[72:75], v[152:155], v[190:193], v[72:75]
	v_mfma_f32_16x16x32_bf16 v[68:71], v[144:147], v[198:201], v[68:71]
	v_mfma_f32_16x16x32_bf16 v[64:67], v[152:155], v[198:201], v[64:67]
	v_mfma_f32_16x16x32_bf16 v[116:119], v[148:151], v[164:167], v[116:119]
	v_mfma_f32_16x16x32_bf16 v[108:111], v[156:159], v[164:167], v[108:111]
	v_mfma_f32_16x16x32_bf16 v[100:103], v[148:151], v[172:175], v[100:103]
	v_mfma_f32_16x16x32_bf16 v[92:95], v[156:159], v[172:175], v[92:95]
	v_mfma_f32_16x16x32_bf16 v[80:83], v[148:151], v[194:197], v[80:83]
	v_mfma_f32_16x16x32_bf16 v[72:75], v[156:159], v[194:197], v[72:75]
	v_mfma_f32_16x16x32_bf16 v[68:71], v[148:151], v[216:219], v[68:71]
	v_mfma_f32_16x16x32_bf16 v[64:67], v[156:159], v[216:219], v[64:67]
	s_setprio 0
	s_barrier
	s_add_i32 s53, s35, s22
	v_lshl_add_u64 v[202:203], s[18:19], 0, v[176:177]
	s_mov_b32 m0, s53
	ds_read_b128 v[160:163], v214 offset:16384
	ds_read_b128 v[164:167], v214 offset:17408
	ds_read_b128 v[168:171], v214 offset:18432
	ds_read_b128 v[172:175], v214 offset:19456
	ds_read_b128 v[190:193], v214 offset:20480
	ds_read_b128 v[194:197], v214 offset:21504
	ds_read_b128 v[198:201], v214 offset:22528
	ds_read_b128 v[216:219], v214 offset:23552
	global_load_lds_dwordx4 v[202:203], off
	s_add_i32 m0, s53, 0x2000
	s_add_u32 s54, s18, 0xb0000
	v_lshl_add_u64 v[220:221], s[18:19], 0, v[178:179]
	s_addc_u32 s55, s19, 0
	s_add_i32 s53, s36, s22
	global_load_lds_dwordx4 v[220:221], off
	v_lshl_add_u64 v[222:223], s[54:55], 0, v[176:177]
	s_mov_b32 m0, s53
	v_lshl_add_u64 v[224:225], s[20:21], 0, v[178:179]
	global_load_lds_dwordx4 v[222:223], off
	v_lshl_add_u64 v[222:223], s[54:55], 0, v[178:179]
	s_add_i32 m0, s53, 0x2000
	s_nop 0
	global_load_lds_dwordx4 v[222:223], off
	v_lshl_add_u64 v[222:223], s[20:21], 0, v[176:177]
	s_mov_b32 m0, s23
	s_nop 0
	global_load_lds_dwordx4 v[222:223], off
	s_mov_b32 m0, s24
	s_nop 0
	global_load_lds_dwordx4 v[224:225], off
	s_waitcnt vmcnt(8)
	s_waitcnt lgkmcnt(0)
	s_barrier
	s_setprio 1
	s_waitcnt lgkmcnt(0)
	v_mfma_f32_16x16x32_bf16 v[60:63], v[128:131], v[160:163], v[60:63]
	v_mfma_f32_16x16x32_bf16 v[56:59], v[136:139], v[160:163], v[56:59]
	v_mfma_f32_16x16x32_bf16 v[48:51], v[128:131], v[168:171], v[48:51]
	v_mfma_f32_16x16x32_bf16 v[40:43], v[136:139], v[168:171], v[40:43]
	v_mfma_f32_16x16x32_bf16 v[32:35], v[128:131], v[190:193], v[32:35]
	v_mfma_f32_16x16x32_bf16 v[24:27], v[136:139], v[190:193], v[24:27]
	v_mfma_f32_16x16x32_bf16 v[20:23], v[128:131], v[198:201], v[20:23]
	v_mfma_f32_16x16x32_bf16 v[12:15], v[136:139], v[198:201], v[12:15]
	v_mfma_f32_16x16x32_bf16 v[60:63], v[132:135], v[164:167], v[60:63]
	v_mfma_f32_16x16x32_bf16 v[56:59], v[140:143], v[164:167], v[56:59]
	v_mfma_f32_16x16x32_bf16 v[48:51], v[132:135], v[172:175], v[48:51]
	v_mfma_f32_16x16x32_bf16 v[40:43], v[140:143], v[172:175], v[40:43]
	v_mfma_f32_16x16x32_bf16 v[32:35], v[132:135], v[194:197], v[32:35]
	v_mfma_f32_16x16x32_bf16 v[24:27], v[140:143], v[194:197], v[24:27]
	v_mfma_f32_16x16x32_bf16 v[20:23], v[132:135], v[216:219], v[20:23]
	v_mfma_f32_16x16x32_bf16 v[12:15], v[140:143], v[216:219], v[12:15]
	s_setprio 0
	s_setprio 1
	v_mfma_f32_16x16x32_bf16 v[52:55], v[144:147], v[160:163], v[52:55]
	v_mfma_f32_16x16x32_bf16 v[44:47], v[152:155], v[160:163], v[44:47]
	v_mfma_f32_16x16x32_bf16 v[36:39], v[144:147], v[168:171], v[36:39]
	v_mfma_f32_16x16x32_bf16 v[28:31], v[152:155], v[168:171], v[28:31]
	v_mfma_f32_16x16x32_bf16 v[16:19], v[144:147], v[190:193], v[16:19]
	v_mfma_f32_16x16x32_bf16 v[8:11], v[152:155], v[190:193], v[8:11]
	v_mfma_f32_16x16x32_bf16 v[4:7], v[144:147], v[198:201], v[4:7]
	v_mfma_f32_16x16x32_bf16 v[0:3], v[152:155], v[198:201], v[0:3]
	v_mfma_f32_16x16x32_bf16 v[52:55], v[148:151], v[164:167], v[52:55]
	v_mfma_f32_16x16x32_bf16 v[44:47], v[156:159], v[164:167], v[44:47]
	v_mfma_f32_16x16x32_bf16 v[36:39], v[148:151], v[172:175], v[36:39]
	v_mfma_f32_16x16x32_bf16 v[28:31], v[156:159], v[172:175], v[28:31]
	v_mfma_f32_16x16x32_bf16 v[16:19], v[148:151], v[194:197], v[16:19]
	v_mfma_f32_16x16x32_bf16 v[8:11], v[156:159], v[194:197], v[8:11]
	v_mfma_f32_16x16x32_bf16 v[4:7], v[148:151], v[216:219], v[4:7]
	v_mfma_f32_16x16x32_bf16 v[0:3], v[156:159], v[216:219], v[0:3]
	s_setprio 0
	s_barrier
	s_add_i32 s53, 0, 0x18000
	s_add_i32 s54, 0, 0x1c000
	v_add_u32_e32 v140, s53, v210
	v_add_u32_e32 v156, s54, v210
	ds_read_b128 v[128:131], v140
	ds_read_b128 v[132:135], v140 offset:1024
	ds_read_b128 v[136:139], v140 offset:2048
	ds_read_b128 v[140:143], v140 offset:3072
	ds_read_b128 v[144:147], v156
	ds_read_b128 v[148:151], v156 offset:1024
	ds_read_b128 v[152:155], v156 offset:2048
	ds_read_b128 v[156:159], v156 offset:3072
	s_add_u32 s20, s20, 0xb0000
	s_addc_u32 s21, s21, 0
	s_mov_b32 m0, s25
	v_lshl_add_u64 v[226:227], s[20:21], 0, v[176:177]
	ds_read_b128 v[160:163], v214 offset:32768
	ds_read_b128 v[164:167], v214 offset:33792
	ds_read_b128 v[168:171], v214 offset:34816
	ds_read_b128 v[172:175], v214 offset:35840
	ds_read_b128 v[190:193], v214 offset:36864
	ds_read_b128 v[194:197], v214 offset:37888
	ds_read_b128 v[198:201], v214 offset:38912
	ds_read_b128 v[216:219], v214 offset:39936
	global_load_lds_dwordx4 v[226:227], off
	v_lshl_add_u64 v[226:227], s[20:21], 0, v[178:179]
	s_mov_b32 m0, s26
	s_nop 0
	global_load_lds_dwordx4 v[226:227], off
	s_waitcnt vmcnt(8)
	s_waitcnt lgkmcnt(0)
	s_barrier
	s_setprio 1
	s_waitcnt lgkmcnt(0)
	v_mfma_f32_16x16x32_bf16 v[124:127], v[128:131], v[160:163], v[124:127]
	v_mfma_f32_16x16x32_bf16 v[120:123], v[136:139], v[160:163], v[120:123]
	v_mfma_f32_16x16x32_bf16 v[112:115], v[128:131], v[168:171], v[112:115]
	v_mfma_f32_16x16x32_bf16 v[104:107], v[136:139], v[168:171], v[104:107]
	v_mfma_f32_16x16x32_bf16 v[96:99], v[128:131], v[190:193], v[96:99]
	v_mfma_f32_16x16x32_bf16 v[88:91], v[136:139], v[190:193], v[88:91]
	v_mfma_f32_16x16x32_bf16 v[84:87], v[128:131], v[198:201], v[84:87]
	v_mfma_f32_16x16x32_bf16 v[76:79], v[136:139], v[198:201], v[76:79]
	v_mfma_f32_16x16x32_bf16 v[124:127], v[132:135], v[164:167], v[124:127]
	v_mfma_f32_16x16x32_bf16 v[120:123], v[140:143], v[164:167], v[120:123]
	v_mfma_f32_16x16x32_bf16 v[112:115], v[132:135], v[172:175], v[112:115]
	v_mfma_f32_16x16x32_bf16 v[104:107], v[140:143], v[172:175], v[104:107]
	v_mfma_f32_16x16x32_bf16 v[96:99], v[132:135], v[194:197], v[96:99]
	v_mfma_f32_16x16x32_bf16 v[88:91], v[140:143], v[194:197], v[88:91]
	v_mfma_f32_16x16x32_bf16 v[84:87], v[132:135], v[216:219], v[84:87]
	v_mfma_f32_16x16x32_bf16 v[76:79], v[140:143], v[216:219], v[76:79]
	s_setprio 0
	s_setprio 1
	v_mfma_f32_16x16x32_bf16 v[116:119], v[144:147], v[160:163], v[116:119]
	v_mfma_f32_16x16x32_bf16 v[108:111], v[152:155], v[160:163], v[108:111]
	v_mfma_f32_16x16x32_bf16 v[100:103], v[144:147], v[168:171], v[100:103]
	v_mfma_f32_16x16x32_bf16 v[92:95], v[152:155], v[168:171], v[92:95]
	v_mfma_f32_16x16x32_bf16 v[80:83], v[144:147], v[190:193], v[80:83]
	v_mfma_f32_16x16x32_bf16 v[72:75], v[152:155], v[190:193], v[72:75]
	v_mfma_f32_16x16x32_bf16 v[68:71], v[144:147], v[198:201], v[68:71]
	v_mfma_f32_16x16x32_bf16 v[64:67], v[152:155], v[198:201], v[64:67]
	v_mfma_f32_16x16x32_bf16 v[116:119], v[148:151], v[164:167], v[116:119]
	v_mfma_f32_16x16x32_bf16 v[108:111], v[156:159], v[164:167], v[108:111]
	v_mfma_f32_16x16x32_bf16 v[100:103], v[148:151], v[172:175], v[100:103]
	v_mfma_f32_16x16x32_bf16 v[92:95], v[156:159], v[172:175], v[92:95]
	v_mfma_f32_16x16x32_bf16 v[80:83], v[148:151], v[194:197], v[80:83]
	v_mfma_f32_16x16x32_bf16 v[72:75], v[156:159], v[194:197], v[72:75]
	v_mfma_f32_16x16x32_bf16 v[68:71], v[148:151], v[216:219], v[68:71]
	v_mfma_f32_16x16x32_bf16 v[64:67], v[156:159], v[216:219], v[64:67]
	s_setprio 0
	s_barrier
	s_add_i32 s20, s53, s22
	v_lshl_add_u64 v[202:203], v[202:203], 0, s[10:11]
	s_mov_b32 m0, s20
	ds_read_b128 v[160:163], v214 offset:49152
	ds_read_b128 v[164:167], v214 offset:50176
	ds_read_b128 v[168:171], v214 offset:51200
	ds_read_b128 v[172:175], v214 offset:52224
	ds_read_b128 v[190:193], v214 offset:53248
	ds_read_b128 v[194:197], v214 offset:54272
	ds_read_b128 v[198:201], v214 offset:55296
	ds_read_b128 v[216:219], v214 offset:56320
	global_load_lds_dwordx4 v[202:203], off
	s_add_i32 m0, s20, 0x2000
	s_add_u32 s18, s18, 0xb0080
	v_lshl_add_u64 v[202:203], v[220:221], 0, s[10:11]
	s_addc_u32 s19, s19, 0
	s_add_i32 s20, s54, s22
	global_load_lds_dwordx4 v[202:203], off
	v_lshl_add_u64 v[202:203], s[18:19], 0, v[176:177]
	s_mov_b32 m0, s20
	s_nop 0
	global_load_lds_dwordx4 v[202:203], off
	v_lshl_add_u64 v[202:203], s[18:19], 0, v[178:179]
	s_add_i32 m0, s20, 0x2000
	s_nop 0
	global_load_lds_dwordx4 v[202:203], off
	v_lshl_add_u64 v[202:203], v[222:223], 0, s[10:11]
	s_mov_b32 m0, s29
	s_nop 0
	global_load_lds_dwordx4 v[202:203], off
	v_lshl_add_u64 v[202:203], v[224:225], 0, s[10:11]
	s_mov_b32 m0, s30
	s_nop 0
	global_load_lds_dwordx4 v[202:203], off
	s_waitcnt vmcnt(8)
	s_waitcnt lgkmcnt(0)
	s_barrier
	s_setprio 1
	s_waitcnt lgkmcnt(0)
	v_mfma_f32_16x16x32_bf16 v[60:63], v[128:131], v[160:163], v[60:63]
	v_mfma_f32_16x16x32_bf16 v[56:59], v[136:139], v[160:163], v[56:59]
	v_mfma_f32_16x16x32_bf16 v[48:51], v[128:131], v[168:171], v[48:51]
	v_mfma_f32_16x16x32_bf16 v[40:43], v[136:139], v[168:171], v[40:43]
	v_mfma_f32_16x16x32_bf16 v[32:35], v[128:131], v[190:193], v[32:35]
	v_mfma_f32_16x16x32_bf16 v[24:27], v[136:139], v[190:193], v[24:27]
	v_mfma_f32_16x16x32_bf16 v[20:23], v[128:131], v[198:201], v[20:23]
	v_mfma_f32_16x16x32_bf16 v[12:15], v[136:139], v[198:201], v[12:15]
	v_mfma_f32_16x16x32_bf16 v[60:63], v[132:135], v[164:167], v[60:63]
	v_mfma_f32_16x16x32_bf16 v[56:59], v[140:143], v[164:167], v[56:59]
	v_mfma_f32_16x16x32_bf16 v[48:51], v[132:135], v[172:175], v[48:51]
	v_mfma_f32_16x16x32_bf16 v[40:43], v[140:143], v[172:175], v[40:43]
	v_mfma_f32_16x16x32_bf16 v[32:35], v[132:135], v[194:197], v[32:35]
	v_mfma_f32_16x16x32_bf16 v[24:27], v[140:143], v[194:197], v[24:27]
	v_mfma_f32_16x16x32_bf16 v[20:23], v[132:135], v[216:219], v[20:23]
	v_mfma_f32_16x16x32_bf16 v[12:15], v[140:143], v[216:219], v[12:15]
	s_setprio 0
	s_setprio 1
	v_mfma_f32_16x16x32_bf16 v[52:55], v[144:147], v[160:163], v[52:55]
	v_mfma_f32_16x16x32_bf16 v[44:47], v[152:155], v[160:163], v[44:47]
	v_mfma_f32_16x16x32_bf16 v[36:39], v[144:147], v[168:171], v[36:39]
	v_mfma_f32_16x16x32_bf16 v[28:31], v[152:155], v[168:171], v[28:31]
	v_mfma_f32_16x16x32_bf16 v[16:19], v[144:147], v[190:193], v[16:19]
	v_mfma_f32_16x16x32_bf16 v[8:11], v[152:155], v[190:193], v[8:11]
	v_mfma_f32_16x16x32_bf16 v[4:7], v[144:147], v[198:201], v[4:7]
	v_mfma_f32_16x16x32_bf16 v[0:3], v[152:155], v[198:201], v[0:3]
	v_mfma_f32_16x16x32_bf16 v[52:55], v[148:151], v[164:167], v[52:55]
	v_mfma_f32_16x16x32_bf16 v[44:47], v[156:159], v[164:167], v[44:47]
	v_mfma_f32_16x16x32_bf16 v[36:39], v[148:151], v[172:175], v[36:39]
	v_mfma_f32_16x16x32_bf16 v[28:31], v[156:159], v[172:175], v[28:31]
	v_mfma_f32_16x16x32_bf16 v[16:19], v[148:151], v[194:197], v[16:19]
	v_mfma_f32_16x16x32_bf16 v[8:11], v[156:159], v[194:197], v[8:11]
	v_mfma_f32_16x16x32_bf16 v[4:7], v[148:151], v[216:219], v[4:7]
	v_mfma_f32_16x16x32_bf16 v[0:3], v[156:159], v[216:219], v[0:3]
	s_add_i32 s52, s52, 2
	s_add_u32 s16, s16, 0x100
	s_addc_u32 s17, s17, 0
	s_add_u32 s50, s50, 0x100
	s_addc_u32 s51, s51, 0
	s_cmp_gt_u32 s52, 41
	s_setprio 0
	s_barrier
	s_cbranch_scc0 .LBB0_2476
	s_and_b64 vcc, exec, s[12:13]
	s_cbranch_vccz .LBB0_2479
	s_barrier
